# P3a tile rewrite: GEMM1 A^T via LDS-DMA + ds_read_b64_tr_b16, gate scaling in registers, GEMM2 LDS-DMA, 16x16x32 MFMA; P3b LDS-DMA K-loop
# speedup vs baseline: 1.1892x; 1.0080x over previous
; template <class AL, class BL>
; DEV void gemm_mainloop(Acc& acc, const AL& al, const BL& bl, int m0, int n0, int kbeg, int kend, char* lds) {
;   const int tid = tidx_full();
;   const int wave = tid >> 6, lane = tid & 63;
;   const int wm = (wave >> 2) * 128, wn = (wave & 3) * 64;
;   const int lr = lane & 31, lh = lane >> 5;
;   const int nk = (kend - kbeg) / BK;
;   R4 a0 = al.load(tid, m0, kbeg);
;   R4 b0 = bl.load(tid, n0, kbeg);
;   __syncthreads();
;   al.store(tid, lds, a0);
;   bl.store(tid, lds + TILE_BYTES, b0);
;   a0 = al.load(tid, m0, kbeg + BK);
;   b0 = bl.load(tid, n0, kbeg + BK);
;   __syncthreads();
; DEV void phase_p3a(const Params& p, int g, char* smem) {
;     ...
;   for (int iter = 0;; ++iter) {
;     int mt, nt;
;     if (!tile_map(iter, 128, 4, mt, nt)) break;
;     const int m0 = mt * 256, n0 = nt * 256;
;     Acc acc;
;     acc_zero(acc);
;     {
;       TransLoader al{UHY, L};
;       RowLoader bl{WbrT, 1024};
;       gemm_mainloop(acc, al, bl, m0, n0, 0, 512, smem);
.LBB0_937:
	s_lshl_b32 s3, s5, 8
	s_lshl_b32 s2, s6, 8
	v_readlane_b32 s11, v252, 18
	v_readlane_b32 s6, v251, 16
	v_readlane_b32 s7, v251, 17
	v_readlane_b32 s12, v249, 48
	v_readlane_b32 s13, v249, 49
	s_lshr_b32 s0, s3, s11
	s_lshl_b32 s1, s0, s11
	s_sub_u32 s1, s3, s1
	s_mulk_i32 s0, 0x600
	s_addk_i32 s0, 0x400
	s_add_u32 s11, s11, 1
	s_lshl_b32 s0, s0, s11
	s_lshl_b32 s1, s1, 1
	s_add_u32 s0, s0, s1
	s_add_u32 s0, s74, s0
	s_addc_u32 s1, s75, 0
	s_lshl_b32 s10, 64, s11
	v_lshrrev_b32_e32 v149, 6, v202
	v_and_b32_e32 v148, 63, v202
	s_nop 0
	v_readfirstlane_b32 s5, v149
	v_lshrrev_b32_e32 v150, 3, v148
	v_lshl_add_u32 v150, v149, 5, v150
	v_and_b32_e32 v151, 7, v148
	v_lshrrev_b32_e32 v128, 4, v148
	v_xor_b32_e32 v151, v128, v151
	v_lshlrev_b32_e32 v151, 4, v151
	s_mul_i32 s9, s5, 0x2300
	s_lshl_b32 s5, s5, 12
	v_add_u32_e32 v132, s2, v150
	v_lshlrev_b32_e32 v132, 11, v132
	v_add_u32_e32 v132, v132, v151
	v_add_u32_e32 v133, 0x4000, v132
	v_add_u32_e32 v134, 0x8000, v132
	v_add_u32_e32 v135, 0xc000, v132
	v_xor_b32_e32 v133, 0x40, v133
	v_xor_b32_e32 v135, 0x40, v135
	v_add_u32_e32 v140, 0x40000, v132
	v_add_u32_e32 v141, 0x40000, v133
	v_add_u32_e32 v142, 0x40000, v134
	v_add_u32_e32 v143, 0x40000, v135
	v_lshrrev_b32_e32 v164, 5, v148
	v_bfe_u32 v242, v148, 1, 4
	v_xor_b32_e32 v242, v242, v164
	v_lshlrev_b32_e32 v242, 1, v242
	v_and_b32_e32 v128, 1, v148
	v_or_b32_e32 v242, v242, v128
	v_lshlrev_b32_e32 v242, 4, v242
	v_lshl_add_u32 v164, v149, 4, v164
	v_lshlrev_b32_e32 v164, s11, v164
	v_add_u32_e32 v128, v164, v242
	s_lshl_b32 s8, 2, s11
	v_add_u32_e32 v129, s8, v128
	v_add_u32_e32 v130, s8, v129
	v_add_u32_e32 v131, s8, v130
	v_add_u32_e32 v136, s8, v131
	v_add_u32_e32 v137, s8, v136
	v_add_u32_e32 v138, s8, v137
	v_add_u32_e32 v139, s8, v138
	v_lshrrev_b32_e32 v242, 6, v202
	v_and_b32_e32 v164, 63, v202
	v_bfe_u32 v243, v164, 1, 3
	v_lshrrev_b32_e32 v244, 4, v164
	v_xor_b32_e32 v243, v243, v244
	v_lshlrev_b32_e32 v243, 4, v243
	v_and_b32_e32 v244, 15, v164
	v_lshlrev_b32_e32 v244, 7, v244
	v_lshrrev_b32_e32 v144, 2, v242
	v_lshl_add_u32 v144, v144, 14, v244
	v_and_b32_e32 v146, 3, v242
	v_lshl_add_u32 v146, v146, 13, v244
	v_add_u32_e32 v146, 0x10000, v146
	v_xor_b32_e32 v145, 0x40, v243
	v_add_u32_e32 v145, v144, v145
	v_add_u32_e32 v144, v144, v243
	v_xor_b32_e32 v147, 0x40, v243
	v_add_u32_e32 v147, v146, v147
	v_add_u32_e32 v146, v146, v243
	v_lshrrev_b32_e32 v164, 4, v148
	v_bfe_u32 v242, v148, 2, 2
	v_lshrrev_b32_e32 v243, 1, v242
	v_mul_u32_u24_e32 v244, 0x1180, v164
	v_mul_u32_u24_e32 v243, 0x440, v243
	v_add_u32_e32 v244, v244, v243
	v_and_b32_e32 v243, 1, v242
	v_lshl_add_u32 v244, v243, 9, v244
	v_and_b32_e32 v164, 3, v148
	v_lshl_add_u32 v244, v164, 3, v244
	v_lshrrev_b32_e32 v164, 2, v149
	v_lshl_add_u32 v244, v164, 8, v244
	v_lshl_add_u32 v160, v243, 5, v244
	v_xor_b32_e32 v243, 1, v243
	v_lshl_add_u32 v161, v243, 5, v244
	s_waitcnt vmcnt(0)
	s_cmp_lt_u32 s5, 0x4000
	s_cbranch_scc0 .Lp3a_t1
	s_add_u32 m0, s9, 0x0
	s_nop 0
	global_load_lds_dwordx4 v128, s[0:1]
	s_add_u32 m0, s9, 0x440
	s_nop 0
	global_load_lds_dwordx4 v129, s[0:1]
	s_add_u32 m0, s9, 0x880
	s_nop 0
	global_load_lds_dwordx4 v130, s[0:1]
	s_add_u32 m0, s9, 0xcc0
	s_nop 0
	global_load_lds_dwordx4 v131, s[0:1]
	s_add_u32 m0, s9, 0x1180
	s_nop 0
	global_load_lds_dwordx4 v136, s[0:1]
	s_add_u32 m0, s9, 0x15c0
	s_nop 0
	global_load_lds_dwordx4 v137, s[0:1]
	s_add_u32 m0, s9, 0x1a00
	s_nop 0
	global_load_lds_dwordx4 v138, s[0:1]
	s_add_u32 m0, s9, 0x1e40
	s_nop 0
	global_load_lds_dwordx4 v139, s[0:1]
	s_add_u32 m0, s5, 0x11800
	s_nop 0
	global_load_lds_dwordx4 v132, s[6:7]
	s_add_u32 m0, m0, 0x400
	s_nop 0
	global_load_lds_dwordx4 v133, s[6:7]
	s_add_u32 m0, m0, 0x400
	s_nop 0
	global_load_lds_dwordx4 v134, s[6:7]
	s_add_u32 m0, m0, 0x400
	s_nop 0
	global_load_lds_dwordx4 v135, s[6:7]
	s_add_u32 m0, s5, 0x15800
	s_nop 0
	global_load_lds_dwordx4 v140, s[6:7]
	s_add_u32 m0, m0, 0x400
	s_nop 0
	global_load_lds_dwordx4 v141, s[6:7]
	s_add_u32 m0, m0, 0x400
	s_nop 0
	global_load_lds_dwordx4 v142, s[6:7]
	s_add_u32 m0, m0, 0x400
	s_nop 0
	global_load_lds_dwordx4 v143, s[6:7]
.Lp3a_t1:
	s_add_u32 s0, s0, s10
	s_addc_u32 s1, s1, 0
	s_add_u32 s6, s6, 0x80
	s_addc_u32 s7, s7, 0
	v_mov_b32_e32 v0, 0
	v_mov_b32_e32 v1, 0
	v_mov_b64_e32 v[2:3], v[0:1]
	v_mov_b64_e32 v[4:5], v[0:1]
	v_mov_b64_e32 v[6:7], v[0:1]
	v_mov_b64_e32 v[8:9], v[0:1]
	v_mov_b64_e32 v[10:11], v[0:1]
	v_mov_b64_e32 v[12:13], v[0:1]
	v_mov_b64_e32 v[14:15], v[0:1]
	v_mov_b64_e32 v[16:17], v[0:1]
	v_mov_b64_e32 v[18:19], v[0:1]
	v_mov_b64_e32 v[20:21], v[0:1]
	v_mov_b64_e32 v[22:23], v[0:1]
	v_mov_b64_e32 v[24:25], v[0:1]
	v_mov_b64_e32 v[26:27], v[0:1]
	v_mov_b64_e32 v[28:29], v[0:1]
	v_mov_b64_e32 v[30:31], v[0:1]
	v_mov_b64_e32 v[32:33], v[0:1]
	v_mov_b64_e32 v[34:35], v[0:1]
	v_mov_b64_e32 v[36:37], v[0:1]
	v_mov_b64_e32 v[38:39], v[0:1]
	v_mov_b64_e32 v[40:41], v[0:1]
	v_mov_b64_e32 v[42:43], v[0:1]
	v_mov_b64_e32 v[44:45], v[0:1]
	v_mov_b64_e32 v[46:47], v[0:1]
	v_mov_b64_e32 v[48:49], v[0:1]
	v_mov_b64_e32 v[50:51], v[0:1]
	v_mov_b64_e32 v[52:53], v[0:1]
	v_mov_b64_e32 v[54:55], v[0:1]
	v_mov_b64_e32 v[56:57], v[0:1]
	v_mov_b64_e32 v[58:59], v[0:1]
	v_mov_b64_e32 v[60:61], v[0:1]
	v_mov_b64_e32 v[62:63], v[0:1]
	v_mov_b64_e32 v[64:65], v[0:1]
	v_mov_b64_e32 v[66:67], v[0:1]
	v_mov_b64_e32 v[68:69], v[0:1]
	v_mov_b64_e32 v[70:71], v[0:1]
	v_mov_b64_e32 v[72:73], v[0:1]
	v_mov_b64_e32 v[74:75], v[0:1]
	v_mov_b64_e32 v[76:77], v[0:1]
	v_mov_b64_e32 v[78:79], v[0:1]
	v_mov_b64_e32 v[80:81], v[0:1]
	v_mov_b64_e32 v[82:83], v[0:1]
	v_mov_b64_e32 v[84:85], v[0:1]
	v_mov_b64_e32 v[86:87], v[0:1]
	v_mov_b64_e32 v[88:89], v[0:1]
	v_mov_b64_e32 v[90:91], v[0:1]
	v_mov_b64_e32 v[92:93], v[0:1]
	v_mov_b64_e32 v[94:95], v[0:1]
	v_mov_b64_e32 v[96:97], v[0:1]
	v_mov_b64_e32 v[98:99], v[0:1]
	v_mov_b64_e32 v[100:101], v[0:1]
	v_mov_b64_e32 v[102:103], v[0:1]
	v_mov_b64_e32 v[104:105], v[0:1]
	v_mov_b64_e32 v[106:107], v[0:1]
	v_mov_b64_e32 v[108:109], v[0:1]
	v_mov_b64_e32 v[110:111], v[0:1]
	v_mov_b64_e32 v[112:113], v[0:1]
	v_mov_b64_e32 v[114:115], v[0:1]
	v_mov_b64_e32 v[116:117], v[0:1]
	v_mov_b64_e32 v[118:119], v[0:1]
	v_mov_b64_e32 v[120:121], v[0:1]
	v_mov_b64_e32 v[122:123], v[0:1]
	v_mov_b64_e32 v[124:125], v[0:1]
	v_mov_b64_e32 v[126:127], v[0:1]
	s_mov_b32 s8, 0
	s_waitcnt vmcnt(0)
	s_barrier
; template <class AL, class BL>
; DEV void gemm_ktile(Acc& acc, const char* A, const char* B, int wm, int wn, int lr, int lh, const AL& al, const BL& bl,
;                     int tid, int m0, int n0, int knext, char* nxt, R4& ra, R4& rb) {
;     ...
;   for (int ks = 0; ks < 4; ++ks) {
;     const int cur = ks & 1, nx = cur ^ 1;
;     if (ks < 3) {
; #pragma unroll
;       for (int i = 0; i < 4; ++i) a[nx][i] = *(const bf16x8*)(pa + 32 * i * LDSROW + (ks + 1) * 32);
; #pragma unroll
;       for (int j = 0; j < 2; ++j) b[nx][j] = *(const bf16x8*)(pb + 32 * j * LDSROW + (ks + 1) * 32);
;     }
;     __builtin_amdgcn_sched_barrier(0);
; #pragma unroll
;     for (int i = 0; i < 4; ++i)
; #pragma unroll
;       for (int j = 0; j < 2; ++j)
;         acc[i][j] = __builtin_amdgcn_mfma_f32_32x32x16_bf16(a[cur][i], b[cur][j], acc[i][j], 0, 0, 0);
;     __builtin_amdgcn_sched_barrier(0);
;     if (ks == 1) {
;       al.store(tid, nxt, ra);
;       bl.store(tid, nxt + TILE_BYTES, rb);
;       __builtin_amdgcn_sched_barrier(0);
;       ra = al.load(tid, m0, knext);
;       rb = bl.load(tid, n0, knext);
;       __builtin_amdgcn_sched_barrier(0);
;     }
; template <class AL, class BL>
; DEV void gemm_mainloop(Acc& acc, const AL& al, const BL& bl, int m0, int n0, int kbeg, int kend, char* lds) {
;     ...
;   for (int kt = 0; kt < nk; ++kt) {
;     const char* cur = lds + (kt & 1) * 2 * TILE_BYTES;
;     char* nxt = lds + ((kt + 1) & 1) * 2 * TILE_BYTES;
;     const int t2 = (kt + 2 < nk) ? kt + 2 : nk - 1;
;     __builtin_amdgcn_sched_barrier(0);
;     gemm_ktile(acc, cur, cur + TILE_BYTES, wm, wn, lr, lh, al, bl, tid, m0, n0, kbeg + t2 * BK, nxt, a0, b0);
;     __builtin_amdgcn_sched_barrier(0);
;     __syncthreads();
;   }
.Lp3a_k1loop:
	s_cmp_lt_u32 s5, 0x4000
	s_cbranch_scc0 .Lp3a_t2
	s_add_u32 m0, s9, 0x8c00
	s_nop 0
	global_load_lds_dwordx4 v128, s[0:1]
	s_add_u32 m0, s9, 0x9040
	s_nop 0
	global_load_lds_dwordx4 v129, s[0:1]
	s_add_u32 m0, s9, 0x9480
	s_nop 0
	global_load_lds_dwordx4 v130, s[0:1]
	s_add_u32 m0, s9, 0x98c0
	s_nop 0
	global_load_lds_dwordx4 v131, s[0:1]
	s_add_u32 m0, s9, 0x9d80
	s_nop 0
	global_load_lds_dwordx4 v136, s[0:1]
	s_add_u32 m0, s9, 0xa1c0
	s_nop 0
	global_load_lds_dwordx4 v137, s[0:1]
	s_add_u32 m0, s9, 0xa600
	s_nop 0
	global_load_lds_dwordx4 v138, s[0:1]
	s_add_u32 m0, s9, 0xaa40
	s_nop 0
	global_load_lds_dwordx4 v139, s[0:1]
	s_add_u32 m0, s5, 0x19800
	s_nop 0
	global_load_lds_dwordx4 v132, s[6:7]
	s_add_u32 m0, m0, 0x400
	s_nop 0
	global_load_lds_dwordx4 v133, s[6:7]
	s_add_u32 m0, m0, 0x400
	s_nop 0
	global_load_lds_dwordx4 v134, s[6:7]
	s_add_u32 m0, m0, 0x400
	s_nop 0
	global_load_lds_dwordx4 v135, s[6:7]
	s_add_u32 m0, s5, 0x1d800
	s_nop 0
	global_load_lds_dwordx4 v140, s[6:7]
	s_add_u32 m0, m0, 0x400
	s_nop 0
	global_load_lds_dwordx4 v141, s[6:7]
	s_add_u32 m0, m0, 0x400
	s_nop 0
	global_load_lds_dwordx4 v142, s[6:7]
	s_add_u32 m0, m0, 0x400
	s_nop 0
	global_load_lds_dwordx4 v143, s[6:7]
.Lp3a_t2:
	s_add_u32 s0, s0, s10
	s_addc_u32 s1, s1, 0
	s_add_u32 s6, s6, 0x80
	s_addc_u32 s7, s7, 0
	ds_read_b128 v[166:169], v146 offset:6144
	ds_read_b128 v[170:173], v146 offset:8192
	ds_read_b128 v[174:177], v146 offset:10240
	ds_read_b128 v[178:181], v146 offset:12288
	ds_read_b64_tr_b16 v[222:223], v160 offset:0
	ds_read_b64_tr_b16 v[224:225], v160 offset:2176
	ds_read_b64_tr_b16 v[226:227], v161 offset:0
	ds_read_b64_tr_b16 v[228:229], v161 offset:2176
	ds_read_b64_tr_b16 v[230:231], v160 offset:64
	ds_read_b64_tr_b16 v[232:233], v160 offset:2240
	ds_read_b64_tr_b16 v[234:235], v161 offset:64
	ds_read_b64_tr_b16 v[236:237], v161 offset:2240
	ds_read_b64_tr_b16 v[238:239], v160 offset:128
	ds_read_b64_tr_b16 v[240:241], v160 offset:2304
	ds_read_b64_tr_b16 v[198:199], v161 offset:128
	ds_read_b64_tr_b16 v[200:201], v161 offset:2304
	ds_read_b64_tr_b16 v[152:153], v160 offset:192
	ds_read_b64_tr_b16 v[154:155], v160 offset:2368
	ds_read_b64_tr_b16 v[156:157], v161 offset:192
	ds_read_b64_tr_b16 v[158:159], v161 offset:2368
	ds_read_b128 v[182:185], v147 offset:6144
	ds_read_b128 v[186:189], v147 offset:8192
	ds_read_b128 v[190:193], v147 offset:10240
	ds_read_b128 v[194:197], v147 offset:12288
	s_waitcnt lgkmcnt(12)
	v_mfma_f32_16x16x32_bf16 v[0:3], v[166:169], v[222:225], v[0:3]
	v_mfma_f32_16x16x32_bf16 v[4:7], v[170:173], v[222:225], v[4:7]
	v_mfma_f32_16x16x32_bf16 v[8:11], v[174:177], v[222:225], v[8:11]
	v_mfma_f32_16x16x32_bf16 v[12:15], v[178:181], v[222:225], v[12:15]
	v_mfma_f32_16x16x32_bf16 v[16:19], v[166:169], v[226:229], v[16:19]
	v_mfma_f32_16x16x32_bf16 v[20:23], v[170:173], v[226:229], v[20:23]
	v_mfma_f32_16x16x32_bf16 v[24:27], v[174:177], v[226:229], v[24:27]
	v_mfma_f32_16x16x32_bf16 v[28:31], v[178:181], v[226:229], v[28:31]
	v_mfma_f32_16x16x32_bf16 v[32:35], v[166:169], v[230:233], v[32:35]
	v_mfma_f32_16x16x32_bf16 v[36:39], v[170:173], v[230:233], v[36:39]
	v_mfma_f32_16x16x32_bf16 v[40:43], v[174:177], v[230:233], v[40:43]
	v_mfma_f32_16x16x32_bf16 v[44:47], v[178:181], v[230:233], v[44:47]
	v_mfma_f32_16x16x32_bf16 v[48:51], v[166:169], v[234:237], v[48:51]
	v_mfma_f32_16x16x32_bf16 v[52:55], v[170:173], v[234:237], v[52:55]
	v_mfma_f32_16x16x32_bf16 v[56:59], v[174:177], v[234:237], v[56:59]
	v_mfma_f32_16x16x32_bf16 v[60:63], v[178:181], v[234:237], v[60:63]
	ds_read_b64_tr_b16 v[222:223], v160 offset:17920
	ds_read_b64_tr_b16 v[224:225], v160 offset:20096
	ds_read_b64_tr_b16 v[226:227], v161 offset:17920
	ds_read_b64_tr_b16 v[228:229], v161 offset:20096
	ds_read_b64_tr_b16 v[230:231], v160 offset:17984
	ds_read_b64_tr_b16 v[232:233], v160 offset:20160
	ds_read_b64_tr_b16 v[234:235], v161 offset:17984
	ds_read_b64_tr_b16 v[236:237], v161 offset:20160
	s_waitcnt lgkmcnt(12)
	v_mfma_f32_16x16x32_bf16 v[64:67], v[166:169], v[238:241], v[64:67]
	v_mfma_f32_16x16x32_bf16 v[68:71], v[170:173], v[238:241], v[68:71]
	v_mfma_f32_16x16x32_bf16 v[72:75], v[174:177], v[238:241], v[72:75]
	v_mfma_f32_16x16x32_bf16 v[76:79], v[178:181], v[238:241], v[76:79]
	v_mfma_f32_16x16x32_bf16 v[80:83], v[166:169], v[198:201], v[80:83]
	v_mfma_f32_16x16x32_bf16 v[84:87], v[170:173], v[198:201], v[84:87]
	v_mfma_f32_16x16x32_bf16 v[88:91], v[174:177], v[198:201], v[88:91]
	v_mfma_f32_16x16x32_bf16 v[92:95], v[178:181], v[198:201], v[92:95]
	v_mfma_f32_16x16x32_bf16 v[96:99], v[166:169], v[152:155], v[96:99]
	v_mfma_f32_16x16x32_bf16 v[100:103], v[170:173], v[152:155], v[100:103]
	v_mfma_f32_16x16x32_bf16 v[104:107], v[174:177], v[152:155], v[104:107]
	v_mfma_f32_16x16x32_bf16 v[108:111], v[178:181], v[152:155], v[108:111]
	v_mfma_f32_16x16x32_bf16 v[112:115], v[166:169], v[156:159], v[112:115]
	v_mfma_f32_16x16x32_bf16 v[116:119], v[170:173], v[156:159], v[116:119]
	v_mfma_f32_16x16x32_bf16 v[120:123], v[174:177], v[156:159], v[120:123]
	v_mfma_f32_16x16x32_bf16 v[124:127], v[178:181], v[156:159], v[124:127]
	ds_read_b64_tr_b16 v[238:239], v160 offset:18048
	ds_read_b64_tr_b16 v[240:241], v160 offset:20224
	ds_read_b64_tr_b16 v[198:199], v161 offset:18048
	ds_read_b64_tr_b16 v[200:201], v161 offset:20224
	ds_read_b64_tr_b16 v[152:153], v160 offset:18112
	ds_read_b64_tr_b16 v[154:155], v160 offset:20288
	ds_read_b64_tr_b16 v[156:157], v161 offset:18112
	ds_read_b64_tr_b16 v[158:159], v161 offset:20288
	s_waitcnt lgkmcnt(8)
; template <class AL, class BL>
; DEV void gemm_ktile(Acc& acc, const char* A, const char* B, int wm, int wn, int lr, int lh, const AL& al, const BL& bl,
;                     int tid, int m0, int n0, int knext, char* nxt, R4& ra, R4& rb) {
;     ...
;   for (int ks = 0; ks < 4; ++ks) {
;     const int cur = ks & 1, nx = cur ^ 1;
;     if (ks < 3) {
; #pragma unroll
;       for (int i = 0; i < 4; ++i) a[nx][i] = *(const bf16x8*)(pa + 32 * i * LDSROW + (ks + 1) * 32);
; #pragma unroll
;       for (int j = 0; j < 2; ++j) b[nx][j] = *(const bf16x8*)(pb + 32 * j * LDSROW + (ks + 1) * 32);
;     }
;     __builtin_amdgcn_sched_barrier(0);
; #pragma unroll
;     for (int i = 0; i < 4; ++i)
; #pragma unroll
;       for (int j = 0; j < 2; ++j)
;         acc[i][j] = __builtin_amdgcn_mfma_f32_32x32x16_bf16(a[cur][i], b[cur][j], acc[i][j], 0, 0, 0);
;     __builtin_amdgcn_sched_barrier(0);
;     if (ks == 1) {
;       al.store(tid, nxt, ra);
;       bl.store(tid, nxt + TILE_BYTES, rb);
;       __builtin_amdgcn_sched_barrier(0);
;       ra = al.load(tid, m0, knext);
;       rb = bl.load(tid, n0, knext);
;       __builtin_amdgcn_sched_barrier(0);
;     }
; template <class AL, class BL>
; DEV void gemm_mainloop(Acc& acc, const AL& al, const BL& bl, int m0, int n0, int kbeg, int kend, char* lds) {
;     ...
;   for (int kt = 0; kt < nk; ++kt) {
;     const char* cur = lds + (kt & 1) * 2 * TILE_BYTES;
;     char* nxt = lds + ((kt + 1) & 1) * 2 * TILE_BYTES;
;     const int t2 = (kt + 2 < nk) ? kt + 2 : nk - 1;
;     __builtin_amdgcn_sched_barrier(0);
;     gemm_ktile(acc, cur, cur + TILE_BYTES, wm, wn, lr, lh, al, bl, tid, m0, n0, kbeg + t2 * BK, nxt, a0, b0);
;     __builtin_amdgcn_sched_barrier(0);
;     __syncthreads();
;   }
	v_mfma_f32_16x16x32_bf16 v[0:3], v[182:185], v[222:225], v[0:3]
	v_mfma_f32_16x16x32_bf16 v[4:7], v[186:189], v[222:225], v[4:7]
	v_mfma_f32_16x16x32_bf16 v[8:11], v[190:193], v[222:225], v[8:11]
	v_mfma_f32_16x16x32_bf16 v[12:15], v[194:197], v[222:225], v[12:15]
	v_mfma_f32_16x16x32_bf16 v[16:19], v[182:185], v[226:229], v[16:19]
	v_mfma_f32_16x16x32_bf16 v[20:23], v[186:189], v[226:229], v[20:23]
	v_mfma_f32_16x16x32_bf16 v[24:27], v[190:193], v[226:229], v[24:27]
	v_mfma_f32_16x16x32_bf16 v[28:31], v[194:197], v[226:229], v[28:31]
	v_mfma_f32_16x16x32_bf16 v[32:35], v[182:185], v[230:233], v[32:35]
	v_mfma_f32_16x16x32_bf16 v[36:39], v[186:189], v[230:233], v[36:39]
	v_mfma_f32_16x16x32_bf16 v[40:43], v[190:193], v[230:233], v[40:43]
	v_mfma_f32_16x16x32_bf16 v[44:47], v[194:197], v[230:233], v[44:47]
	v_mfma_f32_16x16x32_bf16 v[48:51], v[182:185], v[234:237], v[48:51]
	v_mfma_f32_16x16x32_bf16 v[52:55], v[186:189], v[234:237], v[52:55]
	v_mfma_f32_16x16x32_bf16 v[56:59], v[190:193], v[234:237], v[56:59]
	v_mfma_f32_16x16x32_bf16 v[60:63], v[194:197], v[234:237], v[60:63]
	s_waitcnt lgkmcnt(0)
	v_mfma_f32_16x16x32_bf16 v[64:67], v[182:185], v[238:241], v[64:67]
	v_mfma_f32_16x16x32_bf16 v[68:71], v[186:189], v[238:241], v[68:71]
	v_mfma_f32_16x16x32_bf16 v[72:75], v[190:193], v[238:241], v[72:75]
	v_mfma_f32_16x16x32_bf16 v[76:79], v[194:197], v[238:241], v[76:79]
	v_mfma_f32_16x16x32_bf16 v[80:83], v[182:185], v[198:201], v[80:83]
	v_mfma_f32_16x16x32_bf16 v[84:87], v[186:189], v[198:201], v[84:87]
	v_mfma_f32_16x16x32_bf16 v[88:91], v[190:193], v[198:201], v[88:91]
	v_mfma_f32_16x16x32_bf16 v[92:95], v[194:197], v[198:201], v[92:95]
	v_mfma_f32_16x16x32_bf16 v[96:99], v[182:185], v[152:155], v[96:99]
	v_mfma_f32_16x16x32_bf16 v[100:103], v[186:189], v[152:155], v[100:103]
	v_mfma_f32_16x16x32_bf16 v[104:107], v[190:193], v[152:155], v[104:107]
	v_mfma_f32_16x16x32_bf16 v[108:111], v[194:197], v[152:155], v[108:111]
	v_mfma_f32_16x16x32_bf16 v[112:115], v[182:185], v[156:159], v[112:115]
	v_mfma_f32_16x16x32_bf16 v[116:119], v[186:189], v[156:159], v[116:119]
	v_mfma_f32_16x16x32_bf16 v[120:123], v[190:193], v[156:159], v[120:123]
	v_mfma_f32_16x16x32_bf16 v[124:127], v[194:197], v[156:159], v[124:127]
	s_waitcnt vmcnt(0)
	s_barrier
	s_cmp_eq_u32 s8, 3
	s_cbranch_scc1 .Lp3a_k1last
	s_cmp_lt_u32 s5, 0x4000
	s_cbranch_scc0 .Lp3a_t3
	s_add_u32 m0, s9, 0x0
	s_nop 0
	global_load_lds_dwordx4 v128, s[0:1]
	s_add_u32 m0, s9, 0x440
	s_nop 0
	global_load_lds_dwordx4 v129, s[0:1]
	s_add_u32 m0, s9, 0x880
	s_nop 0
	global_load_lds_dwordx4 v130, s[0:1]
	s_add_u32 m0, s9, 0xcc0
	s_nop 0
	global_load_lds_dwordx4 v131, s[0:1]
	s_add_u32 m0, s9, 0x1180
	s_nop 0
	global_load_lds_dwordx4 v136, s[0:1]
	s_add_u32 m0, s9, 0x15c0
	s_nop 0
	global_load_lds_dwordx4 v137, s[0:1]
	s_add_u32 m0, s9, 0x1a00
	s_nop 0
	global_load_lds_dwordx4 v138, s[0:1]
	s_add_u32 m0, s9, 0x1e40
	s_nop 0
	global_load_lds_dwordx4 v139, s[0:1]
	s_add_u32 m0, s5, 0x11800
	s_nop 0
	global_load_lds_dwordx4 v132, s[6:7]
	s_add_u32 m0, m0, 0x400
	s_nop 0
	global_load_lds_dwordx4 v133, s[6:7]
	s_add_u32 m0, m0, 0x400
	s_nop 0
	global_load_lds_dwordx4 v134, s[6:7]
	s_add_u32 m0, m0, 0x400
	s_nop 0
	global_load_lds_dwordx4 v135, s[6:7]
	s_add_u32 m0, s5, 0x15800
	s_nop 0
	global_load_lds_dwordx4 v140, s[6:7]
	s_add_u32 m0, m0, 0x400
	s_nop 0
	global_load_lds_dwordx4 v141, s[6:7]
	s_add_u32 m0, m0, 0x400
	s_nop 0
	global_load_lds_dwordx4 v142, s[6:7]
	s_add_u32 m0, m0, 0x400
	s_nop 0
	global_load_lds_dwordx4 v143, s[6:7]
.Lp3a_t3:
	s_add_u32 s0, s0, s10
	s_addc_u32 s1, s1, 0
	s_add_u32 s6, s6, 0x80
	s_addc_u32 s7, s7, 0
	ds_read_b128 v[166:169], v146 offset:38912
	ds_read_b128 v[170:173], v146 offset:40960
	ds_read_b128 v[174:177], v146 offset:43008
	ds_read_b128 v[178:181], v146 offset:45056
	ds_read_b64_tr_b16 v[222:223], v160 offset:35840
	ds_read_b64_tr_b16 v[224:225], v160 offset:38016
	ds_read_b64_tr_b16 v[226:227], v161 offset:35840
	ds_read_b64_tr_b16 v[228:229], v161 offset:38016
	ds_read_b64_tr_b16 v[230:231], v160 offset:35904
	ds_read_b64_tr_b16 v[232:233], v160 offset:38080
	ds_read_b64_tr_b16 v[234:235], v161 offset:35904
	ds_read_b64_tr_b16 v[236:237], v161 offset:38080
	ds_read_b64_tr_b16 v[238:239], v160 offset:35968
	ds_read_b64_tr_b16 v[240:241], v160 offset:38144
	ds_read_b64_tr_b16 v[198:199], v161 offset:35968
	ds_read_b64_tr_b16 v[200:201], v161 offset:38144
	ds_read_b64_tr_b16 v[152:153], v160 offset:36032
	ds_read_b64_tr_b16 v[154:155], v160 offset:38208
	ds_read_b64_tr_b16 v[156:157], v161 offset:36032
	ds_read_b64_tr_b16 v[158:159], v161 offset:38208
	ds_read_b128 v[182:185], v147 offset:38912
	ds_read_b128 v[186:189], v147 offset:40960
	ds_read_b128 v[190:193], v147 offset:43008
	ds_read_b128 v[194:197], v147 offset:45056
	s_waitcnt lgkmcnt(12)
	v_mfma_f32_16x16x32_bf16 v[0:3], v[166:169], v[222:225], v[0:3]
	v_mfma_f32_16x16x32_bf16 v[4:7], v[170:173], v[222:225], v[4:7]
	v_mfma_f32_16x16x32_bf16 v[8:11], v[174:177], v[222:225], v[8:11]
	v_mfma_f32_16x16x32_bf16 v[12:15], v[178:181], v[222:225], v[12:15]
	v_mfma_f32_16x16x32_bf16 v[16:19], v[166:169], v[226:229], v[16:19]
	v_mfma_f32_16x16x32_bf16 v[20:23], v[170:173], v[226:229], v[20:23]
	v_mfma_f32_16x16x32_bf16 v[24:27], v[174:177], v[226:229], v[24:27]
	v_mfma_f32_16x16x32_bf16 v[28:31], v[178:181], v[226:229], v[28:31]
	v_mfma_f32_16x16x32_bf16 v[32:35], v[166:169], v[230:233], v[32:35]
	v_mfma_f32_16x16x32_bf16 v[36:39], v[170:173], v[230:233], v[36:39]
	v_mfma_f32_16x16x32_bf16 v[40:43], v[174:177], v[230:233], v[40:43]
	v_mfma_f32_16x16x32_bf16 v[44:47], v[178:181], v[230:233], v[44:47]
	v_mfma_f32_16x16x32_bf16 v[48:51], v[166:169], v[234:237], v[48:51]
	v_mfma_f32_16x16x32_bf16 v[52:55], v[170:173], v[234:237], v[52:55]
	v_mfma_f32_16x16x32_bf16 v[56:59], v[174:177], v[234:237], v[56:59]
	v_mfma_f32_16x16x32_bf16 v[60:63], v[178:181], v[234:237], v[60:63]
	ds_read_b64_tr_b16 v[222:223], v160 offset:53760
	ds_read_b64_tr_b16 v[224:225], v160 offset:55936
	ds_read_b64_tr_b16 v[226:227], v161 offset:53760
	ds_read_b64_tr_b16 v[228:229], v161 offset:55936
	ds_read_b64_tr_b16 v[230:231], v160 offset:53824
	ds_read_b64_tr_b16 v[232:233], v160 offset:56000
	ds_read_b64_tr_b16 v[234:235], v161 offset:53824
	ds_read_b64_tr_b16 v[236:237], v161 offset:56000
	s_waitcnt lgkmcnt(12)
; template <class AL, class BL>
; DEV void gemm_ktile(Acc& acc, const char* A, const char* B, int wm, int wn, int lr, int lh, const AL& al, const BL& bl,
;                     int tid, int m0, int n0, int knext, char* nxt, R4& ra, R4& rb) {
;     ...
;   for (int ks = 0; ks < 4; ++ks) {
;     const int cur = ks & 1, nx = cur ^ 1;
;     if (ks < 3) {
; #pragma unroll
;       for (int i = 0; i < 4; ++i) a[nx][i] = *(const bf16x8*)(pa + 32 * i * LDSROW + (ks + 1) * 32);
; #pragma unroll
;       for (int j = 0; j < 2; ++j) b[nx][j] = *(const bf16x8*)(pb + 32 * j * LDSROW + (ks + 1) * 32);
;     }
;     __builtin_amdgcn_sched_barrier(0);
; #pragma unroll
;     for (int i = 0; i < 4; ++i)
; #pragma unroll
;       for (int j = 0; j < 2; ++j)
;         acc[i][j] = __builtin_amdgcn_mfma_f32_32x32x16_bf16(a[cur][i], b[cur][j], acc[i][j], 0, 0, 0);
;     __builtin_amdgcn_sched_barrier(0);
;     if (ks == 1) {
;       al.store(tid, nxt, ra);
;       bl.store(tid, nxt + TILE_BYTES, rb);
;       __builtin_amdgcn_sched_barrier(0);
;       ra = al.load(tid, m0, knext);
;       rb = bl.load(tid, n0, knext);
;       __builtin_amdgcn_sched_barrier(0);
;     }
; template <class AL, class BL>
; DEV void gemm_mainloop(Acc& acc, const AL& al, const BL& bl, int m0, int n0, int kbeg, int kend, char* lds) {
;     ...
;   for (int kt = 0; kt < nk; ++kt) {
;     const char* cur = lds + (kt & 1) * 2 * TILE_BYTES;
;     char* nxt = lds + ((kt + 1) & 1) * 2 * TILE_BYTES;
;     const int t2 = (kt + 2 < nk) ? kt + 2 : nk - 1;
;     __builtin_amdgcn_sched_barrier(0);
;     gemm_ktile(acc, cur, cur + TILE_BYTES, wm, wn, lr, lh, al, bl, tid, m0, n0, kbeg + t2 * BK, nxt, a0, b0);
;     __builtin_amdgcn_sched_barrier(0);
;     __syncthreads();
;   }
	v_mfma_f32_16x16x32_bf16 v[64:67], v[166:169], v[238:241], v[64:67]
	v_mfma_f32_16x16x32_bf16 v[68:71], v[170:173], v[238:241], v[68:71]
	v_mfma_f32_16x16x32_bf16 v[72:75], v[174:177], v[238:241], v[72:75]
	v_mfma_f32_16x16x32_bf16 v[76:79], v[178:181], v[238:241], v[76:79]
	v_mfma_f32_16x16x32_bf16 v[80:83], v[166:169], v[198:201], v[80:83]
	v_mfma_f32_16x16x32_bf16 v[84:87], v[170:173], v[198:201], v[84:87]
	v_mfma_f32_16x16x32_bf16 v[88:91], v[174:177], v[198:201], v[88:91]
	v_mfma_f32_16x16x32_bf16 v[92:95], v[178:181], v[198:201], v[92:95]
	v_mfma_f32_16x16x32_bf16 v[96:99], v[166:169], v[152:155], v[96:99]
	v_mfma_f32_16x16x32_bf16 v[100:103], v[170:173], v[152:155], v[100:103]
	v_mfma_f32_16x16x32_bf16 v[104:107], v[174:177], v[152:155], v[104:107]
	v_mfma_f32_16x16x32_bf16 v[108:111], v[178:181], v[152:155], v[108:111]
	v_mfma_f32_16x16x32_bf16 v[112:115], v[166:169], v[156:159], v[112:115]
	v_mfma_f32_16x16x32_bf16 v[116:119], v[170:173], v[156:159], v[116:119]
	v_mfma_f32_16x16x32_bf16 v[120:123], v[174:177], v[156:159], v[120:123]
	v_mfma_f32_16x16x32_bf16 v[124:127], v[178:181], v[156:159], v[124:127]
	ds_read_b64_tr_b16 v[238:239], v160 offset:53888
	ds_read_b64_tr_b16 v[240:241], v160 offset:56064
	ds_read_b64_tr_b16 v[198:199], v161 offset:53888
	ds_read_b64_tr_b16 v[200:201], v161 offset:56064
	ds_read_b64_tr_b16 v[152:153], v160 offset:53952
	ds_read_b64_tr_b16 v[154:155], v160 offset:56128
	ds_read_b64_tr_b16 v[156:157], v161 offset:53952
	ds_read_b64_tr_b16 v[158:159], v161 offset:56128
	s_waitcnt lgkmcnt(8)
	v_mfma_f32_16x16x32_bf16 v[0:3], v[182:185], v[222:225], v[0:3]
	v_mfma_f32_16x16x32_bf16 v[4:7], v[186:189], v[222:225], v[4:7]
	v_mfma_f32_16x16x32_bf16 v[8:11], v[190:193], v[222:225], v[8:11]
	v_mfma_f32_16x16x32_bf16 v[12:15], v[194:197], v[222:225], v[12:15]
	v_mfma_f32_16x16x32_bf16 v[16:19], v[182:185], v[226:229], v[16:19]
	v_mfma_f32_16x16x32_bf16 v[20:23], v[186:189], v[226:229], v[20:23]
	v_mfma_f32_16x16x32_bf16 v[24:27], v[190:193], v[226:229], v[24:27]
	v_mfma_f32_16x16x32_bf16 v[28:31], v[194:197], v[226:229], v[28:31]
	v_mfma_f32_16x16x32_bf16 v[32:35], v[182:185], v[230:233], v[32:35]
	v_mfma_f32_16x16x32_bf16 v[36:39], v[186:189], v[230:233], v[36:39]
	v_mfma_f32_16x16x32_bf16 v[40:43], v[190:193], v[230:233], v[40:43]
	v_mfma_f32_16x16x32_bf16 v[44:47], v[194:197], v[230:233], v[44:47]
	v_mfma_f32_16x16x32_bf16 v[48:51], v[182:185], v[234:237], v[48:51]
	v_mfma_f32_16x16x32_bf16 v[52:55], v[186:189], v[234:237], v[52:55]
	v_mfma_f32_16x16x32_bf16 v[56:59], v[190:193], v[234:237], v[56:59]
	v_mfma_f32_16x16x32_bf16 v[60:63], v[194:197], v[234:237], v[60:63]
	s_waitcnt lgkmcnt(0)
	v_mfma_f32_16x16x32_bf16 v[64:67], v[182:185], v[238:241], v[64:67]
	v_mfma_f32_16x16x32_bf16 v[68:71], v[186:189], v[238:241], v[68:71]
	v_mfma_f32_16x16x32_bf16 v[72:75], v[190:193], v[238:241], v[72:75]
	v_mfma_f32_16x16x32_bf16 v[76:79], v[194:197], v[238:241], v[76:79]
	v_mfma_f32_16x16x32_bf16 v[80:83], v[182:185], v[198:201], v[80:83]
	v_mfma_f32_16x16x32_bf16 v[84:87], v[186:189], v[198:201], v[84:87]
	v_mfma_f32_16x16x32_bf16 v[88:91], v[190:193], v[198:201], v[88:91]
	v_mfma_f32_16x16x32_bf16 v[92:95], v[194:197], v[198:201], v[92:95]
	v_mfma_f32_16x16x32_bf16 v[96:99], v[182:185], v[152:155], v[96:99]
	v_mfma_f32_16x16x32_bf16 v[100:103], v[186:189], v[152:155], v[100:103]
	v_mfma_f32_16x16x32_bf16 v[104:107], v[190:193], v[152:155], v[104:107]
	v_mfma_f32_16x16x32_bf16 v[108:111], v[194:197], v[152:155], v[108:111]
	v_mfma_f32_16x16x32_bf16 v[112:115], v[182:185], v[156:159], v[112:115]
	v_mfma_f32_16x16x32_bf16 v[116:119], v[186:189], v[156:159], v[116:119]
	v_mfma_f32_16x16x32_bf16 v[120:123], v[190:193], v[156:159], v[120:123]
	v_mfma_f32_16x16x32_bf16 v[124:127], v[194:197], v[156:159], v[124:127]
	s_add_i32 s8, s8, 1
	s_waitcnt vmcnt(0)
	s_barrier
	s_branch .Lp3a_k1loop
.Lp3a_k1last:
	ds_read_b128 v[166:169], v146 offset:38912
	ds_read_b128 v[170:173], v146 offset:40960
	ds_read_b128 v[174:177], v146 offset:43008
	ds_read_b128 v[178:181], v146 offset:45056
	ds_read_b64_tr_b16 v[222:223], v160 offset:35840
	ds_read_b64_tr_b16 v[224:225], v160 offset:38016
	ds_read_b64_tr_b16 v[226:227], v161 offset:35840
	ds_read_b64_tr_b16 v[228:229], v161 offset:38016
	ds_read_b64_tr_b16 v[230:231], v160 offset:35904
	ds_read_b64_tr_b16 v[232:233], v160 offset:38080
	ds_read_b64_tr_b16 v[234:235], v161 offset:35904
	ds_read_b64_tr_b16 v[236:237], v161 offset:38080
	ds_read_b64_tr_b16 v[238:239], v160 offset:35968
	ds_read_b64_tr_b16 v[240:241], v160 offset:38144
	ds_read_b64_tr_b16 v[198:199], v161 offset:35968
	ds_read_b64_tr_b16 v[200:201], v161 offset:38144
	ds_read_b64_tr_b16 v[152:153], v160 offset:36032
	ds_read_b64_tr_b16 v[154:155], v160 offset:38208
	ds_read_b64_tr_b16 v[156:157], v161 offset:36032
	ds_read_b64_tr_b16 v[158:159], v161 offset:38208
	ds_read_b128 v[182:185], v147 offset:38912
	ds_read_b128 v[186:189], v147 offset:40960
	ds_read_b128 v[190:193], v147 offset:43008
	ds_read_b128 v[194:197], v147 offset:45056
	s_waitcnt lgkmcnt(12)
; template <class AL, class BL>
; DEV void gemm_ktile(Acc& acc, const char* A, const char* B, int wm, int wn, int lr, int lh, const AL& al, const BL& bl,
;                     int tid, int m0, int n0, int knext, char* nxt, R4& ra, R4& rb) {
;     ...
;   for (int ks = 0; ks < 4; ++ks) {
;     const int cur = ks & 1, nx = cur ^ 1;
;     if (ks < 3) {
; #pragma unroll
;       for (int i = 0; i < 4; ++i) a[nx][i] = *(const bf16x8*)(pa + 32 * i * LDSROW + (ks + 1) * 32);
; #pragma unroll
;       for (int j = 0; j < 2; ++j) b[nx][j] = *(const bf16x8*)(pb + 32 * j * LDSROW + (ks + 1) * 32);
;     }
;     __builtin_amdgcn_sched_barrier(0);
; #pragma unroll
;     for (int i = 0; i < 4; ++i)
; #pragma unroll
;       for (int j = 0; j < 2; ++j)
;         acc[i][j] = __builtin_amdgcn_mfma_f32_32x32x16_bf16(a[cur][i], b[cur][j], acc[i][j], 0, 0, 0);
;     __builtin_amdgcn_sched_barrier(0);
	v_mfma_f32_16x16x32_bf16 v[0:3], v[166:169], v[222:225], v[0:3]
	v_mfma_f32_16x16x32_bf16 v[4:7], v[170:173], v[222:225], v[4:7]
	v_mfma_f32_16x16x32_bf16 v[8:11], v[174:177], v[222:225], v[8:11]
	v_mfma_f32_16x16x32_bf16 v[12:15], v[178:181], v[222:225], v[12:15]
	v_mfma_f32_16x16x32_bf16 v[16:19], v[166:169], v[226:229], v[16:19]
	v_mfma_f32_16x16x32_bf16 v[20:23], v[170:173], v[226:229], v[20:23]
	v_mfma_f32_16x16x32_bf16 v[24:27], v[174:177], v[226:229], v[24:27]
	v_mfma_f32_16x16x32_bf16 v[28:31], v[178:181], v[226:229], v[28:31]
	v_mfma_f32_16x16x32_bf16 v[32:35], v[166:169], v[230:233], v[32:35]
	v_mfma_f32_16x16x32_bf16 v[36:39], v[170:173], v[230:233], v[36:39]
	v_mfma_f32_16x16x32_bf16 v[40:43], v[174:177], v[230:233], v[40:43]
	v_mfma_f32_16x16x32_bf16 v[44:47], v[178:181], v[230:233], v[44:47]
	v_mfma_f32_16x16x32_bf16 v[48:51], v[166:169], v[234:237], v[48:51]
	v_mfma_f32_16x16x32_bf16 v[52:55], v[170:173], v[234:237], v[52:55]
	v_mfma_f32_16x16x32_bf16 v[56:59], v[174:177], v[234:237], v[56:59]
	v_mfma_f32_16x16x32_bf16 v[60:63], v[178:181], v[234:237], v[60:63]
	ds_read_b64_tr_b16 v[222:223], v160 offset:53760
	ds_read_b64_tr_b16 v[224:225], v160 offset:55936
	ds_read_b64_tr_b16 v[226:227], v161 offset:53760
	ds_read_b64_tr_b16 v[228:229], v161 offset:55936
	ds_read_b64_tr_b16 v[230:231], v160 offset:53824
	ds_read_b64_tr_b16 v[232:233], v160 offset:56000
	ds_read_b64_tr_b16 v[234:235], v161 offset:53824
	ds_read_b64_tr_b16 v[236:237], v161 offset:56000
	s_waitcnt lgkmcnt(12)
	v_mfma_f32_16x16x32_bf16 v[64:67], v[166:169], v[238:241], v[64:67]
	v_mfma_f32_16x16x32_bf16 v[68:71], v[170:173], v[238:241], v[68:71]
	v_mfma_f32_16x16x32_bf16 v[72:75], v[174:177], v[238:241], v[72:75]
	v_mfma_f32_16x16x32_bf16 v[76:79], v[178:181], v[238:241], v[76:79]
	v_mfma_f32_16x16x32_bf16 v[80:83], v[166:169], v[198:201], v[80:83]
	v_mfma_f32_16x16x32_bf16 v[84:87], v[170:173], v[198:201], v[84:87]
	v_mfma_f32_16x16x32_bf16 v[88:91], v[174:177], v[198:201], v[88:91]
	v_mfma_f32_16x16x32_bf16 v[92:95], v[178:181], v[198:201], v[92:95]
	v_mfma_f32_16x16x32_bf16 v[96:99], v[166:169], v[152:155], v[96:99]
	v_mfma_f32_16x16x32_bf16 v[100:103], v[170:173], v[152:155], v[100:103]
	v_mfma_f32_16x16x32_bf16 v[104:107], v[174:177], v[152:155], v[104:107]
	v_mfma_f32_16x16x32_bf16 v[108:111], v[178:181], v[152:155], v[108:111]
	v_mfma_f32_16x16x32_bf16 v[112:115], v[166:169], v[156:159], v[112:115]
	v_mfma_f32_16x16x32_bf16 v[116:119], v[170:173], v[156:159], v[116:119]
	v_mfma_f32_16x16x32_bf16 v[120:123], v[174:177], v[156:159], v[120:123]
	v_mfma_f32_16x16x32_bf16 v[124:127], v[178:181], v[156:159], v[124:127]
	ds_read_b64_tr_b16 v[238:239], v160 offset:53888
	ds_read_b64_tr_b16 v[240:241], v160 offset:56064
	ds_read_b64_tr_b16 v[198:199], v161 offset:53888
	ds_read_b64_tr_b16 v[200:201], v161 offset:56064
	ds_read_b64_tr_b16 v[152:153], v160 offset:53952
	ds_read_b64_tr_b16 v[154:155], v160 offset:56128
	ds_read_b64_tr_b16 v[156:157], v161 offset:53952
	ds_read_b64_tr_b16 v[158:159], v161 offset:56128
	s_waitcnt lgkmcnt(8)
	v_mfma_f32_16x16x32_bf16 v[0:3], v[182:185], v[222:225], v[0:3]
	v_mfma_f32_16x16x32_bf16 v[4:7], v[186:189], v[222:225], v[4:7]
	v_mfma_f32_16x16x32_bf16 v[8:11], v[190:193], v[222:225], v[8:11]
	v_mfma_f32_16x16x32_bf16 v[12:15], v[194:197], v[222:225], v[12:15]
	v_mfma_f32_16x16x32_bf16 v[16:19], v[182:185], v[226:229], v[16:19]
	v_mfma_f32_16x16x32_bf16 v[20:23], v[186:189], v[226:229], v[20:23]
	v_mfma_f32_16x16x32_bf16 v[24:27], v[190:193], v[226:229], v[24:27]
	v_mfma_f32_16x16x32_bf16 v[28:31], v[194:197], v[226:229], v[28:31]
	v_mfma_f32_16x16x32_bf16 v[32:35], v[182:185], v[230:233], v[32:35]
	v_mfma_f32_16x16x32_bf16 v[36:39], v[186:189], v[230:233], v[36:39]
	v_mfma_f32_16x16x32_bf16 v[40:43], v[190:193], v[230:233], v[40:43]
	v_mfma_f32_16x16x32_bf16 v[44:47], v[194:197], v[230:233], v[44:47]
	v_mfma_f32_16x16x32_bf16 v[48:51], v[182:185], v[234:237], v[48:51]
	v_mfma_f32_16x16x32_bf16 v[52:55], v[186:189], v[234:237], v[52:55]
	v_mfma_f32_16x16x32_bf16 v[56:59], v[190:193], v[234:237], v[56:59]
	v_mfma_f32_16x16x32_bf16 v[60:63], v[194:197], v[234:237], v[60:63]
	s_waitcnt lgkmcnt(0)
	v_mfma_f32_16x16x32_bf16 v[64:67], v[182:185], v[238:241], v[64:67]
	v_mfma_f32_16x16x32_bf16 v[68:71], v[186:189], v[238:241], v[68:71]
	v_mfma_f32_16x16x32_bf16 v[72:75], v[190:193], v[238:241], v[72:75]
	v_mfma_f32_16x16x32_bf16 v[76:79], v[194:197], v[238:241], v[76:79]
	v_mfma_f32_16x16x32_bf16 v[80:83], v[182:185], v[198:201], v[80:83]
	v_mfma_f32_16x16x32_bf16 v[84:87], v[186:189], v[198:201], v[84:87]
	v_mfma_f32_16x16x32_bf16 v[88:91], v[190:193], v[198:201], v[88:91]
	v_mfma_f32_16x16x32_bf16 v[92:95], v[194:197], v[198:201], v[92:95]
	v_mfma_f32_16x16x32_bf16 v[96:99], v[182:185], v[152:155], v[96:99]
	v_mfma_f32_16x16x32_bf16 v[100:103], v[186:189], v[152:155], v[100:103]
	v_mfma_f32_16x16x32_bf16 v[104:107], v[190:193], v[152:155], v[104:107]
	v_mfma_f32_16x16x32_bf16 v[108:111], v[194:197], v[152:155], v[108:111]
	v_mfma_f32_16x16x32_bf16 v[112:115], v[182:185], v[156:159], v[112:115]
	v_mfma_f32_16x16x32_bf16 v[116:119], v[186:189], v[156:159], v[116:119]
	v_mfma_f32_16x16x32_bf16 v[120:123], v[190:193], v[156:159], v[120:123]
	v_mfma_f32_16x16x32_bf16 v[124:127], v[194:197], v[156:159], v[124:127]
	s_barrier
; DEV float bf2f(u16 h) { return __uint_as_float(((unsigned)h) << 16); }
; DEV void phase_p3a(const Params& p, int g, char* smem) {
;     ...
;     acc_foreach(acc, m0, n0, [&](int m, int n, float& v) {
;       const float ga = bf2f(GT[(size_t)m * 2048 + n]);
;       const float gb = bf2f(GT[(size_t)m * 2048 + 1024 + n]);
;       v *= ga * __builtin_amdgcn_rcpf(fmaxf(gb, 1e-30f));
;     });
;     {
;       RowLoader al{PHG - 512, 2560};
;       RowLoader bl{WbrT, 1024};
;       gemm_mainloop(acc, al, bl, m0, n0, 512, 1024, smem);
.Lp3a_mid0:
	v_add_u32_e32 v128, s3, v150
	v_mul_u32_u24_e32 v128, 0x1400, v128
	v_add_u32_e32 v128, v128, v151
	v_add_u32_e32 v129, 0xa000, v128
	v_add_u32_e32 v130, 0x14000, v128
	v_add_u32_e32 v131, 0x1e000, v128
	v_xor_b32_e32 v129, 0x40, v129
	v_xor_b32_e32 v131, 0x40, v131
	v_add_u32_e32 v136, 0xa0000, v128
	v_add_u32_e32 v137, 0xa0000, v129
	v_add_u32_e32 v138, 0xa0000, v130
	v_add_u32_e32 v139, 0xa0000, v131
	s_mov_b64 s[0:1], s[56:57]
	v_readlane_b32 s6, v251, 16
	v_readlane_b32 s7, v251, 17
	s_add_u32 s6, s6, 0x400
	s_addc_u32 s7, s7, 0
	s_cmp_lt_u32 s5, 0x4000
	s_cbranch_scc0 .Lp3a_u1
	s_add_u32 m0, s5, 0x0
	s_nop 0
	global_load_lds_dwordx4 v128, s[0:1]
	s_add_u32 m0, m0, 0x400
	s_nop 0
	global_load_lds_dwordx4 v129, s[0:1]
	s_add_u32 m0, m0, 0x400
	s_nop 0
	global_load_lds_dwordx4 v130, s[0:1]
	s_add_u32 m0, m0, 0x400
	s_nop 0
	global_load_lds_dwordx4 v131, s[0:1]
	s_add_u32 m0, s5, 0x10000
	s_nop 0
	global_load_lds_dwordx4 v132, s[6:7]
	s_add_u32 m0, m0, 0x400
	s_nop 0
	global_load_lds_dwordx4 v133, s[6:7]
	s_add_u32 m0, m0, 0x400
	s_nop 0
	global_load_lds_dwordx4 v134, s[6:7]
	s_add_u32 m0, m0, 0x400
	s_nop 0
	global_load_lds_dwordx4 v135, s[6:7]
	s_add_u32 m0, s5, 0x4000
	s_nop 0
	global_load_lds_dwordx4 v136, s[0:1]
	s_add_u32 m0, m0, 0x400
	s_nop 0
	global_load_lds_dwordx4 v137, s[0:1]
	s_add_u32 m0, m0, 0x400
	s_nop 0
	global_load_lds_dwordx4 v138, s[0:1]
	s_add_u32 m0, m0, 0x400
	s_nop 0
	global_load_lds_dwordx4 v139, s[0:1]
	s_add_u32 m0, s5, 0x14000
	s_nop 0
	global_load_lds_dwordx4 v140, s[6:7]
	s_add_u32 m0, m0, 0x400
	s_nop 0
	global_load_lds_dwordx4 v141, s[6:7]
	s_add_u32 m0, m0, 0x400
	s_nop 0
	global_load_lds_dwordx4 v142, s[6:7]
	s_add_u32 m0, m0, 0x400
	s_nop 0
	global_load_lds_dwordx4 v143, s[6:7]
.Lp3a_u1:
	s_add_u32 s0, s0, 0x80
	s_addc_u32 s1, s1, 0
	s_add_u32 s6, s6, 0x80
	s_addc_u32 s7, s7, 0
	v_and_b32_e32 v222, 15, v148
	v_lshrrev_b32_e32 v223, 2, v149
	v_lshl_add_u32 v222, v223, 7, v222
	v_add_u32_e32 v222, s3, v222
	v_lshlrev_b32_e32 v222, 12, v222
	v_lshrrev_b32_e32 v223, 4, v148
	v_lshlrev_b32_e32 v223, 3, v223
	v_add_u32_e32 v222, v222, v223
	v_and_b32_e32 v223, 3, v149
	v_lshl_add_u32 v222, v223, 7, v222
	s_lshl_b32 s100, s2, 1
	v_add_u32_e32 v198, s100, v222
	global_load_dwordx2 v[166:167], v198, s[12:13]
	global_load_dwordx2 v[182:183], v198, s[12:13] offset:2048
	global_load_dwordx2 v[168:169], v198, s[12:13] offset:32
	global_load_dwordx2 v[184:185], v198, s[12:13] offset:2080
	global_load_dwordx2 v[170:171], v198, s[12:13] offset:64
	global_load_dwordx2 v[186:187], v198, s[12:13] offset:2112
	global_load_dwordx2 v[172:173], v198, s[12:13] offset:96
	global_load_dwordx2 v[188:189], v198, s[12:13] offset:2144
	v_add_u32_e32 v198, 0x10000, v198
	global_load_dwordx2 v[174:175], v198, s[12:13]
	global_load_dwordx2 v[190:191], v198, s[12:13] offset:2048
	global_load_dwordx2 v[176:177], v198, s[12:13] offset:32
	global_load_dwordx2 v[192:193], v198, s[12:13] offset:2080
	global_load_dwordx2 v[178:179], v198, s[12:13] offset:64
	global_load_dwordx2 v[194:195], v198, s[12:13] offset:2112
	global_load_dwordx2 v[180:181], v198, s[12:13] offset:96
	global_load_dwordx2 v[196:197], v198, s[12:13] offset:2144
	v_add_u32_e32 v198, 0x10000, v198
	s_nop 7
	s_nop 7
	s_nop 3
	s_waitcnt vmcnt(8)
	v_lshlrev_b32_e32 v222, 16, v182
	v_and_b32_e32 v223, 0xffff0000, v182
	v_lshlrev_b32_e32 v224, 16, v183
	v_and_b32_e32 v225, 0xffff0000, v183
	v_max_f32_e32 v222, 0xda24260, v222
	v_max_f32_e32 v223, 0xda24260, v223
	v_max_f32_e32 v224, 0xda24260, v224
	v_max_f32_e32 v225, 0xda24260, v225
	v_rcp_f32_e32 v222, v222
	v_rcp_f32_e32 v223, v223
	v_rcp_f32_e32 v224, v224
	v_rcp_f32_e32 v225, v225
	v_lshlrev_b32_e32 v226, 16, v166
	v_and_b32_e32 v227, 0xffff0000, v166
	v_lshlrev_b32_e32 v228, 16, v167
	v_and_b32_e32 v229, 0xffff0000, v167
	v_mul_f32_e32 v222, v222, v226
	v_mul_f32_e32 v223, v223, v227
	v_mul_f32_e32 v224, v224, v228
	v_mul_f32_e32 v225, v225, v229
	v_mul_f32_e32 v0, v0, v222
	v_mul_f32_e32 v1, v1, v223
	v_mul_f32_e32 v2, v2, v224
	v_mul_f32_e32 v3, v3, v225
	v_lshlrev_b32_e32 v222, 16, v184
	v_and_b32_e32 v223, 0xffff0000, v184
	v_lshlrev_b32_e32 v224, 16, v185
	v_and_b32_e32 v225, 0xffff0000, v185
	v_max_f32_e32 v222, 0xda24260, v222
	v_max_f32_e32 v223, 0xda24260, v223
	v_max_f32_e32 v224, 0xda24260, v224
	v_max_f32_e32 v225, 0xda24260, v225
	v_rcp_f32_e32 v222, v222
	v_rcp_f32_e32 v223, v223
	v_rcp_f32_e32 v224, v224
	v_rcp_f32_e32 v225, v225
	v_lshlrev_b32_e32 v226, 16, v168
	v_and_b32_e32 v227, 0xffff0000, v168
	v_lshlrev_b32_e32 v228, 16, v169
	v_and_b32_e32 v229, 0xffff0000, v169
	v_mul_f32_e32 v222, v222, v226
	v_mul_f32_e32 v223, v223, v227
	v_mul_f32_e32 v224, v224, v228
	v_mul_f32_e32 v225, v225, v229
	v_mul_f32_e32 v4, v4, v222
	v_mul_f32_e32 v5, v5, v223
	v_mul_f32_e32 v6, v6, v224
	v_mul_f32_e32 v7, v7, v225
	v_lshlrev_b32_e32 v222, 16, v186
	v_and_b32_e32 v223, 0xffff0000, v186
	v_lshlrev_b32_e32 v224, 16, v187
	v_and_b32_e32 v225, 0xffff0000, v187
	v_max_f32_e32 v222, 0xda24260, v222
	v_max_f32_e32 v223, 0xda24260, v223
	v_max_f32_e32 v224, 0xda24260, v224
	v_max_f32_e32 v225, 0xda24260, v225
	v_rcp_f32_e32 v222, v222
	v_rcp_f32_e32 v223, v223
	v_rcp_f32_e32 v224, v224
	v_rcp_f32_e32 v225, v225
	v_lshlrev_b32_e32 v226, 16, v170
	v_and_b32_e32 v227, 0xffff0000, v170
	v_lshlrev_b32_e32 v228, 16, v171
	v_and_b32_e32 v229, 0xffff0000, v171
	v_mul_f32_e32 v222, v222, v226
	v_mul_f32_e32 v223, v223, v227
	v_mul_f32_e32 v224, v224, v228
	v_mul_f32_e32 v225, v225, v229
	v_mul_f32_e32 v8, v8, v222
	v_mul_f32_e32 v9, v9, v223
	v_mul_f32_e32 v10, v10, v224
	v_mul_f32_e32 v11, v11, v225
	v_lshlrev_b32_e32 v222, 16, v188
	v_and_b32_e32 v223, 0xffff0000, v188
	v_lshlrev_b32_e32 v224, 16, v189
	v_and_b32_e32 v225, 0xffff0000, v189
	v_max_f32_e32 v222, 0xda24260, v222
	v_max_f32_e32 v223, 0xda24260, v223
	v_max_f32_e32 v224, 0xda24260, v224
	v_max_f32_e32 v225, 0xda24260, v225
	v_rcp_f32_e32 v222, v222
	v_rcp_f32_e32 v223, v223
	v_rcp_f32_e32 v224, v224
	v_rcp_f32_e32 v225, v225
	v_lshlrev_b32_e32 v226, 16, v172
	v_and_b32_e32 v227, 0xffff0000, v172
	v_lshlrev_b32_e32 v228, 16, v173
	v_and_b32_e32 v229, 0xffff0000, v173
	v_mul_f32_e32 v222, v222, v226
	v_mul_f32_e32 v223, v223, v227
	v_mul_f32_e32 v224, v224, v228
	v_mul_f32_e32 v225, v225, v229
	v_mul_f32_e32 v12, v12, v222
	v_mul_f32_e32 v13, v13, v223
	v_mul_f32_e32 v14, v14, v224
	v_mul_f32_e32 v15, v15, v225
	global_load_dwordx2 v[166:167], v198, s[12:13]
	global_load_dwordx2 v[182:183], v198, s[12:13] offset:2048
	global_load_dwordx2 v[168:169], v198, s[12:13] offset:32
	global_load_dwordx2 v[184:185], v198, s[12:13] offset:2080
	global_load_dwordx2 v[170:171], v198, s[12:13] offset:64
	global_load_dwordx2 v[186:187], v198, s[12:13] offset:2112
	global_load_dwordx2 v[172:173], v198, s[12:13] offset:96
	global_load_dwordx2 v[188:189], v198, s[12:13] offset:2144
	v_add_u32_e32 v198, 0x10000, v198
	s_waitcnt vmcnt(8)
; DEV float bf2f(u16 h) { return __uint_as_float(((unsigned)h) << 16); }
; DEV void phase_p3a(const Params& p, int g, char* smem) {
;     ...
;     acc_foreach(acc, m0, n0, [&](int m, int n, float& v) {
;       const float ga = bf2f(GT[(size_t)m * 2048 + n]);
;       const float gb = bf2f(GT[(size_t)m * 2048 + 1024 + n]);
;       v *= ga * __builtin_amdgcn_rcpf(fmaxf(gb, 1e-30f));
;     });
	v_lshlrev_b32_e32 v222, 16, v190
	v_and_b32_e32 v223, 0xffff0000, v190
	v_lshlrev_b32_e32 v224, 16, v191
	v_and_b32_e32 v225, 0xffff0000, v191
	v_max_f32_e32 v222, 0xda24260, v222
	v_max_f32_e32 v223, 0xda24260, v223
	v_max_f32_e32 v224, 0xda24260, v224
	v_max_f32_e32 v225, 0xda24260, v225
	v_rcp_f32_e32 v222, v222
	v_rcp_f32_e32 v223, v223
	v_rcp_f32_e32 v224, v224
	v_rcp_f32_e32 v225, v225
	v_lshlrev_b32_e32 v226, 16, v174
	v_and_b32_e32 v227, 0xffff0000, v174
	v_lshlrev_b32_e32 v228, 16, v175
	v_and_b32_e32 v229, 0xffff0000, v175
	v_mul_f32_e32 v222, v222, v226
	v_mul_f32_e32 v223, v223, v227
	v_mul_f32_e32 v224, v224, v228
	v_mul_f32_e32 v225, v225, v229
	v_mul_f32_e32 v16, v16, v222
	v_mul_f32_e32 v17, v17, v223
	v_mul_f32_e32 v18, v18, v224
	v_mul_f32_e32 v19, v19, v225
	v_lshlrev_b32_e32 v222, 16, v192
	v_and_b32_e32 v223, 0xffff0000, v192
	v_lshlrev_b32_e32 v224, 16, v193
	v_and_b32_e32 v225, 0xffff0000, v193
	v_max_f32_e32 v222, 0xda24260, v222
	v_max_f32_e32 v223, 0xda24260, v223
	v_max_f32_e32 v224, 0xda24260, v224
	v_max_f32_e32 v225, 0xda24260, v225
	v_rcp_f32_e32 v222, v222
	v_rcp_f32_e32 v223, v223
	v_rcp_f32_e32 v224, v224
	v_rcp_f32_e32 v225, v225
	v_lshlrev_b32_e32 v226, 16, v176
	v_and_b32_e32 v227, 0xffff0000, v176
	v_lshlrev_b32_e32 v228, 16, v177
	v_and_b32_e32 v229, 0xffff0000, v177
	v_mul_f32_e32 v222, v222, v226
	v_mul_f32_e32 v223, v223, v227
	v_mul_f32_e32 v224, v224, v228
	v_mul_f32_e32 v225, v225, v229
	v_mul_f32_e32 v20, v20, v222
	v_mul_f32_e32 v21, v21, v223
	v_mul_f32_e32 v22, v22, v224
	v_mul_f32_e32 v23, v23, v225
	v_lshlrev_b32_e32 v222, 16, v194
	v_and_b32_e32 v223, 0xffff0000, v194
	v_lshlrev_b32_e32 v224, 16, v195
	v_and_b32_e32 v225, 0xffff0000, v195
	v_max_f32_e32 v222, 0xda24260, v222
	v_max_f32_e32 v223, 0xda24260, v223
	v_max_f32_e32 v224, 0xda24260, v224
	v_max_f32_e32 v225, 0xda24260, v225
	v_rcp_f32_e32 v222, v222
	v_rcp_f32_e32 v223, v223
	v_rcp_f32_e32 v224, v224
	v_rcp_f32_e32 v225, v225
	v_lshlrev_b32_e32 v226, 16, v178
	v_and_b32_e32 v227, 0xffff0000, v178
	v_lshlrev_b32_e32 v228, 16, v179
	v_and_b32_e32 v229, 0xffff0000, v179
	v_mul_f32_e32 v222, v222, v226
	v_mul_f32_e32 v223, v223, v227
	v_mul_f32_e32 v224, v224, v228
	v_mul_f32_e32 v225, v225, v229
	v_mul_f32_e32 v24, v24, v222
	v_mul_f32_e32 v25, v25, v223
	v_mul_f32_e32 v26, v26, v224
	v_mul_f32_e32 v27, v27, v225
	v_lshlrev_b32_e32 v222, 16, v196
	v_and_b32_e32 v223, 0xffff0000, v196
	v_lshlrev_b32_e32 v224, 16, v197
	v_and_b32_e32 v225, 0xffff0000, v197
	v_max_f32_e32 v222, 0xda24260, v222
	v_max_f32_e32 v223, 0xda24260, v223
	v_max_f32_e32 v224, 0xda24260, v224
	v_max_f32_e32 v225, 0xda24260, v225
	v_rcp_f32_e32 v222, v222
	v_rcp_f32_e32 v223, v223
	v_rcp_f32_e32 v224, v224
	v_rcp_f32_e32 v225, v225
	v_lshlrev_b32_e32 v226, 16, v180
	v_and_b32_e32 v227, 0xffff0000, v180
	v_lshlrev_b32_e32 v228, 16, v181
	v_and_b32_e32 v229, 0xffff0000, v181
	v_mul_f32_e32 v222, v222, v226
	v_mul_f32_e32 v223, v223, v227
	v_mul_f32_e32 v224, v224, v228
	v_mul_f32_e32 v225, v225, v229
	v_mul_f32_e32 v28, v28, v222
	v_mul_f32_e32 v29, v29, v223
	v_mul_f32_e32 v30, v30, v224
	v_mul_f32_e32 v31, v31, v225
	global_load_dwordx2 v[174:175], v198, s[12:13]
	global_load_dwordx2 v[190:191], v198, s[12:13] offset:2048
	global_load_dwordx2 v[176:177], v198, s[12:13] offset:32
	global_load_dwordx2 v[192:193], v198, s[12:13] offset:2080
	global_load_dwordx2 v[178:179], v198, s[12:13] offset:64
	global_load_dwordx2 v[194:195], v198, s[12:13] offset:2112
	global_load_dwordx2 v[180:181], v198, s[12:13] offset:96
	global_load_dwordx2 v[196:197], v198, s[12:13] offset:2144
	v_add_u32_e32 v198, 0x10000, v198
	s_waitcnt vmcnt(8)
	v_lshlrev_b32_e32 v222, 16, v182
	v_and_b32_e32 v223, 0xffff0000, v182
	v_lshlrev_b32_e32 v224, 16, v183
	v_and_b32_e32 v225, 0xffff0000, v183
	v_max_f32_e32 v222, 0xda24260, v222
	v_max_f32_e32 v223, 0xda24260, v223
	v_max_f32_e32 v224, 0xda24260, v224
	v_max_f32_e32 v225, 0xda24260, v225
	v_rcp_f32_e32 v222, v222
	v_rcp_f32_e32 v223, v223
	v_rcp_f32_e32 v224, v224
	v_rcp_f32_e32 v225, v225
	v_lshlrev_b32_e32 v226, 16, v166
	v_and_b32_e32 v227, 0xffff0000, v166
	v_lshlrev_b32_e32 v228, 16, v167
	v_and_b32_e32 v229, 0xffff0000, v167
	v_mul_f32_e32 v222, v222, v226
	v_mul_f32_e32 v223, v223, v227
	v_mul_f32_e32 v224, v224, v228
	v_mul_f32_e32 v225, v225, v229
	v_mul_f32_e32 v32, v32, v222
	v_mul_f32_e32 v33, v33, v223
	v_mul_f32_e32 v34, v34, v224
	v_mul_f32_e32 v35, v35, v225
	v_lshlrev_b32_e32 v222, 16, v184
	v_and_b32_e32 v223, 0xffff0000, v184
	v_lshlrev_b32_e32 v224, 16, v185
	v_and_b32_e32 v225, 0xffff0000, v185
	v_max_f32_e32 v222, 0xda24260, v222
	v_max_f32_e32 v223, 0xda24260, v223
	v_max_f32_e32 v224, 0xda24260, v224
	v_max_f32_e32 v225, 0xda24260, v225
	v_rcp_f32_e32 v222, v222
	v_rcp_f32_e32 v223, v223
	v_rcp_f32_e32 v224, v224
	v_rcp_f32_e32 v225, v225
	v_lshlrev_b32_e32 v226, 16, v168
	v_and_b32_e32 v227, 0xffff0000, v168
	v_lshlrev_b32_e32 v228, 16, v169
	v_and_b32_e32 v229, 0xffff0000, v169
	v_mul_f32_e32 v222, v222, v226
	v_mul_f32_e32 v223, v223, v227
	v_mul_f32_e32 v224, v224, v228
	v_mul_f32_e32 v225, v225, v229
	v_mul_f32_e32 v36, v36, v222
	v_mul_f32_e32 v37, v37, v223
	v_mul_f32_e32 v38, v38, v224
	v_mul_f32_e32 v39, v39, v225
	v_lshlrev_b32_e32 v222, 16, v186
	v_and_b32_e32 v223, 0xffff0000, v186
	v_lshlrev_b32_e32 v224, 16, v187
	v_and_b32_e32 v225, 0xffff0000, v187
	v_max_f32_e32 v222, 0xda24260, v222
	v_max_f32_e32 v223, 0xda24260, v223
	v_max_f32_e32 v224, 0xda24260, v224
	v_max_f32_e32 v225, 0xda24260, v225
	v_rcp_f32_e32 v222, v222
	v_rcp_f32_e32 v223, v223
	v_rcp_f32_e32 v224, v224
	v_rcp_f32_e32 v225, v225
; DEV float bf2f(u16 h) { return __uint_as_float(((unsigned)h) << 16); }
; DEV void phase_p3a(const Params& p, int g, char* smem) {
;     ...
;     acc_foreach(acc, m0, n0, [&](int m, int n, float& v) {
;       const float ga = bf2f(GT[(size_t)m * 2048 + n]);
;       const float gb = bf2f(GT[(size_t)m * 2048 + 1024 + n]);
;       v *= ga * __builtin_amdgcn_rcpf(fmaxf(gb, 1e-30f));
;     });
	v_lshlrev_b32_e32 v226, 16, v170
	v_and_b32_e32 v227, 0xffff0000, v170
	v_lshlrev_b32_e32 v228, 16, v171
	v_and_b32_e32 v229, 0xffff0000, v171
	v_mul_f32_e32 v222, v222, v226
	v_mul_f32_e32 v223, v223, v227
	v_mul_f32_e32 v224, v224, v228
	v_mul_f32_e32 v225, v225, v229
	v_mul_f32_e32 v40, v40, v222
	v_mul_f32_e32 v41, v41, v223
	v_mul_f32_e32 v42, v42, v224
	v_mul_f32_e32 v43, v43, v225
	v_lshlrev_b32_e32 v222, 16, v188
	v_and_b32_e32 v223, 0xffff0000, v188
	v_lshlrev_b32_e32 v224, 16, v189
	v_and_b32_e32 v225, 0xffff0000, v189
	v_max_f32_e32 v222, 0xda24260, v222
	v_max_f32_e32 v223, 0xda24260, v223
	v_max_f32_e32 v224, 0xda24260, v224
	v_max_f32_e32 v225, 0xda24260, v225
	v_rcp_f32_e32 v222, v222
	v_rcp_f32_e32 v223, v223
	v_rcp_f32_e32 v224, v224
	v_rcp_f32_e32 v225, v225
	v_lshlrev_b32_e32 v226, 16, v172
	v_and_b32_e32 v227, 0xffff0000, v172
	v_lshlrev_b32_e32 v228, 16, v173
	v_and_b32_e32 v229, 0xffff0000, v173
	v_mul_f32_e32 v222, v222, v226
	v_mul_f32_e32 v223, v223, v227
	v_mul_f32_e32 v224, v224, v228
	v_mul_f32_e32 v225, v225, v229
	v_mul_f32_e32 v44, v44, v222
	v_mul_f32_e32 v45, v45, v223
	v_mul_f32_e32 v46, v46, v224
	v_mul_f32_e32 v47, v47, v225
	global_load_dwordx2 v[166:167], v198, s[12:13]
	global_load_dwordx2 v[182:183], v198, s[12:13] offset:2048
	global_load_dwordx2 v[168:169], v198, s[12:13] offset:32
	global_load_dwordx2 v[184:185], v198, s[12:13] offset:2080
	global_load_dwordx2 v[170:171], v198, s[12:13] offset:64
	global_load_dwordx2 v[186:187], v198, s[12:13] offset:2112
	global_load_dwordx2 v[172:173], v198, s[12:13] offset:96
	global_load_dwordx2 v[188:189], v198, s[12:13] offset:2144
	v_add_u32_e32 v198, 0x10000, v198
	s_waitcnt vmcnt(8)
	v_lshlrev_b32_e32 v222, 16, v190
	v_and_b32_e32 v223, 0xffff0000, v190
	v_lshlrev_b32_e32 v224, 16, v191
	v_and_b32_e32 v225, 0xffff0000, v191
	v_max_f32_e32 v222, 0xda24260, v222
	v_max_f32_e32 v223, 0xda24260, v223
	v_max_f32_e32 v224, 0xda24260, v224
	v_max_f32_e32 v225, 0xda24260, v225
	v_rcp_f32_e32 v222, v222
	v_rcp_f32_e32 v223, v223
	v_rcp_f32_e32 v224, v224
	v_rcp_f32_e32 v225, v225
	v_lshlrev_b32_e32 v226, 16, v174
	v_and_b32_e32 v227, 0xffff0000, v174
	v_lshlrev_b32_e32 v228, 16, v175
	v_and_b32_e32 v229, 0xffff0000, v175
	v_mul_f32_e32 v222, v222, v226
	v_mul_f32_e32 v223, v223, v227
	v_mul_f32_e32 v224, v224, v228
	v_mul_f32_e32 v225, v225, v229
	v_mul_f32_e32 v48, v48, v222
	v_mul_f32_e32 v49, v49, v223
	v_mul_f32_e32 v50, v50, v224
	v_mul_f32_e32 v51, v51, v225
	v_lshlrev_b32_e32 v222, 16, v192
	v_and_b32_e32 v223, 0xffff0000, v192
	v_lshlrev_b32_e32 v224, 16, v193
	v_and_b32_e32 v225, 0xffff0000, v193
	v_max_f32_e32 v222, 0xda24260, v222
	v_max_f32_e32 v223, 0xda24260, v223
	v_max_f32_e32 v224, 0xda24260, v224
	v_max_f32_e32 v225, 0xda24260, v225
	v_rcp_f32_e32 v222, v222
	v_rcp_f32_e32 v223, v223
	v_rcp_f32_e32 v224, v224
	v_rcp_f32_e32 v225, v225
	v_lshlrev_b32_e32 v226, 16, v176
	v_and_b32_e32 v227, 0xffff0000, v176
	v_lshlrev_b32_e32 v228, 16, v177
	v_and_b32_e32 v229, 0xffff0000, v177
	v_mul_f32_e32 v222, v222, v226
	v_mul_f32_e32 v223, v223, v227
	v_mul_f32_e32 v224, v224, v228
	v_mul_f32_e32 v225, v225, v229
	v_mul_f32_e32 v52, v52, v222
	v_mul_f32_e32 v53, v53, v223
	v_mul_f32_e32 v54, v54, v224
	v_mul_f32_e32 v55, v55, v225
	v_lshlrev_b32_e32 v222, 16, v194
	v_and_b32_e32 v223, 0xffff0000, v194
	v_lshlrev_b32_e32 v224, 16, v195
	v_and_b32_e32 v225, 0xffff0000, v195
	v_max_f32_e32 v222, 0xda24260, v222
	v_max_f32_e32 v223, 0xda24260, v223
	v_max_f32_e32 v224, 0xda24260, v224
	v_max_f32_e32 v225, 0xda24260, v225
	v_rcp_f32_e32 v222, v222
	v_rcp_f32_e32 v223, v223
	v_rcp_f32_e32 v224, v224
	v_rcp_f32_e32 v225, v225
	v_lshlrev_b32_e32 v226, 16, v178
	v_and_b32_e32 v227, 0xffff0000, v178
	v_lshlrev_b32_e32 v228, 16, v179
	v_and_b32_e32 v229, 0xffff0000, v179
	v_mul_f32_e32 v222, v222, v226
	v_mul_f32_e32 v223, v223, v227
	v_mul_f32_e32 v224, v224, v228
	v_mul_f32_e32 v225, v225, v229
	v_mul_f32_e32 v56, v56, v222
	v_mul_f32_e32 v57, v57, v223
	v_mul_f32_e32 v58, v58, v224
	v_mul_f32_e32 v59, v59, v225
	v_lshlrev_b32_e32 v222, 16, v196
	v_and_b32_e32 v223, 0xffff0000, v196
	v_lshlrev_b32_e32 v224, 16, v197
	v_and_b32_e32 v225, 0xffff0000, v197
	v_max_f32_e32 v222, 0xda24260, v222
	v_max_f32_e32 v223, 0xda24260, v223
	v_max_f32_e32 v224, 0xda24260, v224
	v_max_f32_e32 v225, 0xda24260, v225
	v_rcp_f32_e32 v222, v222
	v_rcp_f32_e32 v223, v223
	v_rcp_f32_e32 v224, v224
	v_rcp_f32_e32 v225, v225
	v_lshlrev_b32_e32 v226, 16, v180
	v_and_b32_e32 v227, 0xffff0000, v180
	v_lshlrev_b32_e32 v228, 16, v181
	v_and_b32_e32 v229, 0xffff0000, v181
	v_mul_f32_e32 v222, v222, v226
	v_mul_f32_e32 v223, v223, v227
	v_mul_f32_e32 v224, v224, v228
	v_mul_f32_e32 v225, v225, v229
	v_mul_f32_e32 v60, v60, v222
	v_mul_f32_e32 v61, v61, v223
	v_mul_f32_e32 v62, v62, v224
	v_mul_f32_e32 v63, v63, v225
	global_load_dwordx2 v[174:175], v198, s[12:13]
	global_load_dwordx2 v[190:191], v198, s[12:13] offset:2048
	global_load_dwordx2 v[176:177], v198, s[12:13] offset:32
	global_load_dwordx2 v[192:193], v198, s[12:13] offset:2080
	global_load_dwordx2 v[178:179], v198, s[12:13] offset:64
	global_load_dwordx2 v[194:195], v198, s[12:13] offset:2112
	global_load_dwordx2 v[180:181], v198, s[12:13] offset:96
	global_load_dwordx2 v[196:197], v198, s[12:13] offset:2144
	v_add_u32_e32 v198, 0x10000, v198
	s_waitcnt vmcnt(8)
; DEV float bf2f(u16 h) { return __uint_as_float(((unsigned)h) << 16); }
; DEV void phase_p3a(const Params& p, int g, char* smem) {
;     ...
;     acc_foreach(acc, m0, n0, [&](int m, int n, float& v) {
;       const float ga = bf2f(GT[(size_t)m * 2048 + n]);
;       const float gb = bf2f(GT[(size_t)m * 2048 + 1024 + n]);
;       v *= ga * __builtin_amdgcn_rcpf(fmaxf(gb, 1e-30f));
;     });
	v_lshlrev_b32_e32 v222, 16, v182
	v_and_b32_e32 v223, 0xffff0000, v182
	v_lshlrev_b32_e32 v224, 16, v183
	v_and_b32_e32 v225, 0xffff0000, v183
	v_max_f32_e32 v222, 0xda24260, v222
	v_max_f32_e32 v223, 0xda24260, v223
	v_max_f32_e32 v224, 0xda24260, v224
	v_max_f32_e32 v225, 0xda24260, v225
	v_rcp_f32_e32 v222, v222
	v_rcp_f32_e32 v223, v223
	v_rcp_f32_e32 v224, v224
	v_rcp_f32_e32 v225, v225
	v_lshlrev_b32_e32 v226, 16, v166
	v_and_b32_e32 v227, 0xffff0000, v166
	v_lshlrev_b32_e32 v228, 16, v167
	v_and_b32_e32 v229, 0xffff0000, v167
	v_mul_f32_e32 v222, v222, v226
	v_mul_f32_e32 v223, v223, v227
	v_mul_f32_e32 v224, v224, v228
	v_mul_f32_e32 v225, v225, v229
	v_mul_f32_e32 v64, v64, v222
	v_mul_f32_e32 v65, v65, v223
	v_mul_f32_e32 v66, v66, v224
	v_mul_f32_e32 v67, v67, v225
	v_lshlrev_b32_e32 v222, 16, v184
	v_and_b32_e32 v223, 0xffff0000, v184
	v_lshlrev_b32_e32 v224, 16, v185
	v_and_b32_e32 v225, 0xffff0000, v185
	v_max_f32_e32 v222, 0xda24260, v222
	v_max_f32_e32 v223, 0xda24260, v223
	v_max_f32_e32 v224, 0xda24260, v224
	v_max_f32_e32 v225, 0xda24260, v225
	v_rcp_f32_e32 v222, v222
	v_rcp_f32_e32 v223, v223
	v_rcp_f32_e32 v224, v224
	v_rcp_f32_e32 v225, v225
	v_lshlrev_b32_e32 v226, 16, v168
	v_and_b32_e32 v227, 0xffff0000, v168
	v_lshlrev_b32_e32 v228, 16, v169
	v_and_b32_e32 v229, 0xffff0000, v169
	v_mul_f32_e32 v222, v222, v226
	v_mul_f32_e32 v223, v223, v227
	v_mul_f32_e32 v224, v224, v228
	v_mul_f32_e32 v225, v225, v229
	v_mul_f32_e32 v68, v68, v222
	v_mul_f32_e32 v69, v69, v223
	v_mul_f32_e32 v70, v70, v224
	v_mul_f32_e32 v71, v71, v225
	v_lshlrev_b32_e32 v222, 16, v186
	v_and_b32_e32 v223, 0xffff0000, v186
	v_lshlrev_b32_e32 v224, 16, v187
	v_and_b32_e32 v225, 0xffff0000, v187
	v_max_f32_e32 v222, 0xda24260, v222
	v_max_f32_e32 v223, 0xda24260, v223
	v_max_f32_e32 v224, 0xda24260, v224
	v_max_f32_e32 v225, 0xda24260, v225
	v_rcp_f32_e32 v222, v222
	v_rcp_f32_e32 v223, v223
	v_rcp_f32_e32 v224, v224
	v_rcp_f32_e32 v225, v225
	v_lshlrev_b32_e32 v226, 16, v170
	v_and_b32_e32 v227, 0xffff0000, v170
	v_lshlrev_b32_e32 v228, 16, v171
	v_and_b32_e32 v229, 0xffff0000, v171
	v_mul_f32_e32 v222, v222, v226
	v_mul_f32_e32 v223, v223, v227
	v_mul_f32_e32 v224, v224, v228
	v_mul_f32_e32 v225, v225, v229
	v_mul_f32_e32 v72, v72, v222
	v_mul_f32_e32 v73, v73, v223
	v_mul_f32_e32 v74, v74, v224
	v_mul_f32_e32 v75, v75, v225
	v_lshlrev_b32_e32 v222, 16, v188
	v_and_b32_e32 v223, 0xffff0000, v188
	v_lshlrev_b32_e32 v224, 16, v189
	v_and_b32_e32 v225, 0xffff0000, v189
	v_max_f32_e32 v222, 0xda24260, v222
	v_max_f32_e32 v223, 0xda24260, v223
	v_max_f32_e32 v224, 0xda24260, v224
	v_max_f32_e32 v225, 0xda24260, v225
	v_rcp_f32_e32 v222, v222
	v_rcp_f32_e32 v223, v223
	v_rcp_f32_e32 v224, v224
	v_rcp_f32_e32 v225, v225
	v_lshlrev_b32_e32 v226, 16, v172
	v_and_b32_e32 v227, 0xffff0000, v172
	v_lshlrev_b32_e32 v228, 16, v173
	v_and_b32_e32 v229, 0xffff0000, v173
	v_mul_f32_e32 v222, v222, v226
	v_mul_f32_e32 v223, v223, v227
	v_mul_f32_e32 v224, v224, v228
	v_mul_f32_e32 v225, v225, v229
	v_mul_f32_e32 v76, v76, v222
	v_mul_f32_e32 v77, v77, v223
	v_mul_f32_e32 v78, v78, v224
	v_mul_f32_e32 v79, v79, v225
	global_load_dwordx2 v[166:167], v198, s[12:13]
	global_load_dwordx2 v[182:183], v198, s[12:13] offset:2048
	global_load_dwordx2 v[168:169], v198, s[12:13] offset:32
	global_load_dwordx2 v[184:185], v198, s[12:13] offset:2080
	global_load_dwordx2 v[170:171], v198, s[12:13] offset:64
	global_load_dwordx2 v[186:187], v198, s[12:13] offset:2112
	global_load_dwordx2 v[172:173], v198, s[12:13] offset:96
	global_load_dwordx2 v[188:189], v198, s[12:13] offset:2144
	v_add_u32_e32 v198, 0x10000, v198
	s_waitcnt vmcnt(8)
	v_lshlrev_b32_e32 v222, 16, v190
	v_and_b32_e32 v223, 0xffff0000, v190
	v_lshlrev_b32_e32 v224, 16, v191
	v_and_b32_e32 v225, 0xffff0000, v191
	v_max_f32_e32 v222, 0xda24260, v222
	v_max_f32_e32 v223, 0xda24260, v223
	v_max_f32_e32 v224, 0xda24260, v224
	v_max_f32_e32 v225, 0xda24260, v225
	v_rcp_f32_e32 v222, v222
	v_rcp_f32_e32 v223, v223
	v_rcp_f32_e32 v224, v224
	v_rcp_f32_e32 v225, v225
	v_lshlrev_b32_e32 v226, 16, v174
	v_and_b32_e32 v227, 0xffff0000, v174
	v_lshlrev_b32_e32 v228, 16, v175
	v_and_b32_e32 v229, 0xffff0000, v175
	v_mul_f32_e32 v222, v222, v226
	v_mul_f32_e32 v223, v223, v227
	v_mul_f32_e32 v224, v224, v228
	v_mul_f32_e32 v225, v225, v229
	v_mul_f32_e32 v80, v80, v222
	v_mul_f32_e32 v81, v81, v223
	v_mul_f32_e32 v82, v82, v224
	v_mul_f32_e32 v83, v83, v225
	v_lshlrev_b32_e32 v222, 16, v192
	v_and_b32_e32 v223, 0xffff0000, v192
	v_lshlrev_b32_e32 v224, 16, v193
	v_and_b32_e32 v225, 0xffff0000, v193
	v_max_f32_e32 v222, 0xda24260, v222
	v_max_f32_e32 v223, 0xda24260, v223
	v_max_f32_e32 v224, 0xda24260, v224
	v_max_f32_e32 v225, 0xda24260, v225
	v_rcp_f32_e32 v222, v222
	v_rcp_f32_e32 v223, v223
	v_rcp_f32_e32 v224, v224
	v_rcp_f32_e32 v225, v225
	v_lshlrev_b32_e32 v226, 16, v176
	v_and_b32_e32 v227, 0xffff0000, v176
	v_lshlrev_b32_e32 v228, 16, v177
	v_and_b32_e32 v229, 0xffff0000, v177
	v_mul_f32_e32 v222, v222, v226
	v_mul_f32_e32 v223, v223, v227
	v_mul_f32_e32 v224, v224, v228
	v_mul_f32_e32 v225, v225, v229
	v_mul_f32_e32 v84, v84, v222
	v_mul_f32_e32 v85, v85, v223
	v_mul_f32_e32 v86, v86, v224
	v_mul_f32_e32 v87, v87, v225
	v_lshlrev_b32_e32 v222, 16, v194
	v_and_b32_e32 v223, 0xffff0000, v194
	v_lshlrev_b32_e32 v224, 16, v195
	v_and_b32_e32 v225, 0xffff0000, v195
	v_max_f32_e32 v222, 0xda24260, v222
	v_max_f32_e32 v223, 0xda24260, v223
	v_max_f32_e32 v224, 0xda24260, v224
	v_max_f32_e32 v225, 0xda24260, v225
	v_rcp_f32_e32 v222, v222
	v_rcp_f32_e32 v223, v223
	v_rcp_f32_e32 v224, v224
	v_rcp_f32_e32 v225, v225
; DEV float bf2f(u16 h) { return __uint_as_float(((unsigned)h) << 16); }
; DEV void phase_p3a(const Params& p, int g, char* smem) {
;     ...
;     acc_foreach(acc, m0, n0, [&](int m, int n, float& v) {
;       const float ga = bf2f(GT[(size_t)m * 2048 + n]);
;       const float gb = bf2f(GT[(size_t)m * 2048 + 1024 + n]);
;       v *= ga * __builtin_amdgcn_rcpf(fmaxf(gb, 1e-30f));
;     });
	v_lshlrev_b32_e32 v226, 16, v178
	v_and_b32_e32 v227, 0xffff0000, v178
	v_lshlrev_b32_e32 v228, 16, v179
	v_and_b32_e32 v229, 0xffff0000, v179
	v_mul_f32_e32 v222, v222, v226
	v_mul_f32_e32 v223, v223, v227
	v_mul_f32_e32 v224, v224, v228
	v_mul_f32_e32 v225, v225, v229
	v_mul_f32_e32 v88, v88, v222
	v_mul_f32_e32 v89, v89, v223
	v_mul_f32_e32 v90, v90, v224
	v_mul_f32_e32 v91, v91, v225
	v_lshlrev_b32_e32 v222, 16, v196
	v_and_b32_e32 v223, 0xffff0000, v196
	v_lshlrev_b32_e32 v224, 16, v197
	v_and_b32_e32 v225, 0xffff0000, v197
	v_max_f32_e32 v222, 0xda24260, v222
	v_max_f32_e32 v223, 0xda24260, v223
	v_max_f32_e32 v224, 0xda24260, v224
	v_max_f32_e32 v225, 0xda24260, v225
	v_rcp_f32_e32 v222, v222
	v_rcp_f32_e32 v223, v223
	v_rcp_f32_e32 v224, v224
	v_rcp_f32_e32 v225, v225
	v_lshlrev_b32_e32 v226, 16, v180
	v_and_b32_e32 v227, 0xffff0000, v180
	v_lshlrev_b32_e32 v228, 16, v181
	v_and_b32_e32 v229, 0xffff0000, v181
	v_mul_f32_e32 v222, v222, v226
	v_mul_f32_e32 v223, v223, v227
	v_mul_f32_e32 v224, v224, v228
	v_mul_f32_e32 v225, v225, v229
	v_mul_f32_e32 v92, v92, v222
	v_mul_f32_e32 v93, v93, v223
	v_mul_f32_e32 v94, v94, v224
	v_mul_f32_e32 v95, v95, v225
	global_load_dwordx2 v[174:175], v198, s[12:13]
	global_load_dwordx2 v[190:191], v198, s[12:13] offset:2048
	global_load_dwordx2 v[176:177], v198, s[12:13] offset:32
	global_load_dwordx2 v[192:193], v198, s[12:13] offset:2080
	global_load_dwordx2 v[178:179], v198, s[12:13] offset:64
	global_load_dwordx2 v[194:195], v198, s[12:13] offset:2112
	global_load_dwordx2 v[180:181], v198, s[12:13] offset:96
	global_load_dwordx2 v[196:197], v198, s[12:13] offset:2144
	v_add_u32_e32 v198, 0x10000, v198
	s_waitcnt vmcnt(8)
	v_lshlrev_b32_e32 v222, 16, v182
	v_and_b32_e32 v223, 0xffff0000, v182
	v_lshlrev_b32_e32 v224, 16, v183
	v_and_b32_e32 v225, 0xffff0000, v183
	v_max_f32_e32 v222, 0xda24260, v222
	v_max_f32_e32 v223, 0xda24260, v223
	v_max_f32_e32 v224, 0xda24260, v224
	v_max_f32_e32 v225, 0xda24260, v225
	v_rcp_f32_e32 v222, v222
	v_rcp_f32_e32 v223, v223
	v_rcp_f32_e32 v224, v224
	v_rcp_f32_e32 v225, v225
	v_lshlrev_b32_e32 v226, 16, v166
	v_and_b32_e32 v227, 0xffff0000, v166
	v_lshlrev_b32_e32 v228, 16, v167
	v_and_b32_e32 v229, 0xffff0000, v167
	v_mul_f32_e32 v222, v222, v226
	v_mul_f32_e32 v223, v223, v227
	v_mul_f32_e32 v224, v224, v228
	v_mul_f32_e32 v225, v225, v229
	v_mul_f32_e32 v96, v96, v222
	v_mul_f32_e32 v97, v97, v223
	v_mul_f32_e32 v98, v98, v224
	v_mul_f32_e32 v99, v99, v225
	v_lshlrev_b32_e32 v222, 16, v184
	v_and_b32_e32 v223, 0xffff0000, v184
	v_lshlrev_b32_e32 v224, 16, v185
	v_and_b32_e32 v225, 0xffff0000, v185
	v_max_f32_e32 v222, 0xda24260, v222
	v_max_f32_e32 v223, 0xda24260, v223
	v_max_f32_e32 v224, 0xda24260, v224
	v_max_f32_e32 v225, 0xda24260, v225
	v_rcp_f32_e32 v222, v222
	v_rcp_f32_e32 v223, v223
	v_rcp_f32_e32 v224, v224
	v_rcp_f32_e32 v225, v225
	v_lshlrev_b32_e32 v226, 16, v168
	v_and_b32_e32 v227, 0xffff0000, v168
	v_lshlrev_b32_e32 v228, 16, v169
	v_and_b32_e32 v229, 0xffff0000, v169
	v_mul_f32_e32 v222, v222, v226
	v_mul_f32_e32 v223, v223, v227
	v_mul_f32_e32 v224, v224, v228
	v_mul_f32_e32 v225, v225, v229
	v_mul_f32_e32 v100, v100, v222
	v_mul_f32_e32 v101, v101, v223
	v_mul_f32_e32 v102, v102, v224
	v_mul_f32_e32 v103, v103, v225
	v_lshlrev_b32_e32 v222, 16, v186
	v_and_b32_e32 v223, 0xffff0000, v186
	v_lshlrev_b32_e32 v224, 16, v187
	v_and_b32_e32 v225, 0xffff0000, v187
	v_max_f32_e32 v222, 0xda24260, v222
	v_max_f32_e32 v223, 0xda24260, v223
	v_max_f32_e32 v224, 0xda24260, v224
	v_max_f32_e32 v225, 0xda24260, v225
	v_rcp_f32_e32 v222, v222
	v_rcp_f32_e32 v223, v223
	v_rcp_f32_e32 v224, v224
	v_rcp_f32_e32 v225, v225
	v_lshlrev_b32_e32 v226, 16, v170
	v_and_b32_e32 v227, 0xffff0000, v170
	v_lshlrev_b32_e32 v228, 16, v171
	v_and_b32_e32 v229, 0xffff0000, v171
	v_mul_f32_e32 v222, v222, v226
	v_mul_f32_e32 v223, v223, v227
	v_mul_f32_e32 v224, v224, v228
	v_mul_f32_e32 v225, v225, v229
	v_mul_f32_e32 v104, v104, v222
	v_mul_f32_e32 v105, v105, v223
	v_mul_f32_e32 v106, v106, v224
	v_mul_f32_e32 v107, v107, v225
	v_lshlrev_b32_e32 v222, 16, v188
	v_and_b32_e32 v223, 0xffff0000, v188
	v_lshlrev_b32_e32 v224, 16, v189
	v_and_b32_e32 v225, 0xffff0000, v189
	v_max_f32_e32 v222, 0xda24260, v222
	v_max_f32_e32 v223, 0xda24260, v223
	v_max_f32_e32 v224, 0xda24260, v224
	v_max_f32_e32 v225, 0xda24260, v225
	v_rcp_f32_e32 v222, v222
	v_rcp_f32_e32 v223, v223
	v_rcp_f32_e32 v224, v224
	v_rcp_f32_e32 v225, v225
	v_lshlrev_b32_e32 v226, 16, v172
	v_and_b32_e32 v227, 0xffff0000, v172
	v_lshlrev_b32_e32 v228, 16, v173
	v_and_b32_e32 v229, 0xffff0000, v173
	v_mul_f32_e32 v222, v222, v226
	v_mul_f32_e32 v223, v223, v227
	v_mul_f32_e32 v224, v224, v228
	v_mul_f32_e32 v225, v225, v229
	v_mul_f32_e32 v108, v108, v222
	v_mul_f32_e32 v109, v109, v223
	v_mul_f32_e32 v110, v110, v224
	v_mul_f32_e32 v111, v111, v225
	s_waitcnt vmcnt(0)
; DEV float bf2f(u16 h) { return __uint_as_float(((unsigned)h) << 16); }
; DEV void phase_p3a(const Params& p, int g, char* smem) {
;     ...
;     acc_foreach(acc, m0, n0, [&](int m, int n, float& v) {
;       const float ga = bf2f(GT[(size_t)m * 2048 + n]);
;       const float gb = bf2f(GT[(size_t)m * 2048 + 1024 + n]);
;       v *= ga * __builtin_amdgcn_rcpf(fmaxf(gb, 1e-30f));
;     });
;     {
;       RowLoader al{PHG - 512, 2560};
;       RowLoader bl{WbrT, 1024};
;       gemm_mainloop(acc, al, bl, m0, n0, 512, 1024, smem);
	v_lshlrev_b32_e32 v222, 16, v190
	v_and_b32_e32 v223, 0xffff0000, v190
	v_lshlrev_b32_e32 v224, 16, v191
	v_and_b32_e32 v225, 0xffff0000, v191
	v_max_f32_e32 v222, 0xda24260, v222
	v_max_f32_e32 v223, 0xda24260, v223
	v_max_f32_e32 v224, 0xda24260, v224
	v_max_f32_e32 v225, 0xda24260, v225
	v_rcp_f32_e32 v222, v222
	v_rcp_f32_e32 v223, v223
	v_rcp_f32_e32 v224, v224
	v_rcp_f32_e32 v225, v225
	v_lshlrev_b32_e32 v226, 16, v174
	v_and_b32_e32 v227, 0xffff0000, v174
	v_lshlrev_b32_e32 v228, 16, v175
	v_and_b32_e32 v229, 0xffff0000, v175
	v_mul_f32_e32 v222, v222, v226
	v_mul_f32_e32 v223, v223, v227
	v_mul_f32_e32 v224, v224, v228
	v_mul_f32_e32 v225, v225, v229
	v_mul_f32_e32 v112, v112, v222
	v_mul_f32_e32 v113, v113, v223
	v_mul_f32_e32 v114, v114, v224
	v_mul_f32_e32 v115, v115, v225
	v_lshlrev_b32_e32 v222, 16, v192
	v_and_b32_e32 v223, 0xffff0000, v192
	v_lshlrev_b32_e32 v224, 16, v193
	v_and_b32_e32 v225, 0xffff0000, v193
	v_max_f32_e32 v222, 0xda24260, v222
	v_max_f32_e32 v223, 0xda24260, v223
	v_max_f32_e32 v224, 0xda24260, v224
	v_max_f32_e32 v225, 0xda24260, v225
	v_rcp_f32_e32 v222, v222
	v_rcp_f32_e32 v223, v223
	v_rcp_f32_e32 v224, v224
	v_rcp_f32_e32 v225, v225
	v_lshlrev_b32_e32 v226, 16, v176
	v_and_b32_e32 v227, 0xffff0000, v176
	v_lshlrev_b32_e32 v228, 16, v177
	v_and_b32_e32 v229, 0xffff0000, v177
	v_mul_f32_e32 v222, v222, v226
	v_mul_f32_e32 v223, v223, v227
	v_mul_f32_e32 v224, v224, v228
	v_mul_f32_e32 v225, v225, v229
	v_mul_f32_e32 v116, v116, v222
	v_mul_f32_e32 v117, v117, v223
	v_mul_f32_e32 v118, v118, v224
	v_mul_f32_e32 v119, v119, v225
	v_lshlrev_b32_e32 v222, 16, v194
	v_and_b32_e32 v223, 0xffff0000, v194
	v_lshlrev_b32_e32 v224, 16, v195
	v_and_b32_e32 v225, 0xffff0000, v195
	v_max_f32_e32 v222, 0xda24260, v222
	v_max_f32_e32 v223, 0xda24260, v223
	v_max_f32_e32 v224, 0xda24260, v224
	v_max_f32_e32 v225, 0xda24260, v225
	v_rcp_f32_e32 v222, v222
	v_rcp_f32_e32 v223, v223
	v_rcp_f32_e32 v224, v224
	v_rcp_f32_e32 v225, v225
	v_lshlrev_b32_e32 v226, 16, v178
	v_and_b32_e32 v227, 0xffff0000, v178
	v_lshlrev_b32_e32 v228, 16, v179
	v_and_b32_e32 v229, 0xffff0000, v179
	v_mul_f32_e32 v222, v222, v226
	v_mul_f32_e32 v223, v223, v227
	v_mul_f32_e32 v224, v224, v228
	v_mul_f32_e32 v225, v225, v229
	v_mul_f32_e32 v120, v120, v222
	v_mul_f32_e32 v121, v121, v223
	v_mul_f32_e32 v122, v122, v224
	v_mul_f32_e32 v123, v123, v225
	v_lshlrev_b32_e32 v222, 16, v196
	v_and_b32_e32 v223, 0xffff0000, v196
	v_lshlrev_b32_e32 v224, 16, v197
	v_and_b32_e32 v225, 0xffff0000, v197
	v_max_f32_e32 v222, 0xda24260, v222
	v_max_f32_e32 v223, 0xda24260, v223
	v_max_f32_e32 v224, 0xda24260, v224
	v_max_f32_e32 v225, 0xda24260, v225
	v_rcp_f32_e32 v222, v222
	v_rcp_f32_e32 v223, v223
	v_rcp_f32_e32 v224, v224
	v_rcp_f32_e32 v225, v225
	v_lshlrev_b32_e32 v226, 16, v180
	v_and_b32_e32 v227, 0xffff0000, v180
	v_lshlrev_b32_e32 v228, 16, v181
	v_and_b32_e32 v229, 0xffff0000, v181
	v_mul_f32_e32 v222, v222, v226
	v_mul_f32_e32 v223, v223, v227
	v_mul_f32_e32 v224, v224, v228
	v_mul_f32_e32 v225, v225, v229
	v_mul_f32_e32 v124, v124, v222
	v_mul_f32_e32 v125, v125, v223
	v_mul_f32_e32 v126, v126, v224
	v_mul_f32_e32 v127, v127, v225
.Lp3a_mid1:
	s_mov_b32 s8, 0
	s_waitcnt vmcnt(0)
	s_barrier
.Lp3a_k2loop:
	s_cmp_lt_u32 s5, 0x4000
	s_cbranch_scc0 .Lp3a_u2
	s_add_u32 m0, s5, 0x8000
	s_nop 0
	global_load_lds_dwordx4 v128, s[0:1]
	s_add_u32 m0, m0, 0x400
	s_nop 0
	global_load_lds_dwordx4 v129, s[0:1]
	s_add_u32 m0, m0, 0x400
	s_nop 0
	global_load_lds_dwordx4 v130, s[0:1]
	s_add_u32 m0, m0, 0x400
	s_nop 0
	global_load_lds_dwordx4 v131, s[0:1]
	s_add_u32 m0, s5, 0x18000
	s_nop 0
	global_load_lds_dwordx4 v132, s[6:7]
	s_add_u32 m0, m0, 0x400
	s_nop 0
	global_load_lds_dwordx4 v133, s[6:7]
	s_add_u32 m0, m0, 0x400
	s_nop 0
	global_load_lds_dwordx4 v134, s[6:7]
	s_add_u32 m0, m0, 0x400
	s_nop 0
	global_load_lds_dwordx4 v135, s[6:7]
	s_add_u32 m0, s5, 0xc000
	s_nop 0
	global_load_lds_dwordx4 v136, s[0:1]
	s_add_u32 m0, m0, 0x400
	s_nop 0
	global_load_lds_dwordx4 v137, s[0:1]
	s_add_u32 m0, m0, 0x400
	s_nop 0
	global_load_lds_dwordx4 v138, s[0:1]
	s_add_u32 m0, m0, 0x400
	s_nop 0
	global_load_lds_dwordx4 v139, s[0:1]
	s_add_u32 m0, s5, 0x1c000
	s_nop 0
	global_load_lds_dwordx4 v140, s[6:7]
	s_add_u32 m0, m0, 0x400
	s_nop 0
	global_load_lds_dwordx4 v141, s[6:7]
	s_add_u32 m0, m0, 0x400
	s_nop 0
	global_load_lds_dwordx4 v142, s[6:7]
	s_add_u32 m0, m0, 0x400
	s_nop 0
	global_load_lds_dwordx4 v143, s[6:7]
; template <class AL, class BL>
; DEV void gemm_ktile(Acc& acc, const char* A, const char* B, int wm, int wn, int lr, int lh, const AL& al, const BL& bl,
;                     int tid, int m0, int n0, int knext, char* nxt, R4& ra, R4& rb) {
;     ...
;   for (int ks = 0; ks < 4; ++ks) {
;     const int cur = ks & 1, nx = cur ^ 1;
;     if (ks < 3) {
; #pragma unroll
;       for (int i = 0; i < 4; ++i) a[nx][i] = *(const bf16x8*)(pa + 32 * i * LDSROW + (ks + 1) * 32);
; #pragma unroll
;       for (int j = 0; j < 2; ++j) b[nx][j] = *(const bf16x8*)(pb + 32 * j * LDSROW + (ks + 1) * 32);
;     }
;     __builtin_amdgcn_sched_barrier(0);
; #pragma unroll
;     for (int i = 0; i < 4; ++i)
; #pragma unroll
;       for (int j = 0; j < 2; ++j)
;         acc[i][j] = __builtin_amdgcn_mfma_f32_32x32x16_bf16(a[cur][i], b[cur][j], acc[i][j], 0, 0, 0);
;     __builtin_amdgcn_sched_barrier(0);
; DEV void phase_p3a(const Params& p, int g, char* smem) {
;     ...
;       RowLoader al{PHG - 512, 2560};
;       RowLoader bl{WbrT, 1024};
;       gemm_mainloop(acc, al, bl, m0, n0, 512, 1024, smem);
.Lp3a_u2:
	s_add_u32 s0, s0, 0x80
	s_addc_u32 s1, s1, 0
	s_add_u32 s6, s6, 0x80
	s_addc_u32 s7, s7, 0
	ds_read_b128 v[166:169], v146
	ds_read_b128 v[170:173], v146 offset:2048
	ds_read_b128 v[174:177], v146 offset:4096
	ds_read_b128 v[178:181], v146 offset:6144
	ds_read_b128 v[222:225], v144
	ds_read_b128 v[226:229], v144 offset:2048
	ds_read_b128 v[230:233], v144 offset:4096
	ds_read_b128 v[234:237], v144 offset:6144
	ds_read_b128 v[238:241], v144 offset:8192
	ds_read_b128 v[198:201], v144 offset:10240
	ds_read_b128 v[152:155], v144 offset:12288
	ds_read_b128 v[156:159], v144 offset:14336
	ds_read_b128 v[182:185], v147
	ds_read_b128 v[186:189], v147 offset:2048
	ds_read_b128 v[190:193], v147 offset:4096
	ds_read_b128 v[194:197], v147 offset:6144
	s_waitcnt lgkmcnt(8)
	v_mfma_f32_16x16x32_bf16 v[0:3], v[166:169], v[222:225], v[0:3]
	v_mfma_f32_16x16x32_bf16 v[4:7], v[170:173], v[222:225], v[4:7]
	v_mfma_f32_16x16x32_bf16 v[8:11], v[174:177], v[222:225], v[8:11]
	v_mfma_f32_16x16x32_bf16 v[12:15], v[178:181], v[222:225], v[12:15]
	v_mfma_f32_16x16x32_bf16 v[16:19], v[166:169], v[226:229], v[16:19]
	v_mfma_f32_16x16x32_bf16 v[20:23], v[170:173], v[226:229], v[20:23]
	v_mfma_f32_16x16x32_bf16 v[24:27], v[174:177], v[226:229], v[24:27]
	v_mfma_f32_16x16x32_bf16 v[28:31], v[178:181], v[226:229], v[28:31]
	v_mfma_f32_16x16x32_bf16 v[32:35], v[166:169], v[230:233], v[32:35]
	v_mfma_f32_16x16x32_bf16 v[36:39], v[170:173], v[230:233], v[36:39]
	v_mfma_f32_16x16x32_bf16 v[40:43], v[174:177], v[230:233], v[40:43]
	v_mfma_f32_16x16x32_bf16 v[44:47], v[178:181], v[230:233], v[44:47]
	v_mfma_f32_16x16x32_bf16 v[48:51], v[166:169], v[234:237], v[48:51]
	v_mfma_f32_16x16x32_bf16 v[52:55], v[170:173], v[234:237], v[52:55]
	v_mfma_f32_16x16x32_bf16 v[56:59], v[174:177], v[234:237], v[56:59]
	v_mfma_f32_16x16x32_bf16 v[60:63], v[178:181], v[234:237], v[60:63]
	ds_read_b128 v[222:225], v145
	ds_read_b128 v[226:229], v145 offset:2048
	ds_read_b128 v[230:233], v145 offset:4096
	ds_read_b128 v[234:237], v145 offset:6144
	s_waitcnt lgkmcnt(8)
	v_mfma_f32_16x16x32_bf16 v[64:67], v[166:169], v[238:241], v[64:67]
	v_mfma_f32_16x16x32_bf16 v[68:71], v[170:173], v[238:241], v[68:71]
	v_mfma_f32_16x16x32_bf16 v[72:75], v[174:177], v[238:241], v[72:75]
	v_mfma_f32_16x16x32_bf16 v[76:79], v[178:181], v[238:241], v[76:79]
	v_mfma_f32_16x16x32_bf16 v[80:83], v[166:169], v[198:201], v[80:83]
	v_mfma_f32_16x16x32_bf16 v[84:87], v[170:173], v[198:201], v[84:87]
	v_mfma_f32_16x16x32_bf16 v[88:91], v[174:177], v[198:201], v[88:91]
	v_mfma_f32_16x16x32_bf16 v[92:95], v[178:181], v[198:201], v[92:95]
	v_mfma_f32_16x16x32_bf16 v[96:99], v[166:169], v[152:155], v[96:99]
	v_mfma_f32_16x16x32_bf16 v[100:103], v[170:173], v[152:155], v[100:103]
	v_mfma_f32_16x16x32_bf16 v[104:107], v[174:177], v[152:155], v[104:107]
	v_mfma_f32_16x16x32_bf16 v[108:111], v[178:181], v[152:155], v[108:111]
	v_mfma_f32_16x16x32_bf16 v[112:115], v[166:169], v[156:159], v[112:115]
	v_mfma_f32_16x16x32_bf16 v[116:119], v[170:173], v[156:159], v[116:119]
	v_mfma_f32_16x16x32_bf16 v[120:123], v[174:177], v[156:159], v[120:123]
	v_mfma_f32_16x16x32_bf16 v[124:127], v[178:181], v[156:159], v[124:127]
	ds_read_b128 v[238:241], v145 offset:8192
	ds_read_b128 v[198:201], v145 offset:10240
	ds_read_b128 v[152:155], v145 offset:12288
	ds_read_b128 v[156:159], v145 offset:14336
	s_waitcnt lgkmcnt(4)
	v_mfma_f32_16x16x32_bf16 v[0:3], v[182:185], v[222:225], v[0:3]
	v_mfma_f32_16x16x32_bf16 v[4:7], v[186:189], v[222:225], v[4:7]
	v_mfma_f32_16x16x32_bf16 v[8:11], v[190:193], v[222:225], v[8:11]
	v_mfma_f32_16x16x32_bf16 v[12:15], v[194:197], v[222:225], v[12:15]
	v_mfma_f32_16x16x32_bf16 v[16:19], v[182:185], v[226:229], v[16:19]
	v_mfma_f32_16x16x32_bf16 v[20:23], v[186:189], v[226:229], v[20:23]
	v_mfma_f32_16x16x32_bf16 v[24:27], v[190:193], v[226:229], v[24:27]
	v_mfma_f32_16x16x32_bf16 v[28:31], v[194:197], v[226:229], v[28:31]
	v_mfma_f32_16x16x32_bf16 v[32:35], v[182:185], v[230:233], v[32:35]
	v_mfma_f32_16x16x32_bf16 v[36:39], v[186:189], v[230:233], v[36:39]
	v_mfma_f32_16x16x32_bf16 v[40:43], v[190:193], v[230:233], v[40:43]
	v_mfma_f32_16x16x32_bf16 v[44:47], v[194:197], v[230:233], v[44:47]
	v_mfma_f32_16x16x32_bf16 v[48:51], v[182:185], v[234:237], v[48:51]
	v_mfma_f32_16x16x32_bf16 v[52:55], v[186:189], v[234:237], v[52:55]
	v_mfma_f32_16x16x32_bf16 v[56:59], v[190:193], v[234:237], v[56:59]
	v_mfma_f32_16x16x32_bf16 v[60:63], v[194:197], v[234:237], v[60:63]
	s_waitcnt lgkmcnt(0)
	v_mfma_f32_16x16x32_bf16 v[64:67], v[182:185], v[238:241], v[64:67]
	v_mfma_f32_16x16x32_bf16 v[68:71], v[186:189], v[238:241], v[68:71]
	v_mfma_f32_16x16x32_bf16 v[72:75], v[190:193], v[238:241], v[72:75]
	v_mfma_f32_16x16x32_bf16 v[76:79], v[194:197], v[238:241], v[76:79]
	v_mfma_f32_16x16x32_bf16 v[80:83], v[182:185], v[198:201], v[80:83]
	v_mfma_f32_16x16x32_bf16 v[84:87], v[186:189], v[198:201], v[84:87]
	v_mfma_f32_16x16x32_bf16 v[88:91], v[190:193], v[198:201], v[88:91]
	v_mfma_f32_16x16x32_bf16 v[92:95], v[194:197], v[198:201], v[92:95]
	v_mfma_f32_16x16x32_bf16 v[96:99], v[182:185], v[152:155], v[96:99]
	v_mfma_f32_16x16x32_bf16 v[100:103], v[186:189], v[152:155], v[100:103]
	v_mfma_f32_16x16x32_bf16 v[104:107], v[190:193], v[152:155], v[104:107]
	v_mfma_f32_16x16x32_bf16 v[108:111], v[194:197], v[152:155], v[108:111]
	v_mfma_f32_16x16x32_bf16 v[112:115], v[182:185], v[156:159], v[112:115]
	v_mfma_f32_16x16x32_bf16 v[116:119], v[186:189], v[156:159], v[116:119]
	v_mfma_f32_16x16x32_bf16 v[120:123], v[190:193], v[156:159], v[120:123]
	v_mfma_f32_16x16x32_bf16 v[124:127], v[194:197], v[156:159], v[124:127]
	s_waitcnt vmcnt(0)
	s_barrier
	s_cmp_eq_u32 s8, 3
	s_cbranch_scc1 .Lp3a_k2last
	s_cmp_lt_u32 s5, 0x4000
	s_cbranch_scc0 .Lp3a_u3
	s_add_u32 m0, s5, 0x0
	s_nop 0
	global_load_lds_dwordx4 v128, s[0:1]
	s_add_u32 m0, m0, 0x400
	s_nop 0
	global_load_lds_dwordx4 v129, s[0:1]
	s_add_u32 m0, m0, 0x400
	s_nop 0
	global_load_lds_dwordx4 v130, s[0:1]
	s_add_u32 m0, m0, 0x400
	s_nop 0
	global_load_lds_dwordx4 v131, s[0:1]
	s_add_u32 m0, s5, 0x10000
	s_nop 0
	global_load_lds_dwordx4 v132, s[6:7]
	s_add_u32 m0, m0, 0x400
	s_nop 0
	global_load_lds_dwordx4 v133, s[6:7]
	s_add_u32 m0, m0, 0x400
	s_nop 0
	global_load_lds_dwordx4 v134, s[6:7]
	s_add_u32 m0, m0, 0x400
	s_nop 0
	global_load_lds_dwordx4 v135, s[6:7]
	s_add_u32 m0, s5, 0x4000
	s_nop 0
	global_load_lds_dwordx4 v136, s[0:1]
	s_add_u32 m0, m0, 0x400
	s_nop 0
	global_load_lds_dwordx4 v137, s[0:1]
	s_add_u32 m0, m0, 0x400
	s_nop 0
	global_load_lds_dwordx4 v138, s[0:1]
	s_add_u32 m0, m0, 0x400
	s_nop 0
	global_load_lds_dwordx4 v139, s[0:1]
	s_add_u32 m0, s5, 0x14000
	s_nop 0
	global_load_lds_dwordx4 v140, s[6:7]
	s_add_u32 m0, m0, 0x400
	s_nop 0
	global_load_lds_dwordx4 v141, s[6:7]
	s_add_u32 m0, m0, 0x400
	s_nop 0
	global_load_lds_dwordx4 v142, s[6:7]
	s_add_u32 m0, m0, 0x400
	s_nop 0
	global_load_lds_dwordx4 v143, s[6:7]
; template <class AL, class BL>
; DEV void gemm_ktile(Acc& acc, const char* A, const char* B, int wm, int wn, int lr, int lh, const AL& al, const BL& bl,
;                     int tid, int m0, int n0, int knext, char* nxt, R4& ra, R4& rb) {
;     ...
;   for (int ks = 0; ks < 4; ++ks) {
;     const int cur = ks & 1, nx = cur ^ 1;
;     if (ks < 3) {
; #pragma unroll
;       for (int i = 0; i < 4; ++i) a[nx][i] = *(const bf16x8*)(pa + 32 * i * LDSROW + (ks + 1) * 32);
; #pragma unroll
;       for (int j = 0; j < 2; ++j) b[nx][j] = *(const bf16x8*)(pb + 32 * j * LDSROW + (ks + 1) * 32);
;     }
;     __builtin_amdgcn_sched_barrier(0);
; #pragma unroll
;     for (int i = 0; i < 4; ++i)
; #pragma unroll
;       for (int j = 0; j < 2; ++j)
;         acc[i][j] = __builtin_amdgcn_mfma_f32_32x32x16_bf16(a[cur][i], b[cur][j], acc[i][j], 0, 0, 0);
;     __builtin_amdgcn_sched_barrier(0);
; DEV void phase_p3a(const Params& p, int g, char* smem) {
;     ...
;       RowLoader al{PHG - 512, 2560};
;       RowLoader bl{WbrT, 1024};
;       gemm_mainloop(acc, al, bl, m0, n0, 512, 1024, smem);
.Lp3a_u3:
	s_add_u32 s0, s0, 0x80
	s_addc_u32 s1, s1, 0
	s_add_u32 s6, s6, 0x80
	s_addc_u32 s7, s7, 0
	ds_read_b128 v[166:169], v146 offset:32768
	ds_read_b128 v[170:173], v146 offset:34816
	ds_read_b128 v[174:177], v146 offset:36864
	ds_read_b128 v[178:181], v146 offset:38912
	ds_read_b128 v[222:225], v144 offset:32768
	ds_read_b128 v[226:229], v144 offset:34816
	ds_read_b128 v[230:233], v144 offset:36864
	ds_read_b128 v[234:237], v144 offset:38912
	ds_read_b128 v[238:241], v144 offset:40960
	ds_read_b128 v[198:201], v144 offset:43008
	ds_read_b128 v[152:155], v144 offset:45056
	ds_read_b128 v[156:159], v144 offset:47104
	ds_read_b128 v[182:185], v147 offset:32768
	ds_read_b128 v[186:189], v147 offset:34816
	ds_read_b128 v[190:193], v147 offset:36864
	ds_read_b128 v[194:197], v147 offset:38912
	s_waitcnt lgkmcnt(8)
	v_mfma_f32_16x16x32_bf16 v[0:3], v[166:169], v[222:225], v[0:3]
	v_mfma_f32_16x16x32_bf16 v[4:7], v[170:173], v[222:225], v[4:7]
	v_mfma_f32_16x16x32_bf16 v[8:11], v[174:177], v[222:225], v[8:11]
	v_mfma_f32_16x16x32_bf16 v[12:15], v[178:181], v[222:225], v[12:15]
	v_mfma_f32_16x16x32_bf16 v[16:19], v[166:169], v[226:229], v[16:19]
	v_mfma_f32_16x16x32_bf16 v[20:23], v[170:173], v[226:229], v[20:23]
	v_mfma_f32_16x16x32_bf16 v[24:27], v[174:177], v[226:229], v[24:27]
	v_mfma_f32_16x16x32_bf16 v[28:31], v[178:181], v[226:229], v[28:31]
	v_mfma_f32_16x16x32_bf16 v[32:35], v[166:169], v[230:233], v[32:35]
	v_mfma_f32_16x16x32_bf16 v[36:39], v[170:173], v[230:233], v[36:39]
	v_mfma_f32_16x16x32_bf16 v[40:43], v[174:177], v[230:233], v[40:43]
	v_mfma_f32_16x16x32_bf16 v[44:47], v[178:181], v[230:233], v[44:47]
	v_mfma_f32_16x16x32_bf16 v[48:51], v[166:169], v[234:237], v[48:51]
	v_mfma_f32_16x16x32_bf16 v[52:55], v[170:173], v[234:237], v[52:55]
	v_mfma_f32_16x16x32_bf16 v[56:59], v[174:177], v[234:237], v[56:59]
	v_mfma_f32_16x16x32_bf16 v[60:63], v[178:181], v[234:237], v[60:63]
	ds_read_b128 v[222:225], v145 offset:32768
	ds_read_b128 v[226:229], v145 offset:34816
	ds_read_b128 v[230:233], v145 offset:36864
	ds_read_b128 v[234:237], v145 offset:38912
	s_waitcnt lgkmcnt(8)
	v_mfma_f32_16x16x32_bf16 v[64:67], v[166:169], v[238:241], v[64:67]
	v_mfma_f32_16x16x32_bf16 v[68:71], v[170:173], v[238:241], v[68:71]
	v_mfma_f32_16x16x32_bf16 v[72:75], v[174:177], v[238:241], v[72:75]
	v_mfma_f32_16x16x32_bf16 v[76:79], v[178:181], v[238:241], v[76:79]
	v_mfma_f32_16x16x32_bf16 v[80:83], v[166:169], v[198:201], v[80:83]
	v_mfma_f32_16x16x32_bf16 v[84:87], v[170:173], v[198:201], v[84:87]
	v_mfma_f32_16x16x32_bf16 v[88:91], v[174:177], v[198:201], v[88:91]
	v_mfma_f32_16x16x32_bf16 v[92:95], v[178:181], v[198:201], v[92:95]
	v_mfma_f32_16x16x32_bf16 v[96:99], v[166:169], v[152:155], v[96:99]
	v_mfma_f32_16x16x32_bf16 v[100:103], v[170:173], v[152:155], v[100:103]
	v_mfma_f32_16x16x32_bf16 v[104:107], v[174:177], v[152:155], v[104:107]
	v_mfma_f32_16x16x32_bf16 v[108:111], v[178:181], v[152:155], v[108:111]
	v_mfma_f32_16x16x32_bf16 v[112:115], v[166:169], v[156:159], v[112:115]
	v_mfma_f32_16x16x32_bf16 v[116:119], v[170:173], v[156:159], v[116:119]
	v_mfma_f32_16x16x32_bf16 v[120:123], v[174:177], v[156:159], v[120:123]
	v_mfma_f32_16x16x32_bf16 v[124:127], v[178:181], v[156:159], v[124:127]
	ds_read_b128 v[238:241], v145 offset:40960
	ds_read_b128 v[198:201], v145 offset:43008
	ds_read_b128 v[152:155], v145 offset:45056
	ds_read_b128 v[156:159], v145 offset:47104
	s_waitcnt lgkmcnt(4)
	v_mfma_f32_16x16x32_bf16 v[0:3], v[182:185], v[222:225], v[0:3]
	v_mfma_f32_16x16x32_bf16 v[4:7], v[186:189], v[222:225], v[4:7]
	v_mfma_f32_16x16x32_bf16 v[8:11], v[190:193], v[222:225], v[8:11]
	v_mfma_f32_16x16x32_bf16 v[12:15], v[194:197], v[222:225], v[12:15]
	v_mfma_f32_16x16x32_bf16 v[16:19], v[182:185], v[226:229], v[16:19]
	v_mfma_f32_16x16x32_bf16 v[20:23], v[186:189], v[226:229], v[20:23]
	v_mfma_f32_16x16x32_bf16 v[24:27], v[190:193], v[226:229], v[24:27]
	v_mfma_f32_16x16x32_bf16 v[28:31], v[194:197], v[226:229], v[28:31]
	v_mfma_f32_16x16x32_bf16 v[32:35], v[182:185], v[230:233], v[32:35]
	v_mfma_f32_16x16x32_bf16 v[36:39], v[186:189], v[230:233], v[36:39]
	v_mfma_f32_16x16x32_bf16 v[40:43], v[190:193], v[230:233], v[40:43]
	v_mfma_f32_16x16x32_bf16 v[44:47], v[194:197], v[230:233], v[44:47]
	v_mfma_f32_16x16x32_bf16 v[48:51], v[182:185], v[234:237], v[48:51]
	v_mfma_f32_16x16x32_bf16 v[52:55], v[186:189], v[234:237], v[52:55]
	v_mfma_f32_16x16x32_bf16 v[56:59], v[190:193], v[234:237], v[56:59]
	v_mfma_f32_16x16x32_bf16 v[60:63], v[194:197], v[234:237], v[60:63]
	s_waitcnt lgkmcnt(0)
	v_mfma_f32_16x16x32_bf16 v[64:67], v[182:185], v[238:241], v[64:67]
	v_mfma_f32_16x16x32_bf16 v[68:71], v[186:189], v[238:241], v[68:71]
	v_mfma_f32_16x16x32_bf16 v[72:75], v[190:193], v[238:241], v[72:75]
	v_mfma_f32_16x16x32_bf16 v[76:79], v[194:197], v[238:241], v[76:79]
	v_mfma_f32_16x16x32_bf16 v[80:83], v[182:185], v[198:201], v[80:83]
	v_mfma_f32_16x16x32_bf16 v[84:87], v[186:189], v[198:201], v[84:87]
	v_mfma_f32_16x16x32_bf16 v[88:91], v[190:193], v[198:201], v[88:91]
	v_mfma_f32_16x16x32_bf16 v[92:95], v[194:197], v[198:201], v[92:95]
	v_mfma_f32_16x16x32_bf16 v[96:99], v[182:185], v[152:155], v[96:99]
	v_mfma_f32_16x16x32_bf16 v[100:103], v[186:189], v[152:155], v[100:103]
	v_mfma_f32_16x16x32_bf16 v[104:107], v[190:193], v[152:155], v[104:107]
	v_mfma_f32_16x16x32_bf16 v[108:111], v[194:197], v[152:155], v[108:111]
	v_mfma_f32_16x16x32_bf16 v[112:115], v[182:185], v[156:159], v[112:115]
	v_mfma_f32_16x16x32_bf16 v[116:119], v[186:189], v[156:159], v[116:119]
	v_mfma_f32_16x16x32_bf16 v[120:123], v[190:193], v[156:159], v[120:123]
	v_mfma_f32_16x16x32_bf16 v[124:127], v[194:197], v[156:159], v[124:127]
	s_add_i32 s8, s8, 1
	s_waitcnt vmcnt(0)
	s_barrier
	s_branch .Lp3a_k2loop

; DEV u16 f2bf(float f) { return (u16)(pack2(f, f) & 0xffffu); }
; DEV float bf2f(u16 h) { return __uint_as_float(((unsigned)h) << 16); }
; DEV void phase_p3a(const Params& p, int g, char* smem) {
;     ...
;     acc_foreach(acc, m0, n0, [&](int m, int n, float& v) {
;       const float gb = bf2f(GT[(size_t)m * 2048 + 1024 + n]);
;       PHG[(size_t)m * 2560 + 1024 + n] = f2bf(gb * v);
;     });
.Lp3a_fin0:
	v_and_b32_e32 v222, 15, v148
	v_lshrrev_b32_e32 v223, 2, v149
	v_lshl_add_u32 v222, v223, 7, v222
	v_add_u32_e32 v222, s3, v222
	v_lshlrev_b32_e32 v222, 12, v222
	v_lshrrev_b32_e32 v223, 4, v148
	v_lshlrev_b32_e32 v223, 3, v223
	v_add_u32_e32 v222, v222, v223
	v_and_b32_e32 v223, 3, v149
	v_lshl_add_u32 v222, v223, 7, v222
	s_lshl_b32 s100, s2, 1
	s_add_u32 s100, s100, 0x800
	v_add_u32_e32 v198, s100, v222
	global_load_dwordx2 v[128:129], v198, s[12:13]
	global_load_dwordx2 v[130:131], v198, s[12:13] offset:32
	global_load_dwordx2 v[132:133], v198, s[12:13] offset:64
	global_load_dwordx2 v[134:135], v198, s[12:13] offset:96
	v_add_u32_e32 v198, 0x10000, v198
	global_load_dwordx2 v[136:137], v198, s[12:13]
	global_load_dwordx2 v[138:139], v198, s[12:13] offset:32
	global_load_dwordx2 v[140:141], v198, s[12:13] offset:64
	global_load_dwordx2 v[142:143], v198, s[12:13] offset:96
	v_add_u32_e32 v198, 0x10000, v198
	global_load_dwordx2 v[144:145], v198, s[12:13]
	global_load_dwordx2 v[146:147], v198, s[12:13] offset:32
	global_load_dwordx2 v[148:149], v198, s[12:13] offset:64
	global_load_dwordx2 v[150:151], v198, s[12:13] offset:96
	v_add_u32_e32 v198, 0x10000, v198
	global_load_dwordx2 v[152:153], v198, s[12:13]
	global_load_dwordx2 v[154:155], v198, s[12:13] offset:32
	global_load_dwordx2 v[156:157], v198, s[12:13] offset:64
	global_load_dwordx2 v[158:159], v198, s[12:13] offset:96
	v_add_u32_e32 v198, 0x10000, v198
	global_load_dwordx2 v[166:167], v198, s[12:13]
	global_load_dwordx2 v[168:169], v198, s[12:13] offset:32
	global_load_dwordx2 v[170:171], v198, s[12:13] offset:64
	global_load_dwordx2 v[172:173], v198, s[12:13] offset:96
	v_add_u32_e32 v198, 0x10000, v198
	global_load_dwordx2 v[174:175], v198, s[12:13]
	global_load_dwordx2 v[176:177], v198, s[12:13] offset:32
	global_load_dwordx2 v[178:179], v198, s[12:13] offset:64
	global_load_dwordx2 v[180:181], v198, s[12:13] offset:96
	v_add_u32_e32 v198, 0x10000, v198
	global_load_dwordx2 v[182:183], v198, s[12:13]
	global_load_dwordx2 v[184:185], v198, s[12:13] offset:32
	global_load_dwordx2 v[186:187], v198, s[12:13] offset:64
	global_load_dwordx2 v[188:189], v198, s[12:13] offset:96
	v_add_u32_e32 v198, 0x10000, v198
	global_load_dwordx2 v[190:191], v198, s[12:13]
	global_load_dwordx2 v[192:193], v198, s[12:13] offset:32
	global_load_dwordx2 v[194:195], v198, s[12:13] offset:64
	global_load_dwordx2 v[196:197], v198, s[12:13] offset:96
	v_add_u32_e32 v198, 0x10000, v198
	s_nop 7
	s_nop 7
	s_nop 3
	s_waitcnt vmcnt(31)
	v_lshlrev_b32_e32 v222, 16, v128
	v_and_b32_e32 v223, 0xffff0000, v128
	v_lshlrev_b32_e32 v224, 16, v129
	v_and_b32_e32 v225, 0xffff0000, v129
	v_mul_f32_e32 v0, v222, v0
	v_mul_f32_e32 v1, v223, v1
	v_mul_f32_e32 v2, v224, v2
	v_mul_f32_e32 v3, v225, v3
	s_waitcnt vmcnt(30)
	v_lshlrev_b32_e32 v222, 16, v130
	v_and_b32_e32 v223, 0xffff0000, v130
	v_lshlrev_b32_e32 v224, 16, v131
	v_and_b32_e32 v225, 0xffff0000, v131
	v_mul_f32_e32 v4, v222, v4
	v_mul_f32_e32 v5, v223, v5
	v_mul_f32_e32 v6, v224, v6
	v_mul_f32_e32 v7, v225, v7
	s_waitcnt vmcnt(29)
	v_lshlrev_b32_e32 v222, 16, v132
	v_and_b32_e32 v223, 0xffff0000, v132
	v_lshlrev_b32_e32 v224, 16, v133
	v_and_b32_e32 v225, 0xffff0000, v133
	v_mul_f32_e32 v8, v222, v8
	v_mul_f32_e32 v9, v223, v9
	v_mul_f32_e32 v10, v224, v10
	v_mul_f32_e32 v11, v225, v11
	s_waitcnt vmcnt(28)
	v_lshlrev_b32_e32 v222, 16, v134
	v_and_b32_e32 v223, 0xffff0000, v134
	v_lshlrev_b32_e32 v224, 16, v135
	v_and_b32_e32 v225, 0xffff0000, v135
	v_mul_f32_e32 v12, v222, v12
	v_mul_f32_e32 v13, v223, v13
	v_mul_f32_e32 v14, v224, v14
	v_mul_f32_e32 v15, v225, v15
	s_waitcnt vmcnt(27)
	v_lshlrev_b32_e32 v222, 16, v136
	v_and_b32_e32 v223, 0xffff0000, v136
	v_lshlrev_b32_e32 v224, 16, v137
	v_and_b32_e32 v225, 0xffff0000, v137
	v_mul_f32_e32 v16, v222, v16
	v_mul_f32_e32 v17, v223, v17
	v_mul_f32_e32 v18, v224, v18
	v_mul_f32_e32 v19, v225, v19
	s_waitcnt vmcnt(26)
	v_lshlrev_b32_e32 v222, 16, v138
	v_and_b32_e32 v223, 0xffff0000, v138
	v_lshlrev_b32_e32 v224, 16, v139
	v_and_b32_e32 v225, 0xffff0000, v139
	v_mul_f32_e32 v20, v222, v20
	v_mul_f32_e32 v21, v223, v21
	v_mul_f32_e32 v22, v224, v22
	v_mul_f32_e32 v23, v225, v23
	s_waitcnt vmcnt(25)
	v_lshlrev_b32_e32 v222, 16, v140
	v_and_b32_e32 v223, 0xffff0000, v140
	v_lshlrev_b32_e32 v224, 16, v141
	v_and_b32_e32 v225, 0xffff0000, v141
	v_mul_f32_e32 v24, v222, v24
	v_mul_f32_e32 v25, v223, v25
	v_mul_f32_e32 v26, v224, v26
	v_mul_f32_e32 v27, v225, v27
	s_waitcnt vmcnt(24)
	v_lshlrev_b32_e32 v222, 16, v142
	v_and_b32_e32 v223, 0xffff0000, v142
	v_lshlrev_b32_e32 v224, 16, v143
	v_and_b32_e32 v225, 0xffff0000, v143
	v_mul_f32_e32 v28, v222, v28
	v_mul_f32_e32 v29, v223, v29
	v_mul_f32_e32 v30, v224, v30
	v_mul_f32_e32 v31, v225, v31
	s_waitcnt vmcnt(23)
	v_lshlrev_b32_e32 v222, 16, v144
	v_and_b32_e32 v223, 0xffff0000, v144
	v_lshlrev_b32_e32 v224, 16, v145
	v_and_b32_e32 v225, 0xffff0000, v145
	v_mul_f32_e32 v32, v222, v32
	v_mul_f32_e32 v33, v223, v33
	v_mul_f32_e32 v34, v224, v34
	v_mul_f32_e32 v35, v225, v35
	s_waitcnt vmcnt(22)
	v_lshlrev_b32_e32 v222, 16, v146
	v_and_b32_e32 v223, 0xffff0000, v146
	v_lshlrev_b32_e32 v224, 16, v147
	v_and_b32_e32 v225, 0xffff0000, v147
	v_mul_f32_e32 v36, v222, v36
	v_mul_f32_e32 v37, v223, v37
	v_mul_f32_e32 v38, v224, v38
	v_mul_f32_e32 v39, v225, v39
	s_waitcnt vmcnt(21)
	v_lshlrev_b32_e32 v222, 16, v148
	v_and_b32_e32 v223, 0xffff0000, v148
	v_lshlrev_b32_e32 v224, 16, v149
	v_and_b32_e32 v225, 0xffff0000, v149
	v_mul_f32_e32 v40, v222, v40
	v_mul_f32_e32 v41, v223, v41
	v_mul_f32_e32 v42, v224, v42
	v_mul_f32_e32 v43, v225, v43
	s_waitcnt vmcnt(20)
; DEV u16 f2bf(float f) { return (u16)(pack2(f, f) & 0xffffu); }
; DEV float bf2f(u16 h) { return __uint_as_float(((unsigned)h) << 16); }
; DEV void phase_p3a(const Params& p, int g, char* smem) {
;     ...
;     acc_foreach(acc, m0, n0, [&](int m, int n, float& v) {
;       const float gb = bf2f(GT[(size_t)m * 2048 + 1024 + n]);
;       PHG[(size_t)m * 2560 + 1024 + n] = f2bf(gb * v);
;     });
	v_lshlrev_b32_e32 v222, 16, v150
	v_and_b32_e32 v223, 0xffff0000, v150
	v_lshlrev_b32_e32 v224, 16, v151
	v_and_b32_e32 v225, 0xffff0000, v151
	v_mul_f32_e32 v44, v222, v44
	v_mul_f32_e32 v45, v223, v45
	v_mul_f32_e32 v46, v224, v46
	v_mul_f32_e32 v47, v225, v47
	s_waitcnt vmcnt(19)
	v_lshlrev_b32_e32 v222, 16, v152
	v_and_b32_e32 v223, 0xffff0000, v152
	v_lshlrev_b32_e32 v224, 16, v153
	v_and_b32_e32 v225, 0xffff0000, v153
	v_mul_f32_e32 v48, v222, v48
	v_mul_f32_e32 v49, v223, v49
	v_mul_f32_e32 v50, v224, v50
	v_mul_f32_e32 v51, v225, v51
	s_waitcnt vmcnt(18)
	v_lshlrev_b32_e32 v222, 16, v154
	v_and_b32_e32 v223, 0xffff0000, v154
	v_lshlrev_b32_e32 v224, 16, v155
	v_and_b32_e32 v225, 0xffff0000, v155
	v_mul_f32_e32 v52, v222, v52
	v_mul_f32_e32 v53, v223, v53
	v_mul_f32_e32 v54, v224, v54
	v_mul_f32_e32 v55, v225, v55
	s_waitcnt vmcnt(17)
	v_lshlrev_b32_e32 v222, 16, v156
	v_and_b32_e32 v223, 0xffff0000, v156
	v_lshlrev_b32_e32 v224, 16, v157
	v_and_b32_e32 v225, 0xffff0000, v157
	v_mul_f32_e32 v56, v222, v56
	v_mul_f32_e32 v57, v223, v57
	v_mul_f32_e32 v58, v224, v58
	v_mul_f32_e32 v59, v225, v59
	s_waitcnt vmcnt(16)
	v_lshlrev_b32_e32 v222, 16, v158
	v_and_b32_e32 v223, 0xffff0000, v158
	v_lshlrev_b32_e32 v224, 16, v159
	v_and_b32_e32 v225, 0xffff0000, v159
	v_mul_f32_e32 v60, v222, v60
	v_mul_f32_e32 v61, v223, v61
	v_mul_f32_e32 v62, v224, v62
	v_mul_f32_e32 v63, v225, v63
	s_waitcnt vmcnt(15)
	v_lshlrev_b32_e32 v222, 16, v166
	v_and_b32_e32 v223, 0xffff0000, v166
	v_lshlrev_b32_e32 v224, 16, v167
	v_and_b32_e32 v225, 0xffff0000, v167
	v_mul_f32_e32 v64, v222, v64
	v_mul_f32_e32 v65, v223, v65
	v_mul_f32_e32 v66, v224, v66
	v_mul_f32_e32 v67, v225, v67
	s_waitcnt vmcnt(14)
	v_lshlrev_b32_e32 v222, 16, v168
	v_and_b32_e32 v223, 0xffff0000, v168
	v_lshlrev_b32_e32 v224, 16, v169
	v_and_b32_e32 v225, 0xffff0000, v169
	v_mul_f32_e32 v68, v222, v68
	v_mul_f32_e32 v69, v223, v69
	v_mul_f32_e32 v70, v224, v70
	v_mul_f32_e32 v71, v225, v71
	s_waitcnt vmcnt(13)
	v_lshlrev_b32_e32 v222, 16, v170
	v_and_b32_e32 v223, 0xffff0000, v170
	v_lshlrev_b32_e32 v224, 16, v171
	v_and_b32_e32 v225, 0xffff0000, v171
	v_mul_f32_e32 v72, v222, v72
	v_mul_f32_e32 v73, v223, v73
	v_mul_f32_e32 v74, v224, v74
	v_mul_f32_e32 v75, v225, v75
	s_waitcnt vmcnt(12)
	v_lshlrev_b32_e32 v222, 16, v172
	v_and_b32_e32 v223, 0xffff0000, v172
	v_lshlrev_b32_e32 v224, 16, v173
	v_and_b32_e32 v225, 0xffff0000, v173
	v_mul_f32_e32 v76, v222, v76
	v_mul_f32_e32 v77, v223, v77
	v_mul_f32_e32 v78, v224, v78
	v_mul_f32_e32 v79, v225, v79
	s_waitcnt vmcnt(11)
	v_lshlrev_b32_e32 v222, 16, v174
	v_and_b32_e32 v223, 0xffff0000, v174
	v_lshlrev_b32_e32 v224, 16, v175
	v_and_b32_e32 v225, 0xffff0000, v175
	v_mul_f32_e32 v80, v222, v80
	v_mul_f32_e32 v81, v223, v81
	v_mul_f32_e32 v82, v224, v82
	v_mul_f32_e32 v83, v225, v83
	s_waitcnt vmcnt(10)
	v_lshlrev_b32_e32 v222, 16, v176
	v_and_b32_e32 v223, 0xffff0000, v176
	v_lshlrev_b32_e32 v224, 16, v177
	v_and_b32_e32 v225, 0xffff0000, v177
	v_mul_f32_e32 v84, v222, v84
	v_mul_f32_e32 v85, v223, v85
	v_mul_f32_e32 v86, v224, v86
	v_mul_f32_e32 v87, v225, v87
	s_waitcnt vmcnt(9)
	v_lshlrev_b32_e32 v222, 16, v178
	v_and_b32_e32 v223, 0xffff0000, v178
	v_lshlrev_b32_e32 v224, 16, v179
	v_and_b32_e32 v225, 0xffff0000, v179
	v_mul_f32_e32 v88, v222, v88
	v_mul_f32_e32 v89, v223, v89
	v_mul_f32_e32 v90, v224, v90
	v_mul_f32_e32 v91, v225, v91
	s_waitcnt vmcnt(8)
	v_lshlrev_b32_e32 v222, 16, v180
	v_and_b32_e32 v223, 0xffff0000, v180
	v_lshlrev_b32_e32 v224, 16, v181
	v_and_b32_e32 v225, 0xffff0000, v181
	v_mul_f32_e32 v92, v222, v92
	v_mul_f32_e32 v93, v223, v93
	v_mul_f32_e32 v94, v224, v94
	v_mul_f32_e32 v95, v225, v95
	s_waitcnt vmcnt(7)
	v_lshlrev_b32_e32 v222, 16, v182
	v_and_b32_e32 v223, 0xffff0000, v182
	v_lshlrev_b32_e32 v224, 16, v183
	v_and_b32_e32 v225, 0xffff0000, v183
	v_mul_f32_e32 v96, v222, v96
	v_mul_f32_e32 v97, v223, v97
	v_mul_f32_e32 v98, v224, v98
	v_mul_f32_e32 v99, v225, v99
	s_waitcnt vmcnt(6)
	v_lshlrev_b32_e32 v222, 16, v184
	v_and_b32_e32 v223, 0xffff0000, v184
	v_lshlrev_b32_e32 v224, 16, v185
	v_and_b32_e32 v225, 0xffff0000, v185
	v_mul_f32_e32 v100, v222, v100
	v_mul_f32_e32 v101, v223, v101
	v_mul_f32_e32 v102, v224, v102
	v_mul_f32_e32 v103, v225, v103
	s_waitcnt vmcnt(5)
	v_lshlrev_b32_e32 v222, 16, v186
	v_and_b32_e32 v223, 0xffff0000, v186
	v_lshlrev_b32_e32 v224, 16, v187
	v_and_b32_e32 v225, 0xffff0000, v187
	v_mul_f32_e32 v104, v222, v104
	v_mul_f32_e32 v105, v223, v105
	v_mul_f32_e32 v106, v224, v106
	v_mul_f32_e32 v107, v225, v107
	s_waitcnt vmcnt(4)
	v_lshlrev_b32_e32 v222, 16, v188
	v_and_b32_e32 v223, 0xffff0000, v188
	v_lshlrev_b32_e32 v224, 16, v189
	v_and_b32_e32 v225, 0xffff0000, v189
	v_mul_f32_e32 v108, v222, v108
	v_mul_f32_e32 v109, v223, v109
	v_mul_f32_e32 v110, v224, v110
	v_mul_f32_e32 v111, v225, v111
	s_waitcnt vmcnt(3)
	v_lshlrev_b32_e32 v222, 16, v190
	v_and_b32_e32 v223, 0xffff0000, v190
	v_lshlrev_b32_e32 v224, 16, v191
	v_and_b32_e32 v225, 0xffff0000, v191
	v_mul_f32_e32 v112, v222, v112
	v_mul_f32_e32 v113, v223, v113
	v_mul_f32_e32 v114, v224, v114
	v_mul_f32_e32 v115, v225, v115
	s_waitcnt vmcnt(2)
	v_lshlrev_b32_e32 v222, 16, v192
	v_and_b32_e32 v223, 0xffff0000, v192
	v_lshlrev_b32_e32 v224, 16, v193
	v_and_b32_e32 v225, 0xffff0000, v193
	v_mul_f32_e32 v116, v222, v116
	v_mul_f32_e32 v117, v223, v117
	v_mul_f32_e32 v118, v224, v118
	v_mul_f32_e32 v119, v225, v119
	s_waitcnt vmcnt(1)
	v_lshlrev_b32_e32 v222, 16, v194
	v_and_b32_e32 v223, 0xffff0000, v194
	v_lshlrev_b32_e32 v224, 16, v195
	v_and_b32_e32 v225, 0xffff0000, v195
	v_mul_f32_e32 v120, v222, v120
	v_mul_f32_e32 v121, v223, v121
	v_mul_f32_e32 v122, v224, v122
	v_mul_f32_e32 v123, v225, v123
	s_waitcnt vmcnt(0)
; DEV u16 f2bf(float f) { return (u16)(pack2(f, f) & 0xffffu); }
; DEV float bf2f(u16 h) { return __uint_as_float(((unsigned)h) << 16); }
; DEV void phase_p3a(const Params& p, int g, char* smem) {
;     ...
;     acc_foreach(acc, m0, n0, [&](int m, int n, float& v) {
;       const float gb = bf2f(GT[(size_t)m * 2048 + 1024 + n]);
;       PHG[(size_t)m * 2560 + 1024 + n] = f2bf(gb * v);
;     });
	v_lshlrev_b32_e32 v222, 16, v196
	v_and_b32_e32 v223, 0xffff0000, v196
	v_lshlrev_b32_e32 v224, 16, v197
	v_and_b32_e32 v225, 0xffff0000, v197
	v_mul_f32_e32 v124, v222, v124
	v_mul_f32_e32 v125, v223, v125
	v_mul_f32_e32 v126, v224, v126
	v_mul_f32_e32 v127, v225, v127
	s_add_u32 s0, s56, 0x800
	s_addc_u32 s1, s57, 0
	s_nop 7
	s_nop 7
	s_nop 3
	v_and_b32_e32 v160, 63, v202
	v_lshrrev_b32_e32 v161, 6, v202
	v_and_b32_e32 v164, 3, v161
	v_lshlrev_b32_e32 v164, 13, v164
	v_add_u32_e32 v164, 0x8000, v164
	v_lshrrev_b32_e32 v160, 2, v161
	v_lshl_add_u32 v164, v160, 16, v164
	v_and_b32_e32 v160, 63, v202
	v_and_b32_e32 v166, 15, v160
	v_lshrrev_b32_e32 v167, 4, v160
	v_lshl_add_u32 v168, v166, 7, v164
	v_and_b32_e32 v169, 1, v167
	v_lshl_add_u32 v168, v169, 3, v168
	v_lshrrev_b32_e32 v167, 1, v167
	v_and_b32_e32 v166, 7, v166
	v_xor_b32_e32 v166, v166, v167
	v_lshlrev_b32_e32 v166, 4, v166
	v_add_u32_e32 v170, v168, v166
	v_xor_b32_e32 v167, 0x20, v166
	v_add_u32_e32 v171, v168, v167
	v_xor_b32_e32 v167, 0x40, v166
	v_add_u32_e32 v172, v168, v167
	v_xor_b32_e32 v167, 0x60, v166
	v_add_u32_e32 v173, v168, v167
	v_and_b32_e32 v166, 31, v160
	v_lshrrev_b32_e32 v167, 5, v160
	v_lshlrev_b32_e32 v168, 7, v166
	v_lshl_add_u32 v168, v167, 3, v168
	v_add_u32_e32 v168, v164, v168
	v_and_b32_e32 v166, 7, v166
	v_lshlrev_b32_e32 v166, 4, v166
	v_lshrrev_b32_e32 v166, 3, v160
	v_and_b32_e32 v167, 7, v160
	v_lshrrev_b32_e32 v169, 2, v161
	v_lshl_add_u32 v169, v169, 7, v166
	v_add_u32_e32 v169, s3, v169
	v_mul_u32_u24_e32 v169, 0x1400, v169
	v_and_b32_e32 v168, 3, v161
	v_lshlrev_b32_e32 v168, 3, v168
	v_add_u32_e32 v168, v168, v167
	v_lshl_add_u32 v169, v168, 4, v169
	s_lshl_b32 s100, s2, 1
	v_add_u32_e32 v169, s100, v169
	v_xor_b32_e32 v167, v166, v167
	v_lshlrev_b32_e32 v167, 4, v167
	v_lshl_add_u32 v168, v166, 7, v167
	v_add_u32_e32 v168, v164, v168
	v_cvt_pk_bf16_f32 v0, v0, v1
	v_cvt_pk_bf16_f32 v1, v2, v3
	ds_write_b64 v170, v[0:1]
	v_cvt_pk_bf16_f32 v4, v4, v5
	v_cvt_pk_bf16_f32 v5, v6, v7
	ds_write_b64 v171, v[4:5]
	v_cvt_pk_bf16_f32 v8, v8, v9
	v_cvt_pk_bf16_f32 v9, v10, v11
	ds_write_b64 v172, v[8:9]
	v_cvt_pk_bf16_f32 v12, v12, v13
	v_cvt_pk_bf16_f32 v13, v14, v15
	ds_write_b64 v173, v[12:13]
	v_cvt_pk_bf16_f32 v16, v16, v17
	v_cvt_pk_bf16_f32 v17, v18, v19
	ds_write_b64 v170, v[16:17] offset:2048
	v_cvt_pk_bf16_f32 v20, v20, v21
	v_cvt_pk_bf16_f32 v21, v22, v23
	ds_write_b64 v171, v[20:21] offset:2048
	v_cvt_pk_bf16_f32 v24, v24, v25
	v_cvt_pk_bf16_f32 v25, v26, v27
	ds_write_b64 v172, v[24:25] offset:2048
	v_cvt_pk_bf16_f32 v28, v28, v29
	v_cvt_pk_bf16_f32 v29, v30, v31
	ds_write_b64 v173, v[28:29] offset:2048
	v_cvt_pk_bf16_f32 v32, v32, v33
	v_cvt_pk_bf16_f32 v33, v34, v35
	ds_write_b64 v170, v[32:33] offset:4096
	v_cvt_pk_bf16_f32 v36, v36, v37
	v_cvt_pk_bf16_f32 v37, v38, v39
	ds_write_b64 v171, v[36:37] offset:4096
	v_cvt_pk_bf16_f32 v40, v40, v41
	v_cvt_pk_bf16_f32 v41, v42, v43
	ds_write_b64 v172, v[40:41] offset:4096
	v_cvt_pk_bf16_f32 v44, v44, v45
	v_cvt_pk_bf16_f32 v45, v46, v47
	ds_write_b64 v173, v[44:45] offset:4096
	v_cvt_pk_bf16_f32 v48, v48, v49
	v_cvt_pk_bf16_f32 v49, v50, v51
	ds_write_b64 v170, v[48:49] offset:6144
	v_cvt_pk_bf16_f32 v52, v52, v53
	v_cvt_pk_bf16_f32 v53, v54, v55
	ds_write_b64 v171, v[52:53] offset:6144
	v_cvt_pk_bf16_f32 v56, v56, v57
	v_cvt_pk_bf16_f32 v57, v58, v59
	ds_write_b64 v172, v[56:57] offset:6144
	v_cvt_pk_bf16_f32 v60, v60, v61
	v_cvt_pk_bf16_f32 v61, v62, v63
	ds_write_b64 v173, v[60:61] offset:6144
	s_waitcnt lgkmcnt(0)
	ds_read_b128 v[32:35], v168
	ds_read_b128 v[36:39], v168 offset:1024
	ds_read_b128 v[40:43], v168 offset:2048
	ds_read_b128 v[44:47], v168 offset:3072
	ds_read_b128 v[48:51], v168 offset:4096
	ds_read_b128 v[52:55], v168 offset:5120
	ds_read_b128 v[56:59], v168 offset:6144
	ds_read_b128 v[60:63], v168 offset:7168
	s_waitcnt lgkmcnt(7)
; DEV u16 f2bf(float f) { return (u16)(pack2(f, f) & 0xffffu); }
; DEV float bf2f(u16 h) { return __uint_as_float(((unsigned)h) << 16); }
; DEV void phase_p3a(const Params& p, int g, char* smem) {
;     ...
;     acc_foreach(acc, m0, n0, [&](int m, int n, float& v) {
;       const float gb = bf2f(GT[(size_t)m * 2048 + 1024 + n]);
;       PHG[(size_t)m * 2560 + 1024 + n] = f2bf(gb * v);
;     });
	global_store_dwordx4 v169, v[32:35], s[0:1]
	v_add_u32_e32 v169, 0xa000, v169
	s_waitcnt lgkmcnt(6)
	global_store_dwordx4 v169, v[36:39], s[0:1]
	v_add_u32_e32 v169, 0xa000, v169
	s_waitcnt lgkmcnt(5)
	global_store_dwordx4 v169, v[40:43], s[0:1]
	v_add_u32_e32 v169, 0xa000, v169
	s_waitcnt lgkmcnt(4)
	global_store_dwordx4 v169, v[44:47], s[0:1]
	v_add_u32_e32 v169, 0xa000, v169
	s_waitcnt lgkmcnt(3)
	global_store_dwordx4 v169, v[48:51], s[0:1]
	v_add_u32_e32 v169, 0xa000, v169
	s_waitcnt lgkmcnt(2)
	global_store_dwordx4 v169, v[52:55], s[0:1]
	v_add_u32_e32 v169, 0xa000, v169
	s_waitcnt lgkmcnt(1)
	global_store_dwordx4 v169, v[56:59], s[0:1]
	v_add_u32_e32 v169, 0xa000, v169
	s_waitcnt lgkmcnt(0)
	global_store_dwordx4 v169, v[60:63], s[0:1]
	v_add_u32_e32 v169, 0xa000, v169
	v_cvt_pk_bf16_f32 v64, v64, v65
	v_cvt_pk_bf16_f32 v65, v66, v67
	ds_write_b64 v170, v[64:65]
	v_cvt_pk_bf16_f32 v68, v68, v69
	v_cvt_pk_bf16_f32 v69, v70, v71
	ds_write_b64 v171, v[68:69]
	v_cvt_pk_bf16_f32 v72, v72, v73
	v_cvt_pk_bf16_f32 v73, v74, v75
	ds_write_b64 v172, v[72:73]
	v_cvt_pk_bf16_f32 v76, v76, v77
	v_cvt_pk_bf16_f32 v77, v78, v79
	ds_write_b64 v173, v[76:77]
	v_cvt_pk_bf16_f32 v80, v80, v81
	v_cvt_pk_bf16_f32 v81, v82, v83
	ds_write_b64 v170, v[80:81] offset:2048
	v_cvt_pk_bf16_f32 v84, v84, v85
	v_cvt_pk_bf16_f32 v85, v86, v87
	ds_write_b64 v171, v[84:85] offset:2048
	v_cvt_pk_bf16_f32 v88, v88, v89
	v_cvt_pk_bf16_f32 v89, v90, v91
	ds_write_b64 v172, v[88:89] offset:2048
	v_cvt_pk_bf16_f32 v92, v92, v93
	v_cvt_pk_bf16_f32 v93, v94, v95
	ds_write_b64 v173, v[92:93] offset:2048
	v_cvt_pk_bf16_f32 v96, v96, v97
	v_cvt_pk_bf16_f32 v97, v98, v99
	ds_write_b64 v170, v[96:97] offset:4096
	v_cvt_pk_bf16_f32 v100, v100, v101
	v_cvt_pk_bf16_f32 v101, v102, v103
	ds_write_b64 v171, v[100:101] offset:4096
	v_cvt_pk_bf16_f32 v104, v104, v105
	v_cvt_pk_bf16_f32 v105, v106, v107
	ds_write_b64 v172, v[104:105] offset:4096
	v_cvt_pk_bf16_f32 v108, v108, v109
	v_cvt_pk_bf16_f32 v109, v110, v111
	ds_write_b64 v173, v[108:109] offset:4096
	v_cvt_pk_bf16_f32 v112, v112, v113
	v_cvt_pk_bf16_f32 v113, v114, v115
	ds_write_b64 v170, v[112:113] offset:6144
	v_cvt_pk_bf16_f32 v116, v116, v117
	v_cvt_pk_bf16_f32 v117, v118, v119
	ds_write_b64 v171, v[116:117] offset:6144
	v_cvt_pk_bf16_f32 v120, v120, v121
	v_cvt_pk_bf16_f32 v121, v122, v123
	ds_write_b64 v172, v[120:121] offset:6144
	v_cvt_pk_bf16_f32 v124, v124, v125
	v_cvt_pk_bf16_f32 v125, v126, v127
	ds_write_b64 v173, v[124:125] offset:6144
	s_waitcnt lgkmcnt(0)
	ds_read_b128 v[64:67], v168
	ds_read_b128 v[68:71], v168 offset:1024
	ds_read_b128 v[72:75], v168 offset:2048
	ds_read_b128 v[76:79], v168 offset:3072
	ds_read_b128 v[80:83], v168 offset:4096
	ds_read_b128 v[84:87], v168 offset:5120
	ds_read_b128 v[88:91], v168 offset:6144
	ds_read_b128 v[92:95], v168 offset:7168
	s_waitcnt lgkmcnt(7)
	global_store_dwordx4 v169, v[64:67], s[0:1]
	v_add_u32_e32 v169, 0xa000, v169
	s_waitcnt lgkmcnt(6)
	global_store_dwordx4 v169, v[68:71], s[0:1]
	v_add_u32_e32 v169, 0xa000, v169
	s_waitcnt lgkmcnt(5)
	global_store_dwordx4 v169, v[72:75], s[0:1]
	v_add_u32_e32 v169, 0xa000, v169
	s_waitcnt lgkmcnt(4)
	global_store_dwordx4 v169, v[76:79], s[0:1]
	v_add_u32_e32 v169, 0xa000, v169
	s_waitcnt lgkmcnt(3)
	global_store_dwordx4 v169, v[80:83], s[0:1]
	v_add_u32_e32 v169, 0xa000, v169
	s_waitcnt lgkmcnt(2)
	global_store_dwordx4 v169, v[84:87], s[0:1]
	v_add_u32_e32 v169, 0xa000, v169
	s_waitcnt lgkmcnt(1)
	global_store_dwordx4 v169, v[88:91], s[0:1]
	v_add_u32_e32 v169, 0xa000, v169
	s_waitcnt lgkmcnt(0)
	s_barrier
	global_store_dwordx4 v169, v[92:95], s[0:1]
	v_add_u32_e32 v169, 0xa000, v169
	s_add_i32 s4, s4, 1
	s_mov_b64 s[2:3], 0
	s_branch .LBB0_927

; template <class AL, class BL>
; DEV void gemm_mainloop(Acc& acc, const AL& al, const BL& bl, int m0, int n0, int kbeg, int kend, char* lds) {
;   const int tid = tidx_full();
;   const int wave = tid >> 6, lane = tid & 63;
;   const int wm = (wave >> 2) * 128, wn = (wave & 3) * 64;
;   const int lr = lane & 31, lh = lane >> 5;
;   const int nk = (kend - kbeg) / BK;
;   R4 a0 = al.load(tid, m0, kbeg);
;   R4 b0 = bl.load(tid, n0, kbeg);
;   __syncthreads();
;   al.store(tid, lds, a0);
;   bl.store(tid, lds + TILE_BYTES, b0);
;   a0 = al.load(tid, m0, kbeg + BK);
;   b0 = bl.load(tid, n0, kbeg + BK);
;   __syncthreads();
; DEV void phase_p3b(const Params& p, int g, char* smem) {
;     ...
;     const int m0 = mt * 256, n0 = nt * 256;
;     Acc acc;
;     acc_zero(acc);
;     RowLoader al{PHG + 1024, 2560}, bl{WoutT, 1024};
;     gemm_mainloop(acc, al, bl, m0, n0, 0, 1024, smem);
.LBB0_1001:
	v_readlane_b32 s2, v251, 23
	v_readlane_b32 s3, v251, 24
	v_readlane_b32 s10, v251, 21
	v_readlane_b32 s11, v251, 22
	s_lshl_b32 s5, s7, 8
	s_lshl_b32 s4, s8, 8
	v_lshrrev_b32_e32 v149, 6, v202
	v_and_b32_e32 v148, 63, v202
	s_nop 0
	v_readfirstlane_b32 s9, v149
	v_lshrrev_b32_e32 v150, 3, v148
	v_lshl_add_u32 v150, v149, 5, v150
	v_and_b32_e32 v151, 7, v148
	v_lshrrev_b32_e32 v128, 4, v148
	v_xor_b32_e32 v151, v128, v151
	v_lshlrev_b32_e32 v151, 4, v151
	s_lshl_b32 s9, s9, 12
	v_add_u32_e32 v128, s5, v150
	v_mul_u32_u24_e32 v128, 0x1400, v128
	v_add_u32_e32 v128, v128, v151
	v_add_u32_e32 v129, 0xa000, v128
	v_add_u32_e32 v130, 0x14000, v128
	v_add_u32_e32 v131, 0x1e000, v128
	v_xor_b32_e32 v129, 0x40, v129
	v_xor_b32_e32 v131, 0x40, v131
	v_add_u32_e32 v136, 0xa0000, v128
	v_add_u32_e32 v137, 0xa0000, v129
	v_add_u32_e32 v138, 0xa0000, v130
	v_add_u32_e32 v139, 0xa0000, v131
	v_add_u32_e32 v132, s4, v150
	v_lshlrev_b32_e32 v132, 11, v132
	v_add_u32_e32 v132, v132, v151
	v_add_u32_e32 v133, 0x4000, v132
	v_add_u32_e32 v134, 0x8000, v132
	v_add_u32_e32 v135, 0xc000, v132
	v_xor_b32_e32 v133, 0x40, v133
	v_xor_b32_e32 v135, 0x40, v135
	v_add_u32_e32 v140, 0x40000, v132
	v_add_u32_e32 v141, 0x40000, v133
	v_add_u32_e32 v142, 0x40000, v134
	v_add_u32_e32 v143, 0x40000, v135
	v_lshrrev_b32_e32 v161, 6, v202
	v_and_b32_e32 v160, 63, v202
	v_bfe_u32 v164, v160, 1, 3
	v_lshrrev_b32_e32 v199, 4, v160
	v_xor_b32_e32 v164, v164, v199
	v_lshlrev_b32_e32 v164, 4, v164
	v_and_b32_e32 v199, 15, v160
	v_lshlrev_b32_e32 v199, 7, v199
	v_lshrrev_b32_e32 v144, 2, v161
	v_lshl_add_u32 v144, v144, 14, v199
	v_and_b32_e32 v146, 3, v161
	v_lshl_add_u32 v146, v146, 13, v199
	v_add_u32_e32 v146, 0x10000, v146
	v_xor_b32_e32 v145, 0x40, v164
	v_add_u32_e32 v145, v144, v145
	v_add_u32_e32 v144, v144, v164
	v_xor_b32_e32 v147, 0x40, v164
	v_add_u32_e32 v147, v146, v147
	v_add_u32_e32 v146, v146, v164
	s_mov_b64 s[12:13], s[2:3]
	s_mov_b64 s[14:15], s[10:11]
	s_waitcnt vmcnt(0)
	s_cmp_lt_u32 s9, 0x4000
	s_cbranch_scc0 .Lp3b_d1
	s_add_u32 m0, s9, 0x0
	s_nop 0
	global_load_lds_dwordx4 v128, s[12:13]
	s_add_u32 m0, m0, 0x400
	s_nop 0
	global_load_lds_dwordx4 v129, s[12:13]
	s_add_u32 m0, m0, 0x400
	s_nop 0
	global_load_lds_dwordx4 v130, s[12:13]
	s_add_u32 m0, m0, 0x400
	s_nop 0
	global_load_lds_dwordx4 v131, s[12:13]
	s_add_u32 m0, s9, 0x10000
	s_nop 0
	global_load_lds_dwordx4 v132, s[14:15]
	s_add_u32 m0, m0, 0x400
	s_nop 0
	global_load_lds_dwordx4 v133, s[14:15]
	s_add_u32 m0, m0, 0x400
	s_nop 0
	global_load_lds_dwordx4 v134, s[14:15]
	s_add_u32 m0, m0, 0x400
	s_nop 0
	global_load_lds_dwordx4 v135, s[14:15]
	s_add_u32 m0, s9, 0x4000
	s_nop 0
	global_load_lds_dwordx4 v136, s[12:13]
	s_add_u32 m0, m0, 0x400
	s_nop 0
	global_load_lds_dwordx4 v137, s[12:13]
	s_add_u32 m0, m0, 0x400
	s_nop 0
	global_load_lds_dwordx4 v138, s[12:13]
	s_add_u32 m0, m0, 0x400
	s_nop 0
	global_load_lds_dwordx4 v139, s[12:13]
	s_add_u32 m0, s9, 0x14000
	s_nop 0
	global_load_lds_dwordx4 v140, s[14:15]
	s_add_u32 m0, m0, 0x400
	s_nop 0
	global_load_lds_dwordx4 v141, s[14:15]
	s_add_u32 m0, m0, 0x400
	s_nop 0
	global_load_lds_dwordx4 v142, s[14:15]
	s_add_u32 m0, m0, 0x400
	s_nop 0
	global_load_lds_dwordx4 v143, s[14:15]
.Lp3b_d1:
	s_add_u32 s12, s12, 0x80
	s_addc_u32 s13, s13, 0
	s_add_u32 s14, s14, 0x80
	s_addc_u32 s15, s15, 0
	v_mov_b32_e32 v0, 0
	v_mov_b32_e32 v1, 0
	v_mov_b64_e32 v[2:3], v[0:1]
	v_mov_b64_e32 v[4:5], v[0:1]
	v_mov_b64_e32 v[6:7], v[0:1]
	v_mov_b64_e32 v[8:9], v[0:1]
	v_mov_b64_e32 v[10:11], v[0:1]
	v_mov_b64_e32 v[12:13], v[0:1]
	v_mov_b64_e32 v[14:15], v[0:1]
	v_mov_b64_e32 v[16:17], v[0:1]
	v_mov_b64_e32 v[18:19], v[0:1]
	v_mov_b64_e32 v[20:21], v[0:1]
	v_mov_b64_e32 v[22:23], v[0:1]
	v_mov_b64_e32 v[24:25], v[0:1]
	v_mov_b64_e32 v[26:27], v[0:1]
	v_mov_b64_e32 v[28:29], v[0:1]
	v_mov_b64_e32 v[30:31], v[0:1]
	v_mov_b64_e32 v[32:33], v[0:1]
	v_mov_b64_e32 v[34:35], v[0:1]
	v_mov_b64_e32 v[36:37], v[0:1]
	v_mov_b64_e32 v[38:39], v[0:1]
	v_mov_b64_e32 v[40:41], v[0:1]
	v_mov_b64_e32 v[42:43], v[0:1]
	v_mov_b64_e32 v[44:45], v[0:1]
	v_mov_b64_e32 v[46:47], v[0:1]
	v_mov_b64_e32 v[48:49], v[0:1]
	v_mov_b64_e32 v[50:51], v[0:1]
	v_mov_b64_e32 v[52:53], v[0:1]
	v_mov_b64_e32 v[54:55], v[0:1]
	v_mov_b64_e32 v[56:57], v[0:1]
	v_mov_b64_e32 v[58:59], v[0:1]
	v_mov_b64_e32 v[60:61], v[0:1]
	v_mov_b64_e32 v[62:63], v[0:1]
	v_mov_b64_e32 v[64:65], v[0:1]
	v_mov_b64_e32 v[66:67], v[0:1]
	v_mov_b64_e32 v[68:69], v[0:1]
	v_mov_b64_e32 v[70:71], v[0:1]
	v_mov_b64_e32 v[72:73], v[0:1]
	v_mov_b64_e32 v[74:75], v[0:1]
	v_mov_b64_e32 v[76:77], v[0:1]
	v_mov_b64_e32 v[78:79], v[0:1]
	v_mov_b64_e32 v[80:81], v[0:1]
	v_mov_b64_e32 v[82:83], v[0:1]
	v_mov_b64_e32 v[84:85], v[0:1]
	v_mov_b64_e32 v[86:87], v[0:1]
	v_mov_b64_e32 v[88:89], v[0:1]
	v_mov_b64_e32 v[90:91], v[0:1]
	v_mov_b64_e32 v[92:93], v[0:1]
	v_mov_b64_e32 v[94:95], v[0:1]
	v_mov_b64_e32 v[96:97], v[0:1]
	v_mov_b64_e32 v[98:99], v[0:1]
	v_mov_b64_e32 v[100:101], v[0:1]
	v_mov_b64_e32 v[102:103], v[0:1]
	v_mov_b64_e32 v[104:105], v[0:1]
	v_mov_b64_e32 v[106:107], v[0:1]
	v_mov_b64_e32 v[108:109], v[0:1]
	v_mov_b64_e32 v[110:111], v[0:1]
	v_mov_b64_e32 v[112:113], v[0:1]
	v_mov_b64_e32 v[114:115], v[0:1]
	v_mov_b64_e32 v[116:117], v[0:1]
	v_mov_b64_e32 v[118:119], v[0:1]
	v_mov_b64_e32 v[120:121], v[0:1]
	v_mov_b64_e32 v[122:123], v[0:1]
	v_mov_b64_e32 v[124:125], v[0:1]
	v_mov_b64_e32 v[126:127], v[0:1]
	s_mov_b32 s7, 0
	s_waitcnt vmcnt(0)
	s_barrier
; template <class AL, class BL>
; DEV void gemm_ktile(Acc& acc, const char* A, const char* B, int wm, int wn, int lr, int lh, const AL& al, const BL& bl,
;                     int tid, int m0, int n0, int knext, char* nxt, R4& ra, R4& rb) {
;     ...
;   for (int ks = 0; ks < 4; ++ks) {
;     const int cur = ks & 1, nx = cur ^ 1;
;     if (ks < 3) {
; #pragma unroll
;       for (int i = 0; i < 4; ++i) a[nx][i] = *(const bf16x8*)(pa + 32 * i * LDSROW + (ks + 1) * 32);
; #pragma unroll
;       for (int j = 0; j < 2; ++j) b[nx][j] = *(const bf16x8*)(pb + 32 * j * LDSROW + (ks + 1) * 32);
;     }
;     __builtin_amdgcn_sched_barrier(0);
; #pragma unroll
;     for (int i = 0; i < 4; ++i)
; #pragma unroll
;       for (int j = 0; j < 2; ++j)
;         acc[i][j] = __builtin_amdgcn_mfma_f32_32x32x16_bf16(a[cur][i], b[cur][j], acc[i][j], 0, 0, 0);
;     __builtin_amdgcn_sched_barrier(0);
; template <class AL, class BL>
; DEV void gemm_mainloop(Acc& acc, const AL& al, const BL& bl, int m0, int n0, int kbeg, int kend, char* lds) {
;     ...
;   for (int kt = 0; kt < nk; ++kt) {
;     const char* cur = lds + (kt & 1) * 2 * TILE_BYTES;
;     char* nxt = lds + ((kt + 1) & 1) * 2 * TILE_BYTES;
;     const int t2 = (kt + 2 < nk) ? kt + 2 : nk - 1;
;     __builtin_amdgcn_sched_barrier(0);
;     gemm_ktile(acc, cur, cur + TILE_BYTES, wm, wn, lr, lh, al, bl, tid, m0, n0, kbeg + t2 * BK, nxt, a0, b0);
;     __builtin_amdgcn_sched_barrier(0);
;     __syncthreads();
;   }
.Lp3b_kloop:
	s_cmp_lt_u32 s9, 0x4000
	s_cbranch_scc0 .Lp3b_d2
	s_add_u32 m0, s9, 0x8000
	s_nop 0
	global_load_lds_dwordx4 v128, s[12:13]
	s_add_u32 m0, m0, 0x400
	s_nop 0
	global_load_lds_dwordx4 v129, s[12:13]
	s_add_u32 m0, m0, 0x400
	s_nop 0
	global_load_lds_dwordx4 v130, s[12:13]
	s_add_u32 m0, m0, 0x400
	s_nop 0
	global_load_lds_dwordx4 v131, s[12:13]
	s_add_u32 m0, s9, 0x18000
	s_nop 0
	global_load_lds_dwordx4 v132, s[14:15]
	s_add_u32 m0, m0, 0x400
	s_nop 0
	global_load_lds_dwordx4 v133, s[14:15]
	s_add_u32 m0, m0, 0x400
	s_nop 0
	global_load_lds_dwordx4 v134, s[14:15]
	s_add_u32 m0, m0, 0x400
	s_nop 0
	global_load_lds_dwordx4 v135, s[14:15]
	s_add_u32 m0, s9, 0xc000
	s_nop 0
	global_load_lds_dwordx4 v136, s[12:13]
	s_add_u32 m0, m0, 0x400
	s_nop 0
	global_load_lds_dwordx4 v137, s[12:13]
	s_add_u32 m0, m0, 0x400
	s_nop 0
	global_load_lds_dwordx4 v138, s[12:13]
	s_add_u32 m0, m0, 0x400
	s_nop 0
	global_load_lds_dwordx4 v139, s[12:13]
	s_add_u32 m0, s9, 0x1c000
	s_nop 0
	global_load_lds_dwordx4 v140, s[14:15]
	s_add_u32 m0, m0, 0x400
	s_nop 0
	global_load_lds_dwordx4 v141, s[14:15]
	s_add_u32 m0, m0, 0x400
	s_nop 0
	global_load_lds_dwordx4 v142, s[14:15]
	s_add_u32 m0, m0, 0x400
	s_nop 0
	global_load_lds_dwordx4 v143, s[14:15]
.Lp3b_d2:
	s_add_u32 s12, s12, 0x80
	s_addc_u32 s13, s13, 0
	s_add_u32 s14, s14, 0x80
	s_addc_u32 s15, s15, 0
	ds_read_b128 v[166:169], v146
	ds_read_b128 v[170:173], v146 offset:2048
	ds_read_b128 v[174:177], v146 offset:4096
	ds_read_b128 v[178:181], v146 offset:6144
	ds_read_b128 v[222:225], v144
	ds_read_b128 v[226:229], v144 offset:2048
	ds_read_b128 v[230:233], v144 offset:4096
	ds_read_b128 v[234:237], v144 offset:6144
	ds_read_b128 v[238:241], v144 offset:8192
	ds_read_b128 v[198:201], v144 offset:10240
	ds_read_b128 v[152:155], v144 offset:12288
	ds_read_b128 v[156:159], v144 offset:14336
	ds_read_b128 v[182:185], v147
	ds_read_b128 v[186:189], v147 offset:2048
	ds_read_b128 v[190:193], v147 offset:4096
	ds_read_b128 v[194:197], v147 offset:6144
	s_waitcnt lgkmcnt(8)
	v_mfma_f32_16x16x32_bf16 v[0:3], v[166:169], v[222:225], v[0:3]
	v_mfma_f32_16x16x32_bf16 v[4:7], v[170:173], v[222:225], v[4:7]
	v_mfma_f32_16x16x32_bf16 v[8:11], v[174:177], v[222:225], v[8:11]
	v_mfma_f32_16x16x32_bf16 v[12:15], v[178:181], v[222:225], v[12:15]
	v_mfma_f32_16x16x32_bf16 v[16:19], v[166:169], v[226:229], v[16:19]
	v_mfma_f32_16x16x32_bf16 v[20:23], v[170:173], v[226:229], v[20:23]
	v_mfma_f32_16x16x32_bf16 v[24:27], v[174:177], v[226:229], v[24:27]
	v_mfma_f32_16x16x32_bf16 v[28:31], v[178:181], v[226:229], v[28:31]
	v_mfma_f32_16x16x32_bf16 v[32:35], v[166:169], v[230:233], v[32:35]
	v_mfma_f32_16x16x32_bf16 v[36:39], v[170:173], v[230:233], v[36:39]
	v_mfma_f32_16x16x32_bf16 v[40:43], v[174:177], v[230:233], v[40:43]
	v_mfma_f32_16x16x32_bf16 v[44:47], v[178:181], v[230:233], v[44:47]
	v_mfma_f32_16x16x32_bf16 v[48:51], v[166:169], v[234:237], v[48:51]
	v_mfma_f32_16x16x32_bf16 v[52:55], v[170:173], v[234:237], v[52:55]
	v_mfma_f32_16x16x32_bf16 v[56:59], v[174:177], v[234:237], v[56:59]
	v_mfma_f32_16x16x32_bf16 v[60:63], v[178:181], v[234:237], v[60:63]
	ds_read_b128 v[222:225], v145
	ds_read_b128 v[226:229], v145 offset:2048
	ds_read_b128 v[230:233], v145 offset:4096
	ds_read_b128 v[234:237], v145 offset:6144
	s_waitcnt lgkmcnt(8)
	v_mfma_f32_16x16x32_bf16 v[64:67], v[166:169], v[238:241], v[64:67]
	v_mfma_f32_16x16x32_bf16 v[68:71], v[170:173], v[238:241], v[68:71]
	v_mfma_f32_16x16x32_bf16 v[72:75], v[174:177], v[238:241], v[72:75]
	v_mfma_f32_16x16x32_bf16 v[76:79], v[178:181], v[238:241], v[76:79]
	v_mfma_f32_16x16x32_bf16 v[80:83], v[166:169], v[198:201], v[80:83]
	v_mfma_f32_16x16x32_bf16 v[84:87], v[170:173], v[198:201], v[84:87]
	v_mfma_f32_16x16x32_bf16 v[88:91], v[174:177], v[198:201], v[88:91]
	v_mfma_f32_16x16x32_bf16 v[92:95], v[178:181], v[198:201], v[92:95]
	v_mfma_f32_16x16x32_bf16 v[96:99], v[166:169], v[152:155], v[96:99]
	v_mfma_f32_16x16x32_bf16 v[100:103], v[170:173], v[152:155], v[100:103]
	v_mfma_f32_16x16x32_bf16 v[104:107], v[174:177], v[152:155], v[104:107]
	v_mfma_f32_16x16x32_bf16 v[108:111], v[178:181], v[152:155], v[108:111]
	v_mfma_f32_16x16x32_bf16 v[112:115], v[166:169], v[156:159], v[112:115]
	v_mfma_f32_16x16x32_bf16 v[116:119], v[170:173], v[156:159], v[116:119]
	v_mfma_f32_16x16x32_bf16 v[120:123], v[174:177], v[156:159], v[120:123]
	v_mfma_f32_16x16x32_bf16 v[124:127], v[178:181], v[156:159], v[124:127]
	ds_read_b128 v[238:241], v145 offset:8192
	ds_read_b128 v[198:201], v145 offset:10240
	ds_read_b128 v[152:155], v145 offset:12288
	ds_read_b128 v[156:159], v145 offset:14336
	s_waitcnt lgkmcnt(4)
	v_mfma_f32_16x16x32_bf16 v[0:3], v[182:185], v[222:225], v[0:3]
	v_mfma_f32_16x16x32_bf16 v[4:7], v[186:189], v[222:225], v[4:7]
	v_mfma_f32_16x16x32_bf16 v[8:11], v[190:193], v[222:225], v[8:11]
	v_mfma_f32_16x16x32_bf16 v[12:15], v[194:197], v[222:225], v[12:15]
	v_mfma_f32_16x16x32_bf16 v[16:19], v[182:185], v[226:229], v[16:19]
	v_mfma_f32_16x16x32_bf16 v[20:23], v[186:189], v[226:229], v[20:23]
	v_mfma_f32_16x16x32_bf16 v[24:27], v[190:193], v[226:229], v[24:27]
	v_mfma_f32_16x16x32_bf16 v[28:31], v[194:197], v[226:229], v[28:31]
	v_mfma_f32_16x16x32_bf16 v[32:35], v[182:185], v[230:233], v[32:35]
	v_mfma_f32_16x16x32_bf16 v[36:39], v[186:189], v[230:233], v[36:39]
	v_mfma_f32_16x16x32_bf16 v[40:43], v[190:193], v[230:233], v[40:43]
	v_mfma_f32_16x16x32_bf16 v[44:47], v[194:197], v[230:233], v[44:47]
	v_mfma_f32_16x16x32_bf16 v[48:51], v[182:185], v[234:237], v[48:51]
	v_mfma_f32_16x16x32_bf16 v[52:55], v[186:189], v[234:237], v[52:55]
	v_mfma_f32_16x16x32_bf16 v[56:59], v[190:193], v[234:237], v[56:59]
	v_mfma_f32_16x16x32_bf16 v[60:63], v[194:197], v[234:237], v[60:63]
	s_waitcnt lgkmcnt(0)
	v_mfma_f32_16x16x32_bf16 v[64:67], v[182:185], v[238:241], v[64:67]
	v_mfma_f32_16x16x32_bf16 v[68:71], v[186:189], v[238:241], v[68:71]
	v_mfma_f32_16x16x32_bf16 v[72:75], v[190:193], v[238:241], v[72:75]
	v_mfma_f32_16x16x32_bf16 v[76:79], v[194:197], v[238:241], v[76:79]
	v_mfma_f32_16x16x32_bf16 v[80:83], v[182:185], v[198:201], v[80:83]
	v_mfma_f32_16x16x32_bf16 v[84:87], v[186:189], v[198:201], v[84:87]
	v_mfma_f32_16x16x32_bf16 v[88:91], v[190:193], v[198:201], v[88:91]
	v_mfma_f32_16x16x32_bf16 v[92:95], v[194:197], v[198:201], v[92:95]
	v_mfma_f32_16x16x32_bf16 v[96:99], v[182:185], v[152:155], v[96:99]
	v_mfma_f32_16x16x32_bf16 v[100:103], v[186:189], v[152:155], v[100:103]
	v_mfma_f32_16x16x32_bf16 v[104:107], v[190:193], v[152:155], v[104:107]
	v_mfma_f32_16x16x32_bf16 v[108:111], v[194:197], v[152:155], v[108:111]
	v_mfma_f32_16x16x32_bf16 v[112:115], v[182:185], v[156:159], v[112:115]
	v_mfma_f32_16x16x32_bf16 v[116:119], v[186:189], v[156:159], v[116:119]
	v_mfma_f32_16x16x32_bf16 v[120:123], v[190:193], v[156:159], v[120:123]
	v_mfma_f32_16x16x32_bf16 v[124:127], v[194:197], v[156:159], v[124:127]
	s_waitcnt vmcnt(0)
	s_barrier
; template <class AL, class BL>
; DEV void gemm_ktile(Acc& acc, const char* A, const char* B, int wm, int wn, int lr, int lh, const AL& al, const BL& bl,
;                     int tid, int m0, int n0, int knext, char* nxt, R4& ra, R4& rb) {
;     ...
;   for (int ks = 0; ks < 4; ++ks) {
;     const int cur = ks & 1, nx = cur ^ 1;
;     if (ks < 3) {
; #pragma unroll
;       for (int i = 0; i < 4; ++i) a[nx][i] = *(const bf16x8*)(pa + 32 * i * LDSROW + (ks + 1) * 32);
; #pragma unroll
;       for (int j = 0; j < 2; ++j) b[nx][j] = *(const bf16x8*)(pb + 32 * j * LDSROW + (ks + 1) * 32);
;     }
;     __builtin_amdgcn_sched_barrier(0);
; #pragma unroll
;     for (int i = 0; i < 4; ++i)
; #pragma unroll
;       for (int j = 0; j < 2; ++j)
;         acc[i][j] = __builtin_amdgcn_mfma_f32_32x32x16_bf16(a[cur][i], b[cur][j], acc[i][j], 0, 0, 0);
;     __builtin_amdgcn_sched_barrier(0);
; template <class AL, class BL>
; DEV void gemm_mainloop(Acc& acc, const AL& al, const BL& bl, int m0, int n0, int kbeg, int kend, char* lds) {
;     ...
;   for (int kt = 0; kt < nk; ++kt) {
;     const char* cur = lds + (kt & 1) * 2 * TILE_BYTES;
;     char* nxt = lds + ((kt + 1) & 1) * 2 * TILE_BYTES;
;     const int t2 = (kt + 2 < nk) ? kt + 2 : nk - 1;
;     __builtin_amdgcn_sched_barrier(0);
;     gemm_ktile(acc, cur, cur + TILE_BYTES, wm, wn, lr, lh, al, bl, tid, m0, n0, kbeg + t2 * BK, nxt, a0, b0);
;     __builtin_amdgcn_sched_barrier(0);
;     __syncthreads();
;   }
	s_cmp_eq_u32 s7, 7
	s_cbranch_scc1 .Lp3b_last
	s_cmp_lt_u32 s9, 0x4000
	s_cbranch_scc0 .Lp3b_d3
	s_add_u32 m0, s9, 0x0
	s_nop 0
	global_load_lds_dwordx4 v128, s[12:13]
	s_add_u32 m0, m0, 0x400
	s_nop 0
	global_load_lds_dwordx4 v129, s[12:13]
	s_add_u32 m0, m0, 0x400
	s_nop 0
	global_load_lds_dwordx4 v130, s[12:13]
	s_add_u32 m0, m0, 0x400
	s_nop 0
	global_load_lds_dwordx4 v131, s[12:13]
	s_add_u32 m0, s9, 0x10000
	s_nop 0
	global_load_lds_dwordx4 v132, s[14:15]
	s_add_u32 m0, m0, 0x400
	s_nop 0
	global_load_lds_dwordx4 v133, s[14:15]
	s_add_u32 m0, m0, 0x400
	s_nop 0
	global_load_lds_dwordx4 v134, s[14:15]
	s_add_u32 m0, m0, 0x400
	s_nop 0
	global_load_lds_dwordx4 v135, s[14:15]
	s_add_u32 m0, s9, 0x4000
	s_nop 0
	global_load_lds_dwordx4 v136, s[12:13]
	s_add_u32 m0, m0, 0x400
	s_nop 0
	global_load_lds_dwordx4 v137, s[12:13]
	s_add_u32 m0, m0, 0x400
	s_nop 0
	global_load_lds_dwordx4 v138, s[12:13]
	s_add_u32 m0, m0, 0x400
	s_nop 0
	global_load_lds_dwordx4 v139, s[12:13]
	s_add_u32 m0, s9, 0x14000
	s_nop 0
	global_load_lds_dwordx4 v140, s[14:15]
	s_add_u32 m0, m0, 0x400
	s_nop 0
	global_load_lds_dwordx4 v141, s[14:15]
	s_add_u32 m0, m0, 0x400
	s_nop 0
	global_load_lds_dwordx4 v142, s[14:15]
	s_add_u32 m0, m0, 0x400
	s_nop 0
	global_load_lds_dwordx4 v143, s[14:15]
.Lp3b_d3:
	s_add_u32 s12, s12, 0x80
	s_addc_u32 s13, s13, 0
	s_add_u32 s14, s14, 0x80
	s_addc_u32 s15, s15, 0
	ds_read_b128 v[166:169], v146 offset:32768
	ds_read_b128 v[170:173], v146 offset:34816
	ds_read_b128 v[174:177], v146 offset:36864
	ds_read_b128 v[178:181], v146 offset:38912
	ds_read_b128 v[222:225], v144 offset:32768
	ds_read_b128 v[226:229], v144 offset:34816
	ds_read_b128 v[230:233], v144 offset:36864
	ds_read_b128 v[234:237], v144 offset:38912
	ds_read_b128 v[238:241], v144 offset:40960
	ds_read_b128 v[198:201], v144 offset:43008
	ds_read_b128 v[152:155], v144 offset:45056
	ds_read_b128 v[156:159], v144 offset:47104
	ds_read_b128 v[182:185], v147 offset:32768
	ds_read_b128 v[186:189], v147 offset:34816
	ds_read_b128 v[190:193], v147 offset:36864
	ds_read_b128 v[194:197], v147 offset:38912
	s_waitcnt lgkmcnt(8)
	v_mfma_f32_16x16x32_bf16 v[0:3], v[166:169], v[222:225], v[0:3]
	v_mfma_f32_16x16x32_bf16 v[4:7], v[170:173], v[222:225], v[4:7]
	v_mfma_f32_16x16x32_bf16 v[8:11], v[174:177], v[222:225], v[8:11]
	v_mfma_f32_16x16x32_bf16 v[12:15], v[178:181], v[222:225], v[12:15]
	v_mfma_f32_16x16x32_bf16 v[16:19], v[166:169], v[226:229], v[16:19]
	v_mfma_f32_16x16x32_bf16 v[20:23], v[170:173], v[226:229], v[20:23]
	v_mfma_f32_16x16x32_bf16 v[24:27], v[174:177], v[226:229], v[24:27]
	v_mfma_f32_16x16x32_bf16 v[28:31], v[178:181], v[226:229], v[28:31]
	v_mfma_f32_16x16x32_bf16 v[32:35], v[166:169], v[230:233], v[32:35]
	v_mfma_f32_16x16x32_bf16 v[36:39], v[170:173], v[230:233], v[36:39]
	v_mfma_f32_16x16x32_bf16 v[40:43], v[174:177], v[230:233], v[40:43]
	v_mfma_f32_16x16x32_bf16 v[44:47], v[178:181], v[230:233], v[44:47]
	v_mfma_f32_16x16x32_bf16 v[48:51], v[166:169], v[234:237], v[48:51]
	v_mfma_f32_16x16x32_bf16 v[52:55], v[170:173], v[234:237], v[52:55]
	v_mfma_f32_16x16x32_bf16 v[56:59], v[174:177], v[234:237], v[56:59]
	v_mfma_f32_16x16x32_bf16 v[60:63], v[178:181], v[234:237], v[60:63]
	ds_read_b128 v[222:225], v145 offset:32768
	ds_read_b128 v[226:229], v145 offset:34816
	ds_read_b128 v[230:233], v145 offset:36864
	ds_read_b128 v[234:237], v145 offset:38912
	s_waitcnt lgkmcnt(8)
	v_mfma_f32_16x16x32_bf16 v[64:67], v[166:169], v[238:241], v[64:67]
	v_mfma_f32_16x16x32_bf16 v[68:71], v[170:173], v[238:241], v[68:71]
	v_mfma_f32_16x16x32_bf16 v[72:75], v[174:177], v[238:241], v[72:75]
	v_mfma_f32_16x16x32_bf16 v[76:79], v[178:181], v[238:241], v[76:79]
	v_mfma_f32_16x16x32_bf16 v[80:83], v[166:169], v[198:201], v[80:83]
	v_mfma_f32_16x16x32_bf16 v[84:87], v[170:173], v[198:201], v[84:87]
	v_mfma_f32_16x16x32_bf16 v[88:91], v[174:177], v[198:201], v[88:91]
	v_mfma_f32_16x16x32_bf16 v[92:95], v[178:181], v[198:201], v[92:95]
	v_mfma_f32_16x16x32_bf16 v[96:99], v[166:169], v[152:155], v[96:99]
	v_mfma_f32_16x16x32_bf16 v[100:103], v[170:173], v[152:155], v[100:103]
	v_mfma_f32_16x16x32_bf16 v[104:107], v[174:177], v[152:155], v[104:107]
	v_mfma_f32_16x16x32_bf16 v[108:111], v[178:181], v[152:155], v[108:111]
	v_mfma_f32_16x16x32_bf16 v[112:115], v[166:169], v[156:159], v[112:115]
	v_mfma_f32_16x16x32_bf16 v[116:119], v[170:173], v[156:159], v[116:119]
	v_mfma_f32_16x16x32_bf16 v[120:123], v[174:177], v[156:159], v[120:123]
	v_mfma_f32_16x16x32_bf16 v[124:127], v[178:181], v[156:159], v[124:127]
	ds_read_b128 v[238:241], v145 offset:40960
	ds_read_b128 v[198:201], v145 offset:43008
	ds_read_b128 v[152:155], v145 offset:45056
	ds_read_b128 v[156:159], v145 offset:47104
	s_waitcnt lgkmcnt(4)
	v_mfma_f32_16x16x32_bf16 v[0:3], v[182:185], v[222:225], v[0:3]
	v_mfma_f32_16x16x32_bf16 v[4:7], v[186:189], v[222:225], v[4:7]
	v_mfma_f32_16x16x32_bf16 v[8:11], v[190:193], v[222:225], v[8:11]
	v_mfma_f32_16x16x32_bf16 v[12:15], v[194:197], v[222:225], v[12:15]
	v_mfma_f32_16x16x32_bf16 v[16:19], v[182:185], v[226:229], v[16:19]
	v_mfma_f32_16x16x32_bf16 v[20:23], v[186:189], v[226:229], v[20:23]
	v_mfma_f32_16x16x32_bf16 v[24:27], v[190:193], v[226:229], v[24:27]
	v_mfma_f32_16x16x32_bf16 v[28:31], v[194:197], v[226:229], v[28:31]
	v_mfma_f32_16x16x32_bf16 v[32:35], v[182:185], v[230:233], v[32:35]
	v_mfma_f32_16x16x32_bf16 v[36:39], v[186:189], v[230:233], v[36:39]
	v_mfma_f32_16x16x32_bf16 v[40:43], v[190:193], v[230:233], v[40:43]
	v_mfma_f32_16x16x32_bf16 v[44:47], v[194:197], v[230:233], v[44:47]
	v_mfma_f32_16x16x32_bf16 v[48:51], v[182:185], v[234:237], v[48:51]
	v_mfma_f32_16x16x32_bf16 v[52:55], v[186:189], v[234:237], v[52:55]
	v_mfma_f32_16x16x32_bf16 v[56:59], v[190:193], v[234:237], v[56:59]
	v_mfma_f32_16x16x32_bf16 v[60:63], v[194:197], v[234:237], v[60:63]
	s_waitcnt lgkmcnt(0)
	v_mfma_f32_16x16x32_bf16 v[64:67], v[182:185], v[238:241], v[64:67]
	v_mfma_f32_16x16x32_bf16 v[68:71], v[186:189], v[238:241], v[68:71]
	v_mfma_f32_16x16x32_bf16 v[72:75], v[190:193], v[238:241], v[72:75]
	v_mfma_f32_16x16x32_bf16 v[76:79], v[194:197], v[238:241], v[76:79]
	v_mfma_f32_16x16x32_bf16 v[80:83], v[182:185], v[198:201], v[80:83]
	v_mfma_f32_16x16x32_bf16 v[84:87], v[186:189], v[198:201], v[84:87]
	v_mfma_f32_16x16x32_bf16 v[88:91], v[190:193], v[198:201], v[88:91]
	v_mfma_f32_16x16x32_bf16 v[92:95], v[194:197], v[198:201], v[92:95]
	v_mfma_f32_16x16x32_bf16 v[96:99], v[182:185], v[152:155], v[96:99]
	v_mfma_f32_16x16x32_bf16 v[100:103], v[186:189], v[152:155], v[100:103]
	v_mfma_f32_16x16x32_bf16 v[104:107], v[190:193], v[152:155], v[104:107]
	v_mfma_f32_16x16x32_bf16 v[108:111], v[194:197], v[152:155], v[108:111]
	v_mfma_f32_16x16x32_bf16 v[112:115], v[182:185], v[156:159], v[112:115]
	v_mfma_f32_16x16x32_bf16 v[116:119], v[186:189], v[156:159], v[116:119]
	v_mfma_f32_16x16x32_bf16 v[120:123], v[190:193], v[156:159], v[120:123]
	v_mfma_f32_16x16x32_bf16 v[124:127], v[194:197], v[156:159], v[124:127]
	s_add_i32 s7, s7, 1
	s_waitcnt vmcnt(0)
	s_barrier
; template <class AL, class BL>
; DEV void gemm_ktile(Acc& acc, const char* A, const char* B, int wm, int wn, int lr, int lh, const AL& al, const BL& bl,
;                     int tid, int m0, int n0, int knext, char* nxt, R4& ra, R4& rb) {
;     ...
;   for (int ks = 0; ks < 4; ++ks) {
;     const int cur = ks & 1, nx = cur ^ 1;
;     if (ks < 3) {
; #pragma unroll
;       for (int i = 0; i < 4; ++i) a[nx][i] = *(const bf16x8*)(pa + 32 * i * LDSROW + (ks + 1) * 32);
; #pragma unroll
;       for (int j = 0; j < 2; ++j) b[nx][j] = *(const bf16x8*)(pb + 32 * j * LDSROW + (ks + 1) * 32);
;     }
;     __builtin_amdgcn_sched_barrier(0);
; #pragma unroll
;     for (int i = 0; i < 4; ++i)
; #pragma unroll
;       for (int j = 0; j < 2; ++j)
;         acc[i][j] = __builtin_amdgcn_mfma_f32_32x32x16_bf16(a[cur][i], b[cur][j], acc[i][j], 0, 0, 0);
;     __builtin_amdgcn_sched_barrier(0);
; template <class AL, class BL>
; DEV void gemm_mainloop(Acc& acc, const AL& al, const BL& bl, int m0, int n0, int kbeg, int kend, char* lds) {
;     ...
;   for (int kt = 0; kt < nk; ++kt) {
;     const char* cur = lds + (kt & 1) * 2 * TILE_BYTES;
;     char* nxt = lds + ((kt + 1) & 1) * 2 * TILE_BYTES;
;     const int t2 = (kt + 2 < nk) ? kt + 2 : nk - 1;
;     __builtin_amdgcn_sched_barrier(0);
;     gemm_ktile(acc, cur, cur + TILE_BYTES, wm, wn, lr, lh, al, bl, tid, m0, n0, kbeg + t2 * BK, nxt, a0, b0);
;     __builtin_amdgcn_sched_barrier(0);
;     __syncthreads();
;   }
	s_branch .Lp3b_kloop
.Lp3b_last:
	ds_read_b128 v[166:169], v146 offset:32768
	ds_read_b128 v[170:173], v146 offset:34816
	ds_read_b128 v[174:177], v146 offset:36864
	ds_read_b128 v[178:181], v146 offset:38912
	ds_read_b128 v[222:225], v144 offset:32768
	ds_read_b128 v[226:229], v144 offset:34816
	ds_read_b128 v[230:233], v144 offset:36864
	ds_read_b128 v[234:237], v144 offset:38912
	ds_read_b128 v[238:241], v144 offset:40960
	ds_read_b128 v[198:201], v144 offset:43008
	ds_read_b128 v[152:155], v144 offset:45056
	ds_read_b128 v[156:159], v144 offset:47104
	ds_read_b128 v[182:185], v147 offset:32768
	ds_read_b128 v[186:189], v147 offset:34816
	ds_read_b128 v[190:193], v147 offset:36864
	ds_read_b128 v[194:197], v147 offset:38912
	s_waitcnt lgkmcnt(8)
	v_mfma_f32_16x16x32_bf16 v[0:3], v[166:169], v[222:225], v[0:3]
	v_mfma_f32_16x16x32_bf16 v[4:7], v[170:173], v[222:225], v[4:7]
	v_mfma_f32_16x16x32_bf16 v[8:11], v[174:177], v[222:225], v[8:11]
	v_mfma_f32_16x16x32_bf16 v[12:15], v[178:181], v[222:225], v[12:15]
	v_mfma_f32_16x16x32_bf16 v[16:19], v[166:169], v[226:229], v[16:19]
	v_mfma_f32_16x16x32_bf16 v[20:23], v[170:173], v[226:229], v[20:23]
	v_mfma_f32_16x16x32_bf16 v[24:27], v[174:177], v[226:229], v[24:27]
	v_mfma_f32_16x16x32_bf16 v[28:31], v[178:181], v[226:229], v[28:31]
	v_mfma_f32_16x16x32_bf16 v[32:35], v[166:169], v[230:233], v[32:35]
	v_mfma_f32_16x16x32_bf16 v[36:39], v[170:173], v[230:233], v[36:39]
	v_mfma_f32_16x16x32_bf16 v[40:43], v[174:177], v[230:233], v[40:43]
	v_mfma_f32_16x16x32_bf16 v[44:47], v[178:181], v[230:233], v[44:47]
	v_mfma_f32_16x16x32_bf16 v[48:51], v[166:169], v[234:237], v[48:51]
	v_mfma_f32_16x16x32_bf16 v[52:55], v[170:173], v[234:237], v[52:55]
	v_mfma_f32_16x16x32_bf16 v[56:59], v[174:177], v[234:237], v[56:59]
	v_mfma_f32_16x16x32_bf16 v[60:63], v[178:181], v[234:237], v[60:63]
	ds_read_b128 v[222:225], v145 offset:32768
	ds_read_b128 v[226:229], v145 offset:34816
	ds_read_b128 v[230:233], v145 offset:36864
	ds_read_b128 v[234:237], v145 offset:38912
	s_waitcnt lgkmcnt(8)
	v_mfma_f32_16x16x32_bf16 v[64:67], v[166:169], v[238:241], v[64:67]
	v_mfma_f32_16x16x32_bf16 v[68:71], v[170:173], v[238:241], v[68:71]
	v_mfma_f32_16x16x32_bf16 v[72:75], v[174:177], v[238:241], v[72:75]
	v_mfma_f32_16x16x32_bf16 v[76:79], v[178:181], v[238:241], v[76:79]
	v_mfma_f32_16x16x32_bf16 v[80:83], v[166:169], v[198:201], v[80:83]
	v_mfma_f32_16x16x32_bf16 v[84:87], v[170:173], v[198:201], v[84:87]
	v_mfma_f32_16x16x32_bf16 v[88:91], v[174:177], v[198:201], v[88:91]
	v_mfma_f32_16x16x32_bf16 v[92:95], v[178:181], v[198:201], v[92:95]
	v_mfma_f32_16x16x32_bf16 v[96:99], v[166:169], v[152:155], v[96:99]
	v_mfma_f32_16x16x32_bf16 v[100:103], v[170:173], v[152:155], v[100:103]
	v_mfma_f32_16x16x32_bf16 v[104:107], v[174:177], v[152:155], v[104:107]
	v_mfma_f32_16x16x32_bf16 v[108:111], v[178:181], v[152:155], v[108:111]
	v_mfma_f32_16x16x32_bf16 v[112:115], v[166:169], v[156:159], v[112:115]
	v_mfma_f32_16x16x32_bf16 v[116:119], v[170:173], v[156:159], v[116:119]
	v_mfma_f32_16x16x32_bf16 v[120:123], v[174:177], v[156:159], v[120:123]
	v_mfma_f32_16x16x32_bf16 v[124:127], v[178:181], v[156:159], v[124:127]
	ds_read_b128 v[238:241], v145 offset:40960
	ds_read_b128 v[198:201], v145 offset:43008
	ds_read_b128 v[152:155], v145 offset:45056
	ds_read_b128 v[156:159], v145 offset:47104
	s_waitcnt lgkmcnt(4)
	v_mfma_f32_16x16x32_bf16 v[0:3], v[182:185], v[222:225], v[0:3]
	v_mfma_f32_16x16x32_bf16 v[4:7], v[186:189], v[222:225], v[4:7]
	v_mfma_f32_16x16x32_bf16 v[8:11], v[190:193], v[222:225], v[8:11]
	v_mfma_f32_16x16x32_bf16 v[12:15], v[194:197], v[222:225], v[12:15]
	v_mfma_f32_16x16x32_bf16 v[16:19], v[182:185], v[226:229], v[16:19]
	v_mfma_f32_16x16x32_bf16 v[20:23], v[186:189], v[226:229], v[20:23]
	v_mfma_f32_16x16x32_bf16 v[24:27], v[190:193], v[226:229], v[24:27]
	v_mfma_f32_16x16x32_bf16 v[28:31], v[194:197], v[226:229], v[28:31]
	v_mfma_f32_16x16x32_bf16 v[32:35], v[182:185], v[230:233], v[32:35]
	v_mfma_f32_16x16x32_bf16 v[36:39], v[186:189], v[230:233], v[36:39]
	v_mfma_f32_16x16x32_bf16 v[40:43], v[190:193], v[230:233], v[40:43]
	v_mfma_f32_16x16x32_bf16 v[44:47], v[194:197], v[230:233], v[44:47]
	v_mfma_f32_16x16x32_bf16 v[48:51], v[182:185], v[234:237], v[48:51]
	v_mfma_f32_16x16x32_bf16 v[52:55], v[186:189], v[234:237], v[52:55]
	v_mfma_f32_16x16x32_bf16 v[56:59], v[190:193], v[234:237], v[56:59]
	v_mfma_f32_16x16x32_bf16 v[60:63], v[194:197], v[234:237], v[60:63]
	s_waitcnt lgkmcnt(0)
	v_mfma_f32_16x16x32_bf16 v[64:67], v[182:185], v[238:241], v[64:67]
	v_mfma_f32_16x16x32_bf16 v[68:71], v[186:189], v[238:241], v[68:71]
	v_mfma_f32_16x16x32_bf16 v[72:75], v[190:193], v[238:241], v[72:75]
	v_mfma_f32_16x16x32_bf16 v[76:79], v[194:197], v[238:241], v[76:79]
	v_mfma_f32_16x16x32_bf16 v[80:83], v[182:185], v[198:201], v[80:83]
	v_mfma_f32_16x16x32_bf16 v[84:87], v[186:189], v[198:201], v[84:87]
	v_mfma_f32_16x16x32_bf16 v[88:91], v[190:193], v[198:201], v[88:91]
	v_mfma_f32_16x16x32_bf16 v[92:95], v[194:197], v[198:201], v[92:95]
	v_mfma_f32_16x16x32_bf16 v[96:99], v[182:185], v[152:155], v[96:99]
	v_mfma_f32_16x16x32_bf16 v[100:103], v[186:189], v[152:155], v[100:103]
	v_mfma_f32_16x16x32_bf16 v[104:107], v[190:193], v[152:155], v[104:107]
	v_mfma_f32_16x16x32_bf16 v[108:111], v[194:197], v[152:155], v[108:111]
	v_mfma_f32_16x16x32_bf16 v[112:115], v[182:185], v[156:159], v[112:115]
	v_mfma_f32_16x16x32_bf16 v[116:119], v[186:189], v[156:159], v[116:119]
	v_mfma_f32_16x16x32_bf16 v[120:123], v[190:193], v[156:159], v[120:123]
	v_mfma_f32_16x16x32_bf16 v[124:127], v[194:197], v[156:159], v[124:127]
	s_barrier
; DEV void phase_p3b(const Params& p, int g, char* smem) {
;     ...
;     const float* gt = mod + (size_t)(bg0 + m0 / L) * DIN + 2048;
;     acc_foreach(acc, m0, n0, [&](int m, int n, float& v) {
;       X1[(size_t)m * D + n] = X[(size_t)m * D + n] + gt[n] * v;
;     });
	s_abs_i32 s3, s5
	v_readlane_b32 s7, v252, 17
	s_mul_hi_u32 s7, s3, s7
	v_readlane_b32 s10, v252, 16
	s_mul_i32 s8, s7, s10
	s_sub_i32 s3, s3, s8
	s_ashr_i32 s2, s5, 31
	s_add_i32 s8, s7, 1
	s_sub_i32 s9, s3, s10
	s_cmp_ge_u32 s3, s10
	s_cselect_b32 s7, s8, s7
	s_cselect_b32 s3, s9, s3
	s_add_i32 s8, s7, 1
	s_cmp_ge_u32 s3, s10
	s_cselect_b32 s3, s8, s7
	s_xor_b32 s3, s3, s2
	s_sub_i32 s2, s3, s2
	s_add_i32 s2, s2, s16
	s_mul_hi_i32 s3, s2, 0x6000
	s_mulk_i32 s2, 0x6000
	s_add_u32 s2, s88, s2
	s_addc_u32 s3, s89, s3
	s_add_u32 s2, s2, 0x2002000
	s_addc_u32 s3, s3, 0
	s_waitcnt vmcnt(0)
	s_nop 7
	s_nop 7
	s_nop 3
	v_and_b32_e32 v160, 63, v202
	v_lshrrev_b32_e32 v161, 6, v202
	v_and_b32_e32 v164, 3, v161
	v_lshlrev_b32_e32 v164, 13, v164
	v_add_u32_e32 v164, 0x8000, v164
	v_lshrrev_b32_e32 v160, 2, v161
	v_lshl_add_u32 v164, v160, 16, v164
	v_and_b32_e32 v160, 63, v202
	v_lshrrev_b32_e32 v166, 4, v160
	v_and_b32_e32 v167, 15, v160
	v_lshrrev_b32_e32 v182, 2, v161
	v_lshl_add_u32 v182, v182, 7, v166
	v_add_u32_e32 v182, s5, v182
	v_lshlrev_b32_e32 v182, 12, v182
	v_and_b32_e32 v184, 3, v161
	v_lshl_add_u32 v184, v184, 4, v167
	v_lshlrev_b32_e32 v184, 4, v184
	s_lshl_b32 s100, s4, 2
	v_add_u32_e32 v184, s100, v184
	v_add_u32_e32 v182, v182, v184
	v_mov_b32_e32 v183, v182
	global_load_dwordx4 v[128:131], v182, s[0:1]
	v_add_u32_e32 v182, 0x4000, v182
	global_load_dwordx4 v[132:135], v182, s[0:1]
	v_add_u32_e32 v182, 0x4000, v182
	global_load_dwordx4 v[136:139], v182, s[0:1]
	v_add_u32_e32 v182, 0x4000, v182
	global_load_dwordx4 v[140:143], v182, s[0:1]
	v_add_u32_e32 v182, 0x4000, v182
	global_load_dwordx4 v[144:147], v182, s[0:1]
	v_add_u32_e32 v182, 0x4000, v182
	global_load_dwordx4 v[148:151], v182, s[0:1]
	v_add_u32_e32 v182, 0x4000, v182
	global_load_dwordx4 v[152:155], v182, s[0:1]
	v_add_u32_e32 v182, 0x4000, v182
	global_load_dwordx4 v[156:159], v182, s[0:1]
	v_add_u32_e32 v182, 0x4000, v182
	global_load_dwordx4 v[188:191], v182, s[0:1]
	v_add_u32_e32 v182, 0x4000, v182
	global_load_dwordx4 v[192:195], v182, s[0:1]
	v_add_u32_e32 v182, 0x4000, v182
	global_load_dwordx4 v[196:199], v182, s[0:1]
	v_add_u32_e32 v182, 0x4000, v182
	global_load_dwordx4 v[222:225], v182, s[0:1]
	v_add_u32_e32 v182, 0x4000, v182
	global_load_dwordx4 v[226:229], v182, s[0:1]
	v_add_u32_e32 v182, 0x4000, v182
	global_load_dwordx4 v[230:233], v182, s[0:1]
	v_add_u32_e32 v182, 0x4000, v182
	global_load_dwordx4 v[234:237], v182, s[0:1]
	v_add_u32_e32 v182, 0x4000, v182
	global_load_dwordx4 v[238:241], v182, s[0:1]
	v_add_u32_e32 v182, 0x4000, v182
	global_load_dwordx4 v[168:171], v184, s[2:3]
	v_and_b32_e32 v166, 15, v160
	v_lshrrev_b32_e32 v167, 4, v160
	v_lshl_add_u32 v180, v166, 8, v164
	v_and_b32_e32 v166, 7, v166
	v_xor_b32_e32 v166, v166, v167
	v_lshlrev_b32_e32 v166, 4, v166
	v_add_u32_e32 v172, v180, v166
	v_xor_b32_e32 v167, 0x40, v166
	v_add_u32_e32 v173, v180, v167
	v_xor_b32_e32 v167, 0x80, v166
	v_add_u32_e32 v174, v180, v167
	v_xor_b32_e32 v167, 0xc0, v166
	v_add_u32_e32 v175, v180, v167
	v_lshrrev_b32_e32 v166, 4, v160
	v_and_b32_e32 v167, 15, v160
	v_xor_b32_e32 v167, v166, v167
	v_lshlrev_b32_e32 v167, 4, v167
	v_lshl_add_u32 v180, v166, 8, v164
	v_add_u32_e32 v181, v180, v167
	v_xor_b32_e32 v167, 0x40, v167
	v_add_u32_e32 v166, v180, v167
	v_mov_b32_e32 v180, v181
	v_mov_b32_e32 v181, v166
	ds_write_b128 v172, v[0:3]
	ds_write_b128 v173, v[4:7]
	ds_write_b128 v174, v[8:11]
	ds_write_b128 v175, v[12:15]
	ds_write_b128 v172, v[16:19] offset:4096
	ds_write_b128 v173, v[20:23] offset:4096
	ds_write_b128 v174, v[24:27] offset:4096
	ds_write_b128 v175, v[28:31] offset:4096
	s_waitcnt lgkmcnt(0)
	ds_read_b128 v[0:3], v180
	ds_read_b128 v[4:7], v181 offset:1024
	ds_read_b128 v[8:11], v180 offset:2048
	ds_read_b128 v[12:15], v181 offset:3072
	ds_read_b128 v[16:19], v180 offset:4096
	ds_read_b128 v[20:23], v181 offset:5120
	ds_read_b128 v[24:27], v180 offset:6144
	ds_read_b128 v[28:31], v181 offset:7168
	s_waitcnt vmcnt(0)
	s_waitcnt lgkmcnt(7)
	v_fma_f32 v0, v168, v0, v128
	v_fma_f32 v1, v169, v1, v129
	v_fma_f32 v2, v170, v2, v130
	v_fma_f32 v3, v171, v3, v131
	global_store_dwordx4 v183, v[0:3], s[64:65]
	v_add_u32_e32 v183, 0x4000, v183
	s_waitcnt lgkmcnt(6)
	v_fma_f32 v4, v168, v4, v132
	v_fma_f32 v5, v169, v5, v133
	v_fma_f32 v6, v170, v6, v134
	v_fma_f32 v7, v171, v7, v135
	global_store_dwordx4 v183, v[4:7], s[64:65]
	v_add_u32_e32 v183, 0x4000, v183
	s_waitcnt lgkmcnt(5)
	v_fma_f32 v8, v168, v8, v136
	v_fma_f32 v9, v169, v9, v137
	v_fma_f32 v10, v170, v10, v138
	v_fma_f32 v11, v171, v11, v139
	global_store_dwordx4 v183, v[8:11], s[64:65]
	v_add_u32_e32 v183, 0x4000, v183
	s_waitcnt lgkmcnt(4)
	v_fma_f32 v12, v168, v12, v140
	v_fma_f32 v13, v169, v13, v141
	v_fma_f32 v14, v170, v14, v142
	v_fma_f32 v15, v171, v15, v143
	global_store_dwordx4 v183, v[12:15], s[64:65]
	v_add_u32_e32 v183, 0x4000, v183
	s_waitcnt lgkmcnt(3)
	v_fma_f32 v16, v168, v16, v144
	v_fma_f32 v17, v169, v17, v145
	v_fma_f32 v18, v170, v18, v146
	v_fma_f32 v19, v171, v19, v147
	global_store_dwordx4 v183, v[16:19], s[64:65]
	v_add_u32_e32 v183, 0x4000, v183
	s_waitcnt lgkmcnt(2)
	v_fma_f32 v20, v168, v20, v148
	v_fma_f32 v21, v169, v21, v149
	v_fma_f32 v22, v170, v22, v150
	v_fma_f32 v23, v171, v23, v151
	global_store_dwordx4 v183, v[20:23], s[64:65]
	v_add_u32_e32 v183, 0x4000, v183
	s_waitcnt lgkmcnt(1)
	v_fma_f32 v24, v168, v24, v152
	v_fma_f32 v25, v169, v25, v153
	v_fma_f32 v26, v170, v26, v154
	v_fma_f32 v27, v171, v27, v155
	global_store_dwordx4 v183, v[24:27], s[64:65]
	v_add_u32_e32 v183, 0x4000, v183
	s_waitcnt lgkmcnt(0)
; DEV void phase_p3b(const Params& p, int g, char* smem) {
;     ...
;     const float* gt = mod + (size_t)(bg0 + m0 / L) * DIN + 2048;
;     acc_foreach(acc, m0, n0, [&](int m, int n, float& v) {
;       X1[(size_t)m * D + n] = X[(size_t)m * D + n] + gt[n] * v;
;     });
	v_fma_f32 v28, v168, v28, v156
	v_fma_f32 v29, v169, v29, v157
	v_fma_f32 v30, v170, v30, v158
	v_fma_f32 v31, v171, v31, v159
	global_store_dwordx4 v183, v[28:31], s[64:65]
	v_add_u32_e32 v183, 0x4000, v183
	global_load_dwordx4 v[128:131], v182, s[0:1]
	v_add_u32_e32 v182, 0x4000, v182
	global_load_dwordx4 v[132:135], v182, s[0:1]
	v_add_u32_e32 v182, 0x4000, v182
	global_load_dwordx4 v[136:139], v182, s[0:1]
	v_add_u32_e32 v182, 0x4000, v182
	global_load_dwordx4 v[140:143], v182, s[0:1]
	v_add_u32_e32 v182, 0x4000, v182
	global_load_dwordx4 v[144:147], v182, s[0:1]
	v_add_u32_e32 v182, 0x4000, v182
	global_load_dwordx4 v[148:151], v182, s[0:1]
	v_add_u32_e32 v182, 0x4000, v182
	global_load_dwordx4 v[152:155], v182, s[0:1]
	v_add_u32_e32 v182, 0x4000, v182
	global_load_dwordx4 v[156:159], v182, s[0:1]
	v_add_u32_e32 v182, 0x4000, v182
	ds_write_b128 v172, v[32:35]
	ds_write_b128 v173, v[36:39]
	ds_write_b128 v174, v[40:43]
	ds_write_b128 v175, v[44:47]
	ds_write_b128 v172, v[48:51] offset:4096
	ds_write_b128 v173, v[52:55] offset:4096
	ds_write_b128 v174, v[56:59] offset:4096
	ds_write_b128 v175, v[60:63] offset:4096
	s_waitcnt lgkmcnt(0)
	ds_read_b128 v[32:35], v180
	ds_read_b128 v[36:39], v181 offset:1024
	ds_read_b128 v[40:43], v180 offset:2048
	ds_read_b128 v[44:47], v181 offset:3072
	ds_read_b128 v[48:51], v180 offset:4096
	ds_read_b128 v[52:55], v181 offset:5120
	ds_read_b128 v[56:59], v180 offset:6144
	ds_read_b128 v[60:63], v181 offset:7168
	s_waitcnt lgkmcnt(7)
	v_fma_f32 v32, v168, v32, v188
	v_fma_f32 v33, v169, v33, v189
	v_fma_f32 v34, v170, v34, v190
	v_fma_f32 v35, v171, v35, v191
	global_store_dwordx4 v183, v[32:35], s[64:65]
	v_add_u32_e32 v183, 0x4000, v183
	s_waitcnt lgkmcnt(6)
	v_fma_f32 v36, v168, v36, v192
	v_fma_f32 v37, v169, v37, v193
	v_fma_f32 v38, v170, v38, v194
	v_fma_f32 v39, v171, v39, v195
	global_store_dwordx4 v183, v[36:39], s[64:65]
	v_add_u32_e32 v183, 0x4000, v183
	s_waitcnt lgkmcnt(5)
	v_fma_f32 v40, v168, v40, v196
	v_fma_f32 v41, v169, v41, v197
	v_fma_f32 v42, v170, v42, v198
	v_fma_f32 v43, v171, v43, v199
	global_store_dwordx4 v183, v[40:43], s[64:65]
	v_add_u32_e32 v183, 0x4000, v183
	s_waitcnt lgkmcnt(4)
	v_fma_f32 v44, v168, v44, v222
	v_fma_f32 v45, v169, v45, v223
	v_fma_f32 v46, v170, v46, v224
	v_fma_f32 v47, v171, v47, v225
	global_store_dwordx4 v183, v[44:47], s[64:65]
	v_add_u32_e32 v183, 0x4000, v183
	s_waitcnt lgkmcnt(3)
	v_fma_f32 v48, v168, v48, v226
	v_fma_f32 v49, v169, v49, v227
	v_fma_f32 v50, v170, v50, v228
	v_fma_f32 v51, v171, v51, v229
	global_store_dwordx4 v183, v[48:51], s[64:65]
	v_add_u32_e32 v183, 0x4000, v183
	s_waitcnt lgkmcnt(2)
	v_fma_f32 v52, v168, v52, v230
	v_fma_f32 v53, v169, v53, v231
	v_fma_f32 v54, v170, v54, v232
	v_fma_f32 v55, v171, v55, v233
	global_store_dwordx4 v183, v[52:55], s[64:65]
	v_add_u32_e32 v183, 0x4000, v183
	s_waitcnt lgkmcnt(1)
	v_fma_f32 v56, v168, v56, v234
	v_fma_f32 v57, v169, v57, v235
	v_fma_f32 v58, v170, v58, v236
	v_fma_f32 v59, v171, v59, v237
	global_store_dwordx4 v183, v[56:59], s[64:65]
	v_add_u32_e32 v183, 0x4000, v183
	s_waitcnt lgkmcnt(0)
	v_fma_f32 v60, v168, v60, v238
	v_fma_f32 v61, v169, v61, v239
	v_fma_f32 v62, v170, v62, v240
	v_fma_f32 v63, v171, v63, v241
	global_store_dwordx4 v183, v[60:63], s[64:65]
	v_add_u32_e32 v183, 0x4000, v183
	global_load_dwordx4 v[188:191], v182, s[0:1]
	v_add_u32_e32 v182, 0x4000, v182
	global_load_dwordx4 v[192:195], v182, s[0:1]
	v_add_u32_e32 v182, 0x4000, v182
	global_load_dwordx4 v[196:199], v182, s[0:1]
	v_add_u32_e32 v182, 0x4000, v182
	global_load_dwordx4 v[222:225], v182, s[0:1]
	v_add_u32_e32 v182, 0x4000, v182
	global_load_dwordx4 v[226:229], v182, s[0:1]
	v_add_u32_e32 v182, 0x4000, v182
	global_load_dwordx4 v[230:233], v182, s[0:1]
	v_add_u32_e32 v182, 0x4000, v182
	global_load_dwordx4 v[234:237], v182, s[0:1]
	v_add_u32_e32 v182, 0x4000, v182
	global_load_dwordx4 v[238:241], v182, s[0:1]
	v_add_u32_e32 v182, 0x4000, v182
	ds_write_b128 v172, v[64:67]
	ds_write_b128 v173, v[68:71]
	ds_write_b128 v174, v[72:75]
	ds_write_b128 v175, v[76:79]
	ds_write_b128 v172, v[80:83] offset:4096
	ds_write_b128 v173, v[84:87] offset:4096
	ds_write_b128 v174, v[88:91] offset:4096
	ds_write_b128 v175, v[92:95] offset:4096
	s_waitcnt lgkmcnt(0)
	ds_read_b128 v[64:67], v180
	ds_read_b128 v[68:71], v181 offset:1024
	ds_read_b128 v[72:75], v180 offset:2048
	ds_read_b128 v[76:79], v181 offset:3072
	ds_read_b128 v[80:83], v180 offset:4096
	ds_read_b128 v[84:87], v181 offset:5120
	ds_read_b128 v[88:91], v180 offset:6144
	ds_read_b128 v[92:95], v181 offset:7168
	s_waitcnt vmcnt(16)
; DEV void phase_p3b(const Params& p, int g, char* smem) {
;     ...
;     const float* gt = mod + (size_t)(bg0 + m0 / L) * DIN + 2048;
;     acc_foreach(acc, m0, n0, [&](int m, int n, float& v) {
;       X1[(size_t)m * D + n] = X[(size_t)m * D + n] + gt[n] * v;
;     });
	s_waitcnt lgkmcnt(7)
	v_fma_f32 v64, v168, v64, v128
	v_fma_f32 v65, v169, v65, v129
	v_fma_f32 v66, v170, v66, v130
	v_fma_f32 v67, v171, v67, v131
	global_store_dwordx4 v183, v[64:67], s[64:65]
	v_add_u32_e32 v183, 0x4000, v183
	s_waitcnt lgkmcnt(6)
	v_fma_f32 v68, v168, v68, v132
	v_fma_f32 v69, v169, v69, v133
	v_fma_f32 v70, v170, v70, v134
	v_fma_f32 v71, v171, v71, v135
	global_store_dwordx4 v183, v[68:71], s[64:65]
	v_add_u32_e32 v183, 0x4000, v183
	s_waitcnt lgkmcnt(5)
	v_fma_f32 v72, v168, v72, v136
	v_fma_f32 v73, v169, v73, v137
	v_fma_f32 v74, v170, v74, v138
	v_fma_f32 v75, v171, v75, v139
	global_store_dwordx4 v183, v[72:75], s[64:65]
	v_add_u32_e32 v183, 0x4000, v183
	s_waitcnt lgkmcnt(4)
	v_fma_f32 v76, v168, v76, v140
	v_fma_f32 v77, v169, v77, v141
	v_fma_f32 v78, v170, v78, v142
	v_fma_f32 v79, v171, v79, v143
	global_store_dwordx4 v183, v[76:79], s[64:65]
	v_add_u32_e32 v183, 0x4000, v183
	s_waitcnt lgkmcnt(3)
	v_fma_f32 v80, v168, v80, v144
	v_fma_f32 v81, v169, v81, v145
	v_fma_f32 v82, v170, v82, v146
	v_fma_f32 v83, v171, v83, v147
	global_store_dwordx4 v183, v[80:83], s[64:65]
	v_add_u32_e32 v183, 0x4000, v183
	s_waitcnt lgkmcnt(2)
	v_fma_f32 v84, v168, v84, v148
	v_fma_f32 v85, v169, v85, v149
	v_fma_f32 v86, v170, v86, v150
	v_fma_f32 v87, v171, v87, v151
	global_store_dwordx4 v183, v[84:87], s[64:65]
	v_add_u32_e32 v183, 0x4000, v183
	s_waitcnt lgkmcnt(1)
	v_fma_f32 v88, v168, v88, v152
	v_fma_f32 v89, v169, v89, v153
	v_fma_f32 v90, v170, v90, v154
	v_fma_f32 v91, v171, v91, v155
	global_store_dwordx4 v183, v[88:91], s[64:65]
	v_add_u32_e32 v183, 0x4000, v183
	s_waitcnt lgkmcnt(0)
	v_fma_f32 v92, v168, v92, v156
	v_fma_f32 v93, v169, v93, v157
	v_fma_f32 v94, v170, v94, v158
	v_fma_f32 v95, v171, v95, v159
	global_store_dwordx4 v183, v[92:95], s[64:65]
	v_add_u32_e32 v183, 0x4000, v183
	ds_write_b128 v172, v[96:99]
	ds_write_b128 v173, v[100:103]
	ds_write_b128 v174, v[104:107]
	ds_write_b128 v175, v[108:111]
	ds_write_b128 v172, v[112:115] offset:4096
	ds_write_b128 v173, v[116:119] offset:4096
	ds_write_b128 v174, v[120:123] offset:4096
	ds_write_b128 v175, v[124:127] offset:4096
	s_waitcnt lgkmcnt(0)
	ds_read_b128 v[96:99], v180
	ds_read_b128 v[100:103], v181 offset:1024
	ds_read_b128 v[104:107], v180 offset:2048
	ds_read_b128 v[108:111], v181 offset:3072
	ds_read_b128 v[112:115], v180 offset:4096
	ds_read_b128 v[116:119], v181 offset:5120
	ds_read_b128 v[120:123], v180 offset:6144
	ds_read_b128 v[124:127], v181 offset:7168
	s_waitcnt vmcnt(8)
	s_waitcnt lgkmcnt(7)
	v_fma_f32 v96, v168, v96, v188
	v_fma_f32 v97, v169, v97, v189
	v_fma_f32 v98, v170, v98, v190
	v_fma_f32 v99, v171, v99, v191
	global_store_dwordx4 v183, v[96:99], s[64:65]
	v_add_u32_e32 v183, 0x4000, v183
	s_waitcnt lgkmcnt(6)
	v_fma_f32 v100, v168, v100, v192
	v_fma_f32 v101, v169, v101, v193
	v_fma_f32 v102, v170, v102, v194
	v_fma_f32 v103, v171, v103, v195
	global_store_dwordx4 v183, v[100:103], s[64:65]
	v_add_u32_e32 v183, 0x4000, v183
	s_waitcnt lgkmcnt(5)
	v_fma_f32 v104, v168, v104, v196
	v_fma_f32 v105, v169, v105, v197
	v_fma_f32 v106, v170, v106, v198
	v_fma_f32 v107, v171, v107, v199
	global_store_dwordx4 v183, v[104:107], s[64:65]
	v_add_u32_e32 v183, 0x4000, v183
	s_waitcnt lgkmcnt(4)
	v_fma_f32 v108, v168, v108, v222
	v_fma_f32 v109, v169, v109, v223
	v_fma_f32 v110, v170, v110, v224
	v_fma_f32 v111, v171, v111, v225
	global_store_dwordx4 v183, v[108:111], s[64:65]
	v_add_u32_e32 v183, 0x4000, v183
	s_waitcnt lgkmcnt(3)
	v_fma_f32 v112, v168, v112, v226
	v_fma_f32 v113, v169, v113, v227
	v_fma_f32 v114, v170, v114, v228
	v_fma_f32 v115, v171, v115, v229
	global_store_dwordx4 v183, v[112:115], s[64:65]
	v_add_u32_e32 v183, 0x4000, v183
	s_waitcnt lgkmcnt(2)
	v_fma_f32 v116, v168, v116, v230
	v_fma_f32 v117, v169, v117, v231
	v_fma_f32 v118, v170, v118, v232
	v_fma_f32 v119, v171, v119, v233
	global_store_dwordx4 v183, v[116:119], s[64:65]
	v_add_u32_e32 v183, 0x4000, v183
	s_waitcnt lgkmcnt(1)
	v_fma_f32 v120, v168, v120, v234
	v_fma_f32 v121, v169, v121, v235
	v_fma_f32 v122, v170, v122, v236
	v_fma_f32 v123, v171, v123, v237
	global_store_dwordx4 v183, v[120:123], s[64:65]
	v_add_u32_e32 v183, 0x4000, v183
	s_waitcnt lgkmcnt(0)
	v_fma_f32 v124, v168, v124, v238
	v_fma_f32 v125, v169, v125, v239
	v_fma_f32 v126, v170, v126, v240
	v_fma_f32 v127, v171, v127, v241
	global_store_dwordx4 v183, v[124:127], s[64:65]
	v_add_u32_e32 v183, 0x4000, v183
	s_add_i32 s6, s6, 1
	s_mov_b64 s[4:5], 0
	s_branch .LBB0_991
